# store GEMMs: first K-iteration after a tile epilogue waits vmcnt(24) instead of vmcnt(8) at its two early counted waits, so the 16 epilogue stores need not retire first
# baseline (speedup 1.0000x reference)
; #define LAS __attribute__((address_space(3)))
; __device__ __forceinline__ void run_gemm_store(const Params& p, LAS unsigned char* ldsl, const int ph) {
;     unsigned char* ws = p.ws; const int l1 = ph >= 9; const int Mrows = ph >= 12 ? MLAT : MALL;
;     const bf16_t* A = (const bf16_t*)(ws + WS_A);
;     pg8::Gemm g{D}; pg8::SegOrder S; S.init(D, gridDim.x, blockIdx.x);
;     pg8::EpiBf16 E{(bf16_t*)(ws + WS_P), NIN, (bf16_t*)(ws + WS_VT), MALL, 0};
;     if (ph == 2) { S.add(A, ws + WS_WIN, MALL / 256, NIN / 256, 1, D / 64, 0); S.add(ws + WS_WV0, A, 1024 / 256, MALL / 256, 1, D / 64, 1); }
;     else if (ph == 10) { E.ldc0 = NQK; S.add(A, ws + WS_WQKV, MALL / 256, NQK / 256, 1, D / 64, 0); S.add((const bf16_t*)(ws + WS_WQKV) + (size_t)NQK * D, A, D / 256, MALL / 256, 1, D / 64, 1); }
;     else { E.O0 = (bf16_t*)(ws + WS_H); E.ldc0 = DFF; E.ACT = 1; S.add(A, (const bf16_t*)(ws + WS_WUP) + (size_t)l1 * D * DFF, Mrows / 256, DFF / 256, 1, D / 64, 0); }
;     pg8::gemm_phase<pg8::EpiBf16, pg8::SegOrder, true, true>(ldsl, g, S, E);
.LBB0_198:
	s_cmp_lt_i32 s80, 3
	s_cselect_b64 s[2:3], -1, 0
	s_and_b64 s[0:1], s[2:3], s[0:1]
	s_andn2_b64 vcc, exec, s[0:1]
	s_cbranch_vccnz .LBB0_227
	s_mov_b32 s100, 0
	s_ashr_i32 s30, s92, 31
	s_cmpk_lt_i32 s92, 0x484
	s_cselect_b64 s[8:9], -1, 0
	v_readfirstlane_b32 s10, v162
	s_and_b64 vcc, exec, s[8:9]
	s_cbranch_vccnz .LBB0_201
	s_add_u32 s6, s92, 0xfffffb7c
	s_addc_u32 s7, s30, -1
	v_mov_b64_e32 v[0:1], 0x110
	v_cmp_lt_u64_e64 s[8:9], s[6:7], v[0:1]
	s_mov_b32 s34, 1
	s_movk_i32 s13, 0x44
	s_mov_b32 s12, 4
	s_mov_b64 s[4:5], 0xc600000
	s_mov_b64 s[2:3], 0x1200000
	s_andn2_b64 vcc, exec, s[8:9]
	s_cbranch_vccz .LBB0_202
	s_branch .LBB0_227

; #define PG8_STAGE(bufoff, gbase, voff) do { _Pragma("unroll") for (int _i = 0; _i < 2; ++_i) \
;         __builtin_amdgcn_global_load_lds((const unsigned*)((const char*)(gbase) + (voff)[_i]), (LAS unsigned*)(lds + (bufoff) + ldsw + _i * 8192), 16, 0, 0); } while (0)
; #define PG8_LDA(dst, b, h) do { _Pragma("unroll") for (int m = 0; m < 4; ++m) _Pragma("unroll") for (int k = 0; k < 2; ++k) dst[m][k] = *(const LAS bf16x8*)(lds + PG8_SA(b, h) + aoff + m * 2048 + k * 1024); } while (0)
; #define PG8_LDB(dst, b, h) do { _Pragma("unroll") for (int n = 0; n < 2; ++n) _Pragma("unroll") for (int k = 0; k < 2; ++k) dst[n][k] = *(const LAS bf16x8*)(lds + PG8_SB(b, h) + boff + n * 2048 + k * 1024); } while (0)
; #define PG8_MMA(ai, bj, At, Bt) do { __builtin_amdgcn_s_setprio(1); _Pragma("unroll") for (int m = 0; m < 4; ++m) _Pragma("unroll") for (int n = 0; n < 2; ++n) _Pragma("unroll") for (int k = 0; k < 2; ++k) \
;         acc[ai][bj][m][n] = __builtin_amdgcn_mfma_f32_16x16x32_bf16(Bt[n][k], At[m][k], acc[ai][bj][m][n], 0, 0, 0); __builtin_amdgcn_s_setprio(0); } while (0)
; #define PG8_WAIT_V(n) asm volatile("s_waitcnt vmcnt(" #n ")" ::: "memory")
; #define PG8_WAIT_L(n) asm volatile("s_waitcnt lgkmcnt(" #n ")" ::: "memory")
; #define PG8_BAR __builtin_amdgcn_s_barrier()
; #define PG8_SCHED __builtin_amdgcn_sched_barrier(0)
; template <class Epi, class Sched, bool ALIGN_EPI = false, bool SP2 = false>
; __device__ __forceinline__ void gemm_phase(LAS unsigned char* lds, const Gemm g, const Sched& S, const Epi& E) {
;     ...
;             if constexpr (SP2) {
;             PG8_LDB(B0, 0, 0); PG8_LDB(B1, 0, 1); PG8_SCHED; PG8_LDA(At, 0, 0); PG8_STAGE(PG8_SA(1, 1), a1 + hstep, voffA);
;             PG8_WAIT_V(8); PG8_WAIT_L(0); PG8_BAR; PG8_MMA(0, 0, At, B0); PG8_MMA(0, 1, At, B1); PG8_BAR; PG8_SCHED;
.LBB0_220:
	ds_read_b128 v[152:155], v148
	ds_read_b128 v[156:159], v148 offset:1024
	ds_read_b128 v[164:167], v148 offset:2048
	ds_read_b128 v[170:173], v148 offset:3072
	ds_read_b128 v[174:177], v149
	ds_read_b128 v[178:181], v149 offset:1024
	ds_read_b128 v[182:185], v149 offset:2048
	ds_read_b128 v[186:189], v149 offset:3072
	s_add_u32 s22, s20, 0xfff80080
	s_addc_u32 s23, s21, -1
	s_cmp_eq_u32 s70, 28
	s_cselect_b32 s25, s13, s23
	s_cselect_b32 s24, s26, s22
	s_cselect_b32 s23, s27, s69
	s_cselect_b32 s22, s28, s29
	v_lshl_add_u64 v[222:223], s[20:21], 0, v[136:137]
	s_add_i32 m0, s33, 0xc000
	ds_read_b128 v[190:193], v150
	ds_read_b128 v[194:197], v150 offset:1024
	ds_read_b128 v[198:201], v150 offset:2048
	ds_read_b128 v[202:205], v150 offset:3072
	ds_read_b128 v[206:209], v150 offset:4096
	ds_read_b128 v[210:213], v150 offset:5120
	ds_read_b128 v[214:217], v150 offset:6144
	ds_read_b128 v[218:221], v150 offset:7168
	global_load_lds_dwordx4 v[222:223], off
	v_lshl_add_u64 v[222:223], s[20:21], 0, v[138:139]
	s_add_i32 m0, s33, 0xe000
	s_nop 0
	global_load_lds_dwordx4 v[222:223], off
	s_cmp_eq_u32 s100, 1
	s_cbranch_scc1 .Ltw_tilewait_4806_0a
	s_waitcnt vmcnt(8)
	s_branch .Ltw_tilewait_4806_0b

; #define PG8_STAGE(bufoff, gbase, voff) do { _Pragma("unroll") for (int _i = 0; _i < 2; ++_i) \
;         __builtin_amdgcn_global_load_lds((const unsigned*)((const char*)(gbase) + (voff)[_i]), (LAS unsigned*)(lds + (bufoff) + ldsw + _i * 8192), 16, 0, 0); } while (0)
; #define PG8_LDA(dst, b, h) do { _Pragma("unroll") for (int m = 0; m < 4; ++m) _Pragma("unroll") for (int k = 0; k < 2; ++k) dst[m][k] = *(const LAS bf16x8*)(lds + PG8_SA(b, h) + aoff + m * 2048 + k * 1024); } while (0)
; #define PG8_MMA(ai, bj, At, Bt) do { __builtin_amdgcn_s_setprio(1); _Pragma("unroll") for (int m = 0; m < 4; ++m) _Pragma("unroll") for (int n = 0; n < 2; ++n) _Pragma("unroll") for (int k = 0; k < 2; ++k) \
;         acc[ai][bj][m][n] = __builtin_amdgcn_mfma_f32_16x16x32_bf16(Bt[n][k], At[m][k], acc[ai][bj][m][n], 0, 0, 0); __builtin_amdgcn_s_setprio(0); } while (0)
; #define PG8_WAIT_V(n) asm volatile("s_waitcnt vmcnt(" #n ")" ::: "memory")
; #define PG8_WAIT_L(n) asm volatile("s_waitcnt lgkmcnt(" #n ")" ::: "memory")
; #define PG8_BAR __builtin_amdgcn_s_barrier()
; #define PG8_SCHED __builtin_amdgcn_sched_barrier(0)
; template <class Epi, class Sched, bool ALIGN_EPI = false, bool SP2 = false>
; __device__ __forceinline__ void gemm_phase(LAS unsigned char* lds, const Gemm g, const Sched& S, const Epi& E) {
;     ...
;             PG8_WAIT_V(8); PG8_WAIT_L(0); PG8_BAR; PG8_MMA(0, 0, At, B0); PG8_MMA(0, 1, At, B1); PG8_BAR; PG8_SCHED;
;             PG8_LDA(At, 0, 1); PG8_STAGE(PG8_SB(0, 0), b2, voffB); PG8_STAGE(PG8_SB(0, 1), b2 + hstep, voffB); PG8_STAGE(PG8_SA(0, 0), a2, voffA);
;             PG8_WAIT_V(8); PG8_WAIT_L(0); PG8_BAR; PG8_MMA(1, 0, At, B0); PG8_MMA(1, 1, At, B1); PG8_BAR; PG8_SCHED;
.Ltw_tilewait_4806_0b:
	s_waitcnt lgkmcnt(0)
	s_barrier
	s_setprio 1
	s_waitcnt lgkmcnt(0)
	v_mfma_f32_16x16x32_bf16 v[124:127], v[152:155], v[190:193], v[124:127]
	v_mfma_f32_16x16x32_bf16 v[120:123], v[164:167], v[190:193], v[120:123]
	v_mfma_f32_16x16x32_bf16 v[116:119], v[152:155], v[198:201], v[116:119]
	v_mfma_f32_16x16x32_bf16 v[112:115], v[164:167], v[198:201], v[112:115]
	v_mfma_f32_16x16x32_bf16 v[100:103], v[152:155], v[206:209], v[100:103]
	v_mfma_f32_16x16x32_bf16 v[96:99], v[164:167], v[206:209], v[96:99]
	v_mfma_f32_16x16x32_bf16 v[84:87], v[152:155], v[214:217], v[84:87]
	v_mfma_f32_16x16x32_bf16 v[80:83], v[164:167], v[214:217], v[80:83]
	v_mfma_f32_16x16x32_bf16 v[124:127], v[156:159], v[194:197], v[124:127]
	v_mfma_f32_16x16x32_bf16 v[120:123], v[170:173], v[194:197], v[120:123]
	v_mfma_f32_16x16x32_bf16 v[116:119], v[156:159], v[202:205], v[116:119]
	v_mfma_f32_16x16x32_bf16 v[112:115], v[170:173], v[202:205], v[112:115]
	v_mfma_f32_16x16x32_bf16 v[100:103], v[156:159], v[210:213], v[100:103]
	v_mfma_f32_16x16x32_bf16 v[96:99], v[170:173], v[210:213], v[96:99]
	v_mfma_f32_16x16x32_bf16 v[84:87], v[156:159], v[218:221], v[84:87]
	v_mfma_f32_16x16x32_bf16 v[80:83], v[170:173], v[218:221], v[80:83]
	s_setprio 0
	s_setprio 1
	v_mfma_f32_16x16x32_bf16 v[108:111], v[174:177], v[190:193], v[108:111]
	v_mfma_f32_16x16x32_bf16 v[104:107], v[182:185], v[190:193], v[104:107]
	v_mfma_f32_16x16x32_bf16 v[92:95], v[174:177], v[198:201], v[92:95]
	v_mfma_f32_16x16x32_bf16 v[88:91], v[182:185], v[198:201], v[88:91]
	v_mfma_f32_16x16x32_bf16 v[76:79], v[174:177], v[206:209], v[76:79]
	v_mfma_f32_16x16x32_bf16 v[72:75], v[182:185], v[206:209], v[72:75]
	v_mfma_f32_16x16x32_bf16 v[68:71], v[174:177], v[214:217], v[68:71]
	v_mfma_f32_16x16x32_bf16 v[64:67], v[182:185], v[214:217], v[64:67]
	v_mfma_f32_16x16x32_bf16 v[108:111], v[178:181], v[194:197], v[108:111]
	v_mfma_f32_16x16x32_bf16 v[104:107], v[186:189], v[194:197], v[104:107]
	v_mfma_f32_16x16x32_bf16 v[92:95], v[178:181], v[202:205], v[92:95]
	v_mfma_f32_16x16x32_bf16 v[88:91], v[186:189], v[202:205], v[88:91]
	v_mfma_f32_16x16x32_bf16 v[76:79], v[178:181], v[210:213], v[76:79]
	v_mfma_f32_16x16x32_bf16 v[72:75], v[186:189], v[210:213], v[72:75]
	v_mfma_f32_16x16x32_bf16 v[68:71], v[178:181], v[218:221], v[68:71]
	v_mfma_f32_16x16x32_bf16 v[64:67], v[186:189], v[218:221], v[64:67]
	s_setprio 0
	s_barrier
	s_add_i32 s71, s59, s31
	v_lshl_add_u64 v[222:223], s[22:23], 0, v[130:131]
	s_mov_b32 m0, s71
	ds_read_b128 v[190:193], v150 offset:16384
	ds_read_b128 v[194:197], v150 offset:17408
	ds_read_b128 v[198:201], v150 offset:18432
	ds_read_b128 v[202:205], v150 offset:19456
	ds_read_b128 v[206:209], v150 offset:20480
	ds_read_b128 v[210:213], v150 offset:21504
	ds_read_b128 v[214:217], v150 offset:22528
	ds_read_b128 v[218:221], v150 offset:23552
	global_load_lds_dwordx4 v[222:223], off
	s_add_i32 m0, s71, 0x2000
	s_add_u32 s72, s22, 0x80000
	v_lshl_add_u64 v[224:225], s[22:23], 0, v[134:135]
	s_addc_u32 s73, s23, 0
	s_add_i32 s71, s68, s31
	global_load_lds_dwordx4 v[224:225], off
	v_lshl_add_u64 v[226:227], s[72:73], 0, v[130:131]
	s_mov_b32 m0, s71
	v_lshl_add_u64 v[228:229], s[24:25], 0, v[132:133]
	global_load_lds_dwordx4 v[226:227], off
	v_lshl_add_u64 v[226:227], s[72:73], 0, v[134:135]
	s_add_i32 m0, s71, 0x2000
	s_nop 0
	global_load_lds_dwordx4 v[226:227], off
	v_lshl_add_u64 v[226:227], s[24:25], 0, v[128:129]
	s_mov_b32 m0, s33
	s_nop 0
	global_load_lds_dwordx4 v[226:227], off
	s_mov_b32 m0, s35
	s_nop 0
	global_load_lds_dwordx4 v[228:229], off
	s_cmp_eq_u32 s100, 1
	s_cbranch_scc1 .Ltw_tilewait_4806_1a
	s_waitcnt vmcnt(8)
	s_branch .Ltw_tilewait_4806_1b

; #define PG8_STAGE(bufoff, gbase, voff) do { _Pragma("unroll") for (int _i = 0; _i < 2; ++_i) \
;         __builtin_amdgcn_global_load_lds((const unsigned*)((const char*)(gbase) + (voff)[_i]), (LAS unsigned*)(lds + (bufoff) + ldsw + _i * 8192), 16, 0, 0); } while (0)
; #define PG8_LDA(dst, b, h) do { _Pragma("unroll") for (int m = 0; m < 4; ++m) _Pragma("unroll") for (int k = 0; k < 2; ++k) dst[m][k] = *(const LAS bf16x8*)(lds + PG8_SA(b, h) + aoff + m * 2048 + k * 1024); } while (0)
; #define PG8_LDB(dst, b, h) do { _Pragma("unroll") for (int n = 0; n < 2; ++n) _Pragma("unroll") for (int k = 0; k < 2; ++k) dst[n][k] = *(const LAS bf16x8*)(lds + PG8_SB(b, h) + boff + n * 2048 + k * 1024); } while (0)
; #define PG8_MMA(ai, bj, At, Bt) do { __builtin_amdgcn_s_setprio(1); _Pragma("unroll") for (int m = 0; m < 4; ++m) _Pragma("unroll") for (int n = 0; n < 2; ++n) _Pragma("unroll") for (int k = 0; k < 2; ++k) \
;         acc[ai][bj][m][n] = __builtin_amdgcn_mfma_f32_16x16x32_bf16(Bt[n][k], At[m][k], acc[ai][bj][m][n], 0, 0, 0); __builtin_amdgcn_s_setprio(0); } while (0)
; #define PG8_WAIT_V(n) asm volatile("s_waitcnt vmcnt(" #n ")" ::: "memory")
; #define PG8_WAIT_L(n) asm volatile("s_waitcnt lgkmcnt(" #n ")" ::: "memory")
; #define PG8_BAR __builtin_amdgcn_s_barrier()
; #define PG8_SCHED __builtin_amdgcn_sched_barrier(0)
; template <class Epi, class Sched, bool ALIGN_EPI = false, bool SP2 = false>
; __device__ __forceinline__ void gemm_phase(LAS unsigned char* lds, const Gemm g, const Sched& S, const Epi& E) {
;     ...
;             PG8_WAIT_V(8); PG8_WAIT_L(0); PG8_BAR; PG8_MMA(1, 0, At, B0); PG8_MMA(1, 1, At, B1); PG8_BAR; PG8_SCHED;
;             PG8_LDB(B0, 1, 0); PG8_LDB(B1, 1, 1); PG8_SCHED; PG8_LDA(At, 1, 0); PG8_STAGE(PG8_SA(0, 1), a2 + hstep, voffA);
;             PG8_WAIT_V(8); PG8_WAIT_L(0); PG8_BAR; PG8_MMA(0, 0, At, B0); PG8_MMA(0, 1, At, B1); PG8_BAR; PG8_SCHED;
.Ltw_tilewait_4806_1b:
	s_waitcnt lgkmcnt(0)
	s_barrier
	s_setprio 1
	s_waitcnt lgkmcnt(0)
	v_mfma_f32_16x16x32_bf16 v[60:63], v[152:155], v[190:193], v[60:63]
	v_mfma_f32_16x16x32_bf16 v[56:59], v[164:167], v[190:193], v[56:59]
	v_mfma_f32_16x16x32_bf16 v[52:55], v[152:155], v[198:201], v[52:55]
	v_mfma_f32_16x16x32_bf16 v[48:51], v[164:167], v[198:201], v[48:51]
	v_mfma_f32_16x16x32_bf16 v[36:39], v[152:155], v[206:209], v[36:39]
	v_mfma_f32_16x16x32_bf16 v[32:35], v[164:167], v[206:209], v[32:35]
	v_mfma_f32_16x16x32_bf16 v[20:23], v[152:155], v[214:217], v[20:23]
	v_mfma_f32_16x16x32_bf16 v[16:19], v[164:167], v[214:217], v[16:19]
	v_mfma_f32_16x16x32_bf16 v[60:63], v[156:159], v[194:197], v[60:63]
	v_mfma_f32_16x16x32_bf16 v[56:59], v[170:173], v[194:197], v[56:59]
	v_mfma_f32_16x16x32_bf16 v[52:55], v[156:159], v[202:205], v[52:55]
	v_mfma_f32_16x16x32_bf16 v[48:51], v[170:173], v[202:205], v[48:51]
	v_mfma_f32_16x16x32_bf16 v[36:39], v[156:159], v[210:213], v[36:39]
	v_mfma_f32_16x16x32_bf16 v[32:35], v[170:173], v[210:213], v[32:35]
	v_mfma_f32_16x16x32_bf16 v[20:23], v[156:159], v[218:221], v[20:23]
	v_mfma_f32_16x16x32_bf16 v[16:19], v[170:173], v[218:221], v[16:19]
	s_setprio 0
	s_setprio 1
	v_mfma_f32_16x16x32_bf16 v[44:47], v[174:177], v[190:193], v[44:47]
	v_mfma_f32_16x16x32_bf16 v[40:43], v[182:185], v[190:193], v[40:43]
	v_mfma_f32_16x16x32_bf16 v[28:31], v[174:177], v[198:201], v[28:31]
	v_mfma_f32_16x16x32_bf16 v[24:27], v[182:185], v[198:201], v[24:27]
	v_mfma_f32_16x16x32_bf16 v[12:15], v[174:177], v[206:209], v[12:15]
	v_mfma_f32_16x16x32_bf16 v[8:11], v[182:185], v[206:209], v[8:11]
	v_mfma_f32_16x16x32_bf16 v[4:7], v[174:177], v[214:217], v[4:7]
	v_mfma_f32_16x16x32_bf16 v[0:3], v[182:185], v[214:217], v[0:3]
	v_mfma_f32_16x16x32_bf16 v[44:47], v[178:181], v[194:197], v[44:47]
	v_mfma_f32_16x16x32_bf16 v[40:43], v[186:189], v[194:197], v[40:43]
	v_mfma_f32_16x16x32_bf16 v[28:31], v[178:181], v[202:205], v[28:31]
	v_mfma_f32_16x16x32_bf16 v[24:27], v[186:189], v[202:205], v[24:27]
	v_mfma_f32_16x16x32_bf16 v[12:15], v[178:181], v[210:213], v[12:15]
	v_mfma_f32_16x16x32_bf16 v[8:11], v[186:189], v[210:213], v[8:11]
	v_mfma_f32_16x16x32_bf16 v[4:7], v[178:181], v[218:221], v[4:7]
	v_mfma_f32_16x16x32_bf16 v[0:3], v[186:189], v[218:221], v[0:3]
	s_setprio 0
	s_barrier
	s_add_i32 s71, 0, 0x18000
	v_add_u32_e32 v151, s71, v146
	s_add_i32 s72, 0, 0x1c000
	ds_read_b128 v[152:155], v151
	ds_read_b128 v[156:159], v151 offset:1024
	ds_read_b128 v[164:167], v151 offset:2048
	ds_read_b128 v[170:173], v151 offset:3072
	v_add_u32_e32 v151, s72, v146
	ds_read_b128 v[174:177], v151
	ds_read_b128 v[178:181], v151 offset:1024
	ds_read_b128 v[182:185], v151 offset:2048
	ds_read_b128 v[186:189], v151 offset:3072
	s_add_u32 s24, s24, 0x80000
	s_addc_u32 s25, s25, 0
	s_mov_b32 m0, s40
	v_lshl_add_u64 v[230:231], s[24:25], 0, v[128:129]
	ds_read_b128 v[190:193], v150 offset:32768
	ds_read_b128 v[194:197], v150 offset:33792
	ds_read_b128 v[198:201], v150 offset:34816
	ds_read_b128 v[202:205], v150 offset:35840
	ds_read_b128 v[206:209], v150 offset:36864
	ds_read_b128 v[210:213], v150 offset:37888
	ds_read_b128 v[214:217], v150 offset:38912
	ds_read_b128 v[218:221], v150 offset:39936
	global_load_lds_dwordx4 v[230:231], off
	v_lshl_add_u64 v[230:231], s[24:25], 0, v[132:133]
	s_mov_b32 m0, s41
	s_nop 0
	global_load_lds_dwordx4 v[230:231], off
	s_waitcnt vmcnt(8)
	s_waitcnt lgkmcnt(0)
	s_barrier
	s_setprio 1
	s_waitcnt lgkmcnt(0)
	v_mfma_f32_16x16x32_bf16 v[124:127], v[152:155], v[190:193], v[124:127]
	v_mfma_f32_16x16x32_bf16 v[120:123], v[164:167], v[190:193], v[120:123]
	v_mfma_f32_16x16x32_bf16 v[116:119], v[152:155], v[198:201], v[116:119]
	v_mfma_f32_16x16x32_bf16 v[112:115], v[164:167], v[198:201], v[112:115]
	v_mfma_f32_16x16x32_bf16 v[100:103], v[152:155], v[206:209], v[100:103]
	v_mfma_f32_16x16x32_bf16 v[96:99], v[164:167], v[206:209], v[96:99]
	v_mfma_f32_16x16x32_bf16 v[84:87], v[152:155], v[214:217], v[84:87]
	v_mfma_f32_16x16x32_bf16 v[80:83], v[164:167], v[214:217], v[80:83]
	v_mfma_f32_16x16x32_bf16 v[124:127], v[156:159], v[194:197], v[124:127]
	v_mfma_f32_16x16x32_bf16 v[120:123], v[170:173], v[194:197], v[120:123]
	v_mfma_f32_16x16x32_bf16 v[116:119], v[156:159], v[202:205], v[116:119]
	v_mfma_f32_16x16x32_bf16 v[112:115], v[170:173], v[202:205], v[112:115]
	v_mfma_f32_16x16x32_bf16 v[100:103], v[156:159], v[210:213], v[100:103]
	v_mfma_f32_16x16x32_bf16 v[96:99], v[170:173], v[210:213], v[96:99]
	v_mfma_f32_16x16x32_bf16 v[84:87], v[156:159], v[218:221], v[84:87]
	v_mfma_f32_16x16x32_bf16 v[80:83], v[170:173], v[218:221], v[80:83]
	s_setprio 0
	s_setprio 1
	v_mfma_f32_16x16x32_bf16 v[108:111], v[174:177], v[190:193], v[108:111]
	v_mfma_f32_16x16x32_bf16 v[104:107], v[182:185], v[190:193], v[104:107]
	v_mfma_f32_16x16x32_bf16 v[92:95], v[174:177], v[198:201], v[92:95]
	v_mfma_f32_16x16x32_bf16 v[88:91], v[182:185], v[198:201], v[88:91]
	v_mfma_f32_16x16x32_bf16 v[76:79], v[174:177], v[206:209], v[76:79]
	v_mfma_f32_16x16x32_bf16 v[72:75], v[182:185], v[206:209], v[72:75]
	v_mfma_f32_16x16x32_bf16 v[68:71], v[174:177], v[214:217], v[68:71]
	v_mfma_f32_16x16x32_bf16 v[64:67], v[182:185], v[214:217], v[64:67]
	v_mfma_f32_16x16x32_bf16 v[108:111], v[178:181], v[194:197], v[108:111]
	v_mfma_f32_16x16x32_bf16 v[104:107], v[186:189], v[194:197], v[104:107]
	v_mfma_f32_16x16x32_bf16 v[92:95], v[178:181], v[202:205], v[92:95]
	v_mfma_f32_16x16x32_bf16 v[88:91], v[186:189], v[202:205], v[88:91]
	v_mfma_f32_16x16x32_bf16 v[76:79], v[178:181], v[210:213], v[76:79]
	v_mfma_f32_16x16x32_bf16 v[72:75], v[186:189], v[210:213], v[72:75]
	v_mfma_f32_16x16x32_bf16 v[68:71], v[178:181], v[218:221], v[68:71]
	v_mfma_f32_16x16x32_bf16 v[64:67], v[186:189], v[218:221], v[64:67]
	s_setprio 0
	s_barrier
; #define PG8_STAGE(bufoff, gbase, voff) do { _Pragma("unroll") for (int _i = 0; _i < 2; ++_i) \
;         __builtin_amdgcn_global_load_lds((const unsigned*)((const char*)(gbase) + (voff)[_i]), (LAS unsigned*)(lds + (bufoff) + ldsw + _i * 8192), 16, 0, 0); } while (0)
; #define PG8_LDA(dst, b, h) do { _Pragma("unroll") for (int m = 0; m < 4; ++m) _Pragma("unroll") for (int k = 0; k < 2; ++k) dst[m][k] = *(const LAS bf16x8*)(lds + PG8_SA(b, h) + aoff + m * 2048 + k * 1024); } while (0)
; #define PG8_MMA(ai, bj, At, Bt) do { __builtin_amdgcn_s_setprio(1); _Pragma("unroll") for (int m = 0; m < 4; ++m) _Pragma("unroll") for (int n = 0; n < 2; ++n) _Pragma("unroll") for (int k = 0; k < 2; ++k) \
;         acc[ai][bj][m][n] = __builtin_amdgcn_mfma_f32_16x16x32_bf16(Bt[n][k], At[m][k], acc[ai][bj][m][n], 0, 0, 0); __builtin_amdgcn_s_setprio(0); } while (0)
; #define PG8_WAIT_V(n) asm volatile("s_waitcnt vmcnt(" #n ")" ::: "memory")
; #define PG8_WAIT_L(n) asm volatile("s_waitcnt lgkmcnt(" #n ")" ::: "memory")
; #define PG8_BAR __builtin_amdgcn_s_barrier()
; #define PG8_SCHED __builtin_amdgcn_sched_barrier(0)
; template <class Epi, class Sched, bool ALIGN_EPI = false, bool SP2 = false>
; __device__ __forceinline__ void gemm_phase(LAS unsigned char* lds, const Gemm g, const Sched& S, const Epi& E) {
;     ...
;         for (int t = 0; t < nt; t += 2) {
;     ...
;             PG8_LDA(At, 1, 1); PG8_STAGE(PG8_SB(1, 0), b3, voffB); PG8_STAGE(PG8_SB(1, 1), b3 + hstep, voffB); PG8_STAGE(PG8_SA(1, 0), a3, voffA);
;             PG8_WAIT_V(8); PG8_WAIT_L(0); PG8_BAR; PG8_MMA(1, 0, At, B0); PG8_MMA(1, 1, At, B1); PG8_BAR; PG8_SCHED;
	s_add_i32 s24, s71, s31
	v_lshl_add_u64 v[222:223], v[222:223], 0, s[4:5]
	s_mov_b32 m0, s24
	ds_read_b128 v[190:193], v150 offset:49152
	ds_read_b128 v[194:197], v150 offset:50176
	ds_read_b128 v[198:201], v150 offset:51200
	ds_read_b128 v[202:205], v150 offset:52224
	ds_read_b128 v[206:209], v150 offset:53248
	ds_read_b128 v[210:213], v150 offset:54272
	ds_read_b128 v[214:217], v150 offset:55296
	ds_read_b128 v[218:221], v150 offset:56320
	global_load_lds_dwordx4 v[222:223], off
	s_add_i32 m0, s24, 0x2000
	s_add_u32 s22, s22, 0x80080
	v_lshl_add_u64 v[222:223], v[224:225], 0, s[4:5]
	s_addc_u32 s23, s23, 0
	s_add_i32 s24, s72, s31
	global_load_lds_dwordx4 v[222:223], off
	v_lshl_add_u64 v[222:223], s[22:23], 0, v[130:131]
	s_mov_b32 m0, s24
	s_nop 0
	global_load_lds_dwordx4 v[222:223], off
	v_lshl_add_u64 v[222:223], s[22:23], 0, v[134:135]
	s_add_i32 m0, s24, 0x2000
	s_nop 0
	global_load_lds_dwordx4 v[222:223], off
	v_lshl_add_u64 v[222:223], v[226:227], 0, s[4:5]
	s_mov_b32 m0, s54
	s_nop 0
	global_load_lds_dwordx4 v[222:223], off
	v_lshl_add_u64 v[222:223], v[228:229], 0, s[4:5]
	s_mov_b32 m0, s55
	s_nop 0
	global_load_lds_dwordx4 v[222:223], off
	s_waitcnt vmcnt(8)
	s_waitcnt lgkmcnt(0)
	s_barrier
	s_setprio 1
	s_waitcnt lgkmcnt(0)
	v_mfma_f32_16x16x32_bf16 v[60:63], v[152:155], v[190:193], v[60:63]
	v_mfma_f32_16x16x32_bf16 v[56:59], v[164:167], v[190:193], v[56:59]
	v_mfma_f32_16x16x32_bf16 v[52:55], v[152:155], v[198:201], v[52:55]
	v_mfma_f32_16x16x32_bf16 v[48:51], v[164:167], v[198:201], v[48:51]
	v_mfma_f32_16x16x32_bf16 v[36:39], v[152:155], v[206:209], v[36:39]
	v_mfma_f32_16x16x32_bf16 v[32:35], v[164:167], v[206:209], v[32:35]
	v_mfma_f32_16x16x32_bf16 v[20:23], v[152:155], v[214:217], v[20:23]
	v_mfma_f32_16x16x32_bf16 v[16:19], v[164:167], v[214:217], v[16:19]
	v_mfma_f32_16x16x32_bf16 v[60:63], v[156:159], v[194:197], v[60:63]
	v_mfma_f32_16x16x32_bf16 v[56:59], v[170:173], v[194:197], v[56:59]
	v_mfma_f32_16x16x32_bf16 v[52:55], v[156:159], v[202:205], v[52:55]
	v_mfma_f32_16x16x32_bf16 v[48:51], v[170:173], v[202:205], v[48:51]
	v_mfma_f32_16x16x32_bf16 v[36:39], v[156:159], v[210:213], v[36:39]
	v_mfma_f32_16x16x32_bf16 v[32:35], v[170:173], v[210:213], v[32:35]
	v_mfma_f32_16x16x32_bf16 v[20:23], v[156:159], v[218:221], v[20:23]
	v_mfma_f32_16x16x32_bf16 v[16:19], v[170:173], v[218:221], v[16:19]
	s_setprio 0
	s_setprio 1
	v_mfma_f32_16x16x32_bf16 v[44:47], v[174:177], v[190:193], v[44:47]
	v_mfma_f32_16x16x32_bf16 v[40:43], v[182:185], v[190:193], v[40:43]
	v_mfma_f32_16x16x32_bf16 v[28:31], v[174:177], v[198:201], v[28:31]
	v_mfma_f32_16x16x32_bf16 v[24:27], v[182:185], v[198:201], v[24:27]
	v_mfma_f32_16x16x32_bf16 v[12:15], v[174:177], v[206:209], v[12:15]
	v_mfma_f32_16x16x32_bf16 v[8:11], v[182:185], v[206:209], v[8:11]
	v_mfma_f32_16x16x32_bf16 v[4:7], v[174:177], v[214:217], v[4:7]
	v_mfma_f32_16x16x32_bf16 v[0:3], v[182:185], v[214:217], v[0:3]
	v_mfma_f32_16x16x32_bf16 v[44:47], v[178:181], v[194:197], v[44:47]
	v_mfma_f32_16x16x32_bf16 v[40:43], v[186:189], v[194:197], v[40:43]
	v_mfma_f32_16x16x32_bf16 v[28:31], v[178:181], v[202:205], v[28:31]
	v_mfma_f32_16x16x32_bf16 v[24:27], v[186:189], v[202:205], v[24:27]
	v_mfma_f32_16x16x32_bf16 v[12:15], v[178:181], v[210:213], v[12:15]
	v_mfma_f32_16x16x32_bf16 v[8:11], v[186:189], v[210:213], v[8:11]
	v_mfma_f32_16x16x32_bf16 v[4:7], v[178:181], v[218:221], v[4:7]
	v_mfma_f32_16x16x32_bf16 v[0:3], v[186:189], v[218:221], v[0:3]
	s_setprio 0
	s_barrier
	s_add_i32 s70, s70, 2
	s_add_u32 s20, s20, 0x100
	s_addc_u32 s21, s21, 0
	s_add_u32 s29, s29, 0x100
	s_addc_u32 s69, s69, 0
	s_cmp_gt_u32 s70, 29
	s_mov_b32 s100, 0
	s_cbranch_scc0 .LBB0_220
	s_and_b64 vcc, exec, s[6:7]
	s_cbranch_vccz .LBB0_223
	s_barrier
; __device__ __forceinline__ unsigned cvt_pk_bf16(float lo, float hi) { return pk2(lo, hi); }
;     __device__ __forceinline__ void operator()(const f32x4 (&acc)[2][2][4][2], const Unit& u, int wr, int wc, int fr, int fq) const {
;         const int row0 = u.pm * BM + wr * 64 + fr; const int col0 = u.pn * BM + wc * 32 + 8 * fq;
;         bf16_t* O = u.mode ? O1 : O0; const int ldc = u.mode ? ldc1 : ldc0;
; #pragma unroll
;         for (int ai = 0; ai < 2; ++ai)
; #pragma unroll
;             for (int m = 0; m < 4; ++m) { bf16_t* rowp = O + (size_t)(row0 + ai * HALF + m * 16) * ldc + col0;
; #pragma unroll
;                 for (int bj = 0; bj < 2; ++bj) { f32x4 v0 = acc[ai][bj][m][0], v1 = acc[ai][bj][m][1];
;                     if (ACT == 1) {
; #pragma unroll
;                         for (int e = 0; e < 4; ++e) { float a = fmaxf(v0[e], 0.f), b = fmaxf(v1[e], 0.f); v0[e] = a * a; v1[e] = b * b; } }
;                     u32x4 w; w.x = cvt_pk_bf16(v0[0], v0[1]); w.y = cvt_pk_bf16(v0[2], v0[3]); w.z = cvt_pk_bf16(v1[0], v1[1]); w.w = cvt_pk_bf16(v1[2], v1[3]);
;                     *(u32x4*)(rowp + bj * HALF) = w; } }
.LBB0_223:
	v_lshl_or_b32 v152, s9, 8, v147
	s_cmp_eq_u32 s34, 0
	s_mov_b32 s9, 0x10a00000
	s_cselect_b32 s9, s9, 0x19c00000
	s_movk_i32 s13, 0x1100
	s_cselect_b32 s13, s13, 0x4400
	s_add_u32 s20, s90, s9
	s_addc_u32 s21, s91, 0
	v_lshl_add_u32 v151, s8, 8, v145
	v_ashrrev_i32_e32 v153, 31, v152
	v_lshl_add_u64 v[152:153], v[152:153], 1, s[20:21]
	v_mad_i64_i32 v[154:155], s[8:9], s13, v151, 0
	v_cvt_pk_bf16_f32 v108, v108, v109
	v_cvt_pk_bf16_f32 v109, v110, v111
	v_cvt_pk_bf16_f32 v110, v104, v105
	v_or_b32_e32 v104, 16, v151
	v_lshl_add_u64 v[154:155], v[154:155], 1, v[152:153]
	v_cvt_pk_bf16_f32 v111, v106, v107
	v_mad_i64_i32 v[104:105], s[8:9], s13, v104, 0
	v_cvt_pk_bf16_f32 v92, v92, v93
	v_cvt_pk_bf16_f32 v93, v94, v95
	v_cvt_pk_bf16_f32 v94, v88, v89
	v_or_b32_e32 v88, 32, v151
	v_cvt_pk_bf16_f32 v124, v124, v125
	v_cvt_pk_bf16_f32 v125, v126, v127
	v_cvt_pk_bf16_f32 v126, v120, v121
	v_cvt_pk_bf16_f32 v127, v122, v123
	global_store_dwordx4 v[154:155], v[108:111], off offset:256
	v_cvt_pk_bf16_f32 v95, v90, v91
	v_mad_i64_i32 v[88:89], s[8:9], s13, v88, 0
	v_lshl_add_u64 v[108:109], v[104:105], 1, v[152:153]
	v_cvt_pk_bf16_f32 v76, v76, v77
	v_cvt_pk_bf16_f32 v77, v78, v79
	v_cvt_pk_bf16_f32 v78, v72, v73
	v_or_b32_e32 v72, 48, v151
	v_cvt_pk_bf16_f32 v68, v68, v69
	v_cvt_pk_bf16_f32 v69, v70, v71
	v_cvt_pk_bf16_f32 v70, v64, v65
	v_add_u32_e32 v64, 0x80, v151
	global_store_dwordx4 v[154:155], v[124:127], off
	v_cvt_pk_bf16_f32 v104, v116, v117
	v_cvt_pk_bf16_f32 v105, v118, v119
	v_cvt_pk_bf16_f32 v106, v112, v113
	v_cvt_pk_bf16_f32 v107, v114, v115
	global_store_dwordx4 v[108:109], v[92:95], off offset:256
	v_cvt_pk_bf16_f32 v79, v74, v75
	v_mad_i64_i32 v[72:73], s[8:9], s13, v72, 0
	v_lshl_add_u64 v[92:93], v[88:89], 1, v[152:153]
	v_mad_i64_i32 v[64:65], s[8:9], s13, v64, 0
	v_cvt_pk_bf16_f32 v44, v44, v45
	v_cvt_pk_bf16_f32 v45, v46, v47
	v_cvt_pk_bf16_f32 v46, v40, v41
	v_add_u32_e32 v40, 0x90, v151
	global_store_dwordx4 v[108:109], v[104:107], off
	v_cvt_pk_bf16_f32 v88, v100, v101
	v_cvt_pk_bf16_f32 v89, v102, v103
	v_cvt_pk_bf16_f32 v90, v96, v97
	v_cvt_pk_bf16_f32 v91, v98, v99
	global_store_dwordx4 v[92:93], v[76:79], off offset:256
	v_cvt_pk_bf16_f32 v74, v80, v81
	v_cvt_pk_bf16_f32 v75, v82, v83
	v_lshl_add_u64 v[76:77], v[72:73], 1, v[152:153]
	v_cvt_pk_bf16_f32 v72, v84, v85
	v_cvt_pk_bf16_f32 v73, v86, v87
	v_cvt_pk_bf16_f32 v71, v66, v67
	v_lshl_add_u64 v[64:65], v[64:65], 1, v[152:153]
	v_cvt_pk_bf16_f32 v47, v42, v43
	v_mad_i64_i32 v[40:41], s[8:9], s13, v40, 0
	v_cvt_pk_bf16_f32 v28, v28, v29
	v_cvt_pk_bf16_f32 v29, v30, v31
	v_cvt_pk_bf16_f32 v30, v24, v25
	v_add_u32_e32 v24, 0xa0, v151
	global_store_dwordx4 v[92:93], v[88:91], off
	global_store_dwordx4 v[76:77], v[72:75], off
	global_store_dwordx4 v[76:77], v[68:71], off offset:256
	v_cvt_pk_bf16_f32 v60, v60, v61
	v_cvt_pk_bf16_f32 v61, v62, v63
	v_cvt_pk_bf16_f32 v62, v56, v57
	v_cvt_pk_bf16_f32 v63, v58, v59
	global_store_dwordx4 v[64:65], v[44:47], off offset:256
	v_cvt_pk_bf16_f32 v31, v26, v27
	v_mad_i64_i32 v[24:25], s[8:9], s13, v24, 0
	v_lshl_add_u64 v[44:45], v[40:41], 1, v[152:153]
	v_cvt_pk_bf16_f32 v12, v12, v13
	v_cvt_pk_bf16_f32 v13, v14, v15
	v_cvt_pk_bf16_f32 v14, v8, v9
	v_add_u32_e32 v8, 0xb0, v151
	global_store_dwordx4 v[64:65], v[60:63], off
	v_cvt_pk_bf16_f32 v40, v52, v53
	v_cvt_pk_bf16_f32 v41, v54, v55
	v_cvt_pk_bf16_f32 v42, v48, v49
	v_cvt_pk_bf16_f32 v43, v50, v51
	global_store_dwordx4 v[44:45], v[28:31], off offset:256
	v_cvt_pk_bf16_f32 v15, v10, v11
	v_mad_i64_i32 v[8:9], s[8:9], s13, v8, 0
	v_lshl_add_u64 v[28:29], v[24:25], 1, v[152:153]
	global_store_dwordx4 v[44:45], v[40:43], off
	v_cvt_pk_bf16_f32 v24, v36, v37
	v_cvt_pk_bf16_f32 v25, v38, v39
	v_cvt_pk_bf16_f32 v26, v32, v33
	v_cvt_pk_bf16_f32 v27, v34, v35
	global_store_dwordx4 v[28:29], v[12:15], off offset:256
	v_cvt_pk_bf16_f32 v10, v16, v17
	v_cvt_pk_bf16_f32 v11, v18, v19
	v_lshl_add_u64 v[12:13], v[8:9], 1, v[152:153]
	v_cvt_pk_bf16_f32 v8, v20, v21
	v_cvt_pk_bf16_f32 v9, v22, v23
	v_cvt_pk_bf16_f32 v4, v4, v5
	v_cvt_pk_bf16_f32 v5, v6, v7
	v_cvt_pk_bf16_f32 v6, v0, v1
	v_cvt_pk_bf16_f32 v7, v2, v3
	s_andn2_b64 vcc, exec, s[18:19]
	s_mov_b64 s[8:9], -1
	global_store_dwordx4 v[28:29], v[24:27], off
	global_store_dwordx4 v[12:13], v[8:11], off
	global_store_dwordx4 v[12:13], v[4:7], off offset:256
	s_mov_b32 s100, 1
	s_cbranch_vccnz .LBB0_210
	s_andn2_b64 vcc, exec, s[2:3]
	s_cbranch_vccnz .LBB0_209
	s_barrier
	s_branch .LBB0_209

.LBB0_546:
	s_waitcnt lgkmcnt(0)
	s_barrier
	s_add_i32 s26, s47, 4
	s_and_b64 s[2:3], s[2:3], exec
	s_cselect_b32 s2, s47, s26
	s_addk_i32 s33, 0xff80
	s_addk_i32 s46, 0x80
	s_add_i32 s47, s47, 2
	v_lshl_add_u64 v[92:93], v[92:93], 0, s[16:17]
	v_lshl_add_u64 v[94:95], v[94:95], 0, s[14:15]
	s_cmpk_lt_u32 s50, 0x42
	v_lshl_add_u32 v85, s2, 6, v106
	s_mov_b64 s[2:3], 0x400
	v_lshl_add_u64 v[90:91], v[90:91], 0, s[2:3]
	ds_read_b128 v[188:191], v81 offset:61440
	ds_read_b128 v[192:195], v81 offset:61504
	ds_read_b128 v[196:199], v81 offset:61568
	ds_read_b128 v[200:203], v81 offset:61632
	ds_read_b128 v[204:207], v148
	ds_read_b128 v[208:211], v148 offset:64
	ds_read_b128 v[212:215], v148 offset:128
	ds_read_b128 v[216:219], v148 offset:192
	ds_read_b128 v[220:223], v150
	ds_read_b128 v[224:227], v150 offset:64
	ds_read_b128 v[228:231], v150 offset:128
	ds_read_b128 v[232:235], v150 offset:192
	s_waitcnt lgkmcnt(0)
	v_mfma_f32_16x16x32_bf16 v[96:99], v[188:191], v[204:207], 0
	v_mfma_f32_16x16x32_bf16 v[236:239], v[188:191], v[220:223], 0
	v_mfma_f32_16x16x32_bf16 v[96:99], v[192:195], v[208:211], v[96:99]
	v_mfma_f32_16x16x32_bf16 v[236:239], v[192:195], v[224:227], v[236:239]
	v_mfma_f32_16x16x32_bf16 v[96:99], v[196:199], v[212:215], v[96:99]
	v_mfma_f32_16x16x32_bf16 v[236:239], v[196:199], v[228:231], v[236:239]
	v_mfma_f32_16x16x32_bf16 v[96:99], v[200:203], v[216:219], v[96:99]
	v_mfma_f32_16x16x32_bf16 v[236:239], v[200:203], v[232:235], v[236:239]
	ds_read_b128 v[188:191], v83
	ds_read_b128 v[192:195], v83 offset:64
	ds_read_b128 v[204:207], v149
	ds_read_b128 v[208:211], v149 offset:64
	ds_read_b128 v[220:223], v151
	ds_read_b128 v[224:227], v151 offset:64
	s_waitcnt lgkmcnt(0)
	v_mfma_f32_16x16x32_bf16 v[96:99], v[188:191], v[204:207], v[96:99]
	v_mfma_f32_16x16x32_bf16 v[236:239], v[188:191], v[220:223], v[236:239]
	v_mfma_f32_16x16x32_bf16 v[96:99], v[192:195], v[208:211], v[96:99]
	v_mfma_f32_16x16x32_bf16 v[236:239], v[192:195], v[224:227], v[236:239]
	ds_read_u16 v192, v142
	ds_read_u16 v188, v142 offset:272
	ds_read_u16 v189, v142 offset:544
	ds_read_u16 v193, v142 offset:816
	ds_read_u16 v190, v142 offset:1088
	ds_read_u16 v194, v142 offset:1360
	ds_read_u16 v191, v142 offset:1632
	ds_read_u16 v195, v142 offset:1904
	ds_read_u16 v200, v142 offset:8704
	ds_read_u16 v196, v142 offset:8976
	ds_read_u16 v197, v142 offset:9248
	ds_read_u16 v201, v142 offset:9520
	ds_read_u16 v198, v142 offset:9792
	ds_read_u16 v202, v142 offset:10064
	ds_read_u16 v199, v142 offset:10336
	ds_read_u16 v203, v142 offset:10608
	ds_read_b128 v[204:207], v136
	ds_read_b128 v[208:211], v137
	ds_read_b128 v[212:215], v137 offset:2304
	ds_read_b128 v[216:219], v137 offset:4608
	ds_read_b128 v[220:223], v136 offset:64
	ds_read_b128 v[224:227], v137 offset:64
	ds_read_b128 v[228:231], v137 offset:2368
	ds_read_b128 v[232:235], v137 offset:4672
	s_waitcnt lgkmcnt(8)
	v_perm_b32 v189, v193, v189, s44
	v_perm_b32 v188, v188, v192, s44
	v_perm_b32 v190, v194, v190, s44
	v_perm_b32 v191, v195, v191, s44
	v_perm_b32 v197, v201, v197, s44
	v_perm_b32 v196, v196, v200, s44
	v_perm_b32 v198, v202, v198, s44
	v_perm_b32 v199, v203, v199, s44
	ds_write2_b32 v87, v96, v97 offset0:128 offset1:196
	ds_write2_b32 v139, v98, v99 offset0:8 offset1:76
	ds_write2_b32 v140, v236, v237 offset0:128 offset1:196
	ds_write2_b32 v141, v238, v239 offset0:8 offset1:76
	s_waitcnt lgkmcnt(4)
	v_mfma_f32_16x16x32_bf16 v[48:51], v[188:191], v[204:207], v[48:51]
	v_mfma_f32_16x16x32_bf16 v[52:55], v[188:191], v[208:211], v[52:55]
	v_mfma_f32_16x16x32_bf16 v[56:59], v[188:191], v[212:215], v[56:59]
	v_mfma_f32_16x16x32_bf16 v[60:63], v[188:191], v[216:219], v[60:63]
	v_mfma_f32_16x16x32_bf16 v[48:51], v[196:199], v[220:223], v[48:51]
	v_mfma_f32_16x16x32_bf16 v[52:55], v[196:199], v[224:227], v[52:55]
	v_mfma_f32_16x16x32_bf16 v[56:59], v[196:199], v[228:231], v[56:59]
	v_mfma_f32_16x16x32_bf16 v[60:63], v[196:199], v[232:235], v[60:63]
	ds_read_b128 v[96:99], v65 offset:60928
	s_waitcnt lgkmcnt(0)
	s_barrier
	v_pk_mul_f32 v[50:51], v[50:51], v[98:99]
	v_pk_mul_f32 v[48:49], v[48:49], v[96:97]
	v_pk_mul_f32 v[54:55], v[54:55], v[98:99]
	v_pk_mul_f32 v[52:53], v[52:53], v[96:97]
	v_pk_mul_f32 v[56:57], v[56:57], v[96:97]
	v_pk_mul_f32 v[60:61], v[60:61], v[96:97]
	v_cvt_pk_bf16_f32 v96, v48, v49
	v_cvt_pk_bf16_f32 v97, v50, v51
	v_pk_mul_f32 v[58:59], v[58:59], v[98:99]
	ds_write_b64 v143, v[96:97]
	v_cvt_pk_bf16_f32 v96, v52, v53
	v_cvt_pk_bf16_f32 v97, v54, v55
	v_pk_mul_f32 v[62:63], v[62:63], v[98:99]
	ds_write_b64 v145, v[96:97]
	v_cvt_pk_bf16_f32 v96, v56, v57
	v_cvt_pk_bf16_f32 v97, v58, v59
	ds_write_b64 v146, v[96:97]
	v_cvt_pk_bf16_f32 v96, v60, v61
	v_cvt_pk_bf16_f32 v97, v62, v63
	ds_write_b64 v145, v[96:97] offset:8704
	v_sub_u32_e32 v96, s51, v85
	v_cndmask_b32_e64 v96, v96, v85, s[6:7]
	v_ashrrev_i32_e32 v97, 31, v96
	v_lshl_add_u64 v[96:97], s[24:25], 0, v[96:97]
	v_lshlrev_b64 v[96:97], 11, v[96:97]
	v_lshl_add_u64 v[156:157], v[76:77], 0, v[96:97]
	ds_read_b128 v[96:99], v130 offset:25088
	ds_read_b128 v[152:155], v130 offset:25104
	s_waitcnt lgkmcnt(1)
	v_cvt_pk_bf16_f32 v96, v96, v97
	v_cvt_pk_bf16_f32 v97, v98, v99
	s_waitcnt lgkmcnt(0)
	v_cvt_pk_bf16_f32 v98, v152, v153
	v_cvt_pk_bf16_f32 v99, v154, v155
	global_store_dwordx4 v[156:157], v[96:99], off
	s_cbranch_scc0 .LBB0_515

.LBB0_555:
	s_waitcnt lgkmcnt(0)
	s_barrier
	s_cmp_gt_u32 s50, 3
	s_cselect_b64 s[2:3], -1, 0
	s_add_i32 s26, s46, 0xffffff00
	s_and_b64 s[24:25], s[2:3], exec
	s_cselect_b32 s24, s26, s46
	s_cselect_b32 s25, s1, s23
	s_mov_b64 s[26:27], -1
	v_or_b32_e32 v85, s24, v106
	s_movk_i32 s24, 0xfff
	s_cselect_b32 s51, s24, 0xff
	s_cselect_b32 s24, s0, s22
	s_and_b64 vcc, exec, s[20:21]
	ds_read_b128 v[188:191], v81 offset:61440
	ds_read_b128 v[192:195], v81 offset:61504
	ds_read_b128 v[196:199], v81 offset:61568
	ds_read_b128 v[200:203], v81 offset:61632
	ds_read_b128 v[204:207], v148
	ds_read_b128 v[208:211], v148 offset:64
	ds_read_b128 v[212:215], v148 offset:128
	ds_read_b128 v[216:219], v148 offset:192
	ds_read_b128 v[220:223], v150
	ds_read_b128 v[224:227], v150 offset:64
	ds_read_b128 v[228:231], v150 offset:128
	ds_read_b128 v[232:235], v150 offset:192
	s_waitcnt lgkmcnt(0)
	v_mfma_f32_16x16x32_bf16 v[152:155], v[188:191], v[204:207], 0
	v_mfma_f32_16x16x32_bf16 v[236:239], v[188:191], v[220:223], 0
	v_mfma_f32_16x16x32_bf16 v[152:155], v[192:195], v[208:211], v[152:155]
	v_mfma_f32_16x16x32_bf16 v[236:239], v[192:195], v[224:227], v[236:239]
	v_mfma_f32_16x16x32_bf16 v[152:155], v[196:199], v[212:215], v[152:155]
	v_mfma_f32_16x16x32_bf16 v[236:239], v[196:199], v[228:231], v[236:239]
	v_mfma_f32_16x16x32_bf16 v[152:155], v[200:203], v[216:219], v[152:155]
	v_mfma_f32_16x16x32_bf16 v[236:239], v[200:203], v[232:235], v[236:239]
	ds_read_b128 v[188:191], v83
	ds_read_b128 v[192:195], v83 offset:64
	ds_read_b128 v[204:207], v149
	ds_read_b128 v[208:211], v149 offset:64
	ds_read_b128 v[220:223], v151
	ds_read_b128 v[224:227], v151 offset:64
	s_waitcnt lgkmcnt(0)
	v_mfma_f32_16x16x32_bf16 v[152:155], v[188:191], v[204:207], v[152:155]
	v_mfma_f32_16x16x32_bf16 v[236:239], v[188:191], v[220:223], v[236:239]
	v_mfma_f32_16x16x32_bf16 v[152:155], v[192:195], v[208:211], v[152:155]
	v_mfma_f32_16x16x32_bf16 v[236:239], v[192:195], v[224:227], v[236:239]
	ds_read_u16 v192, v142
	ds_read_u16 v188, v142 offset:272
	ds_read_u16 v189, v142 offset:544
	ds_read_u16 v193, v142 offset:816
	ds_read_u16 v190, v142 offset:1088
	ds_read_u16 v194, v142 offset:1360
	ds_read_u16 v191, v142 offset:1632
	ds_read_u16 v195, v142 offset:1904
	ds_read_u16 v200, v142 offset:8704
	ds_read_u16 v196, v142 offset:8976
	ds_read_u16 v197, v142 offset:9248
	ds_read_u16 v201, v142 offset:9520
	ds_read_u16 v198, v142 offset:9792
	ds_read_u16 v202, v142 offset:10064
	ds_read_u16 v199, v142 offset:10336
	ds_read_u16 v203, v142 offset:10608
	ds_read_b128 v[204:207], v136
	ds_read_b128 v[208:211], v137
	ds_read_b128 v[212:215], v137 offset:2304
	ds_read_b128 v[216:219], v137 offset:4608
	ds_read_b128 v[220:223], v136 offset:64
	ds_read_b128 v[224:227], v137 offset:64
	ds_read_b128 v[228:231], v137 offset:2368
	ds_read_b128 v[232:235], v137 offset:4672
	s_waitcnt lgkmcnt(8)
	v_perm_b32 v189, v193, v189, s44
	v_perm_b32 v188, v188, v192, s44
	v_perm_b32 v190, v194, v190, s44
	v_perm_b32 v191, v195, v191, s44
	v_perm_b32 v197, v201, v197, s44
	v_perm_b32 v196, v196, v200, s44
	v_perm_b32 v198, v202, v198, s44
	v_perm_b32 v199, v203, v199, s44
	ds_write2_b32 v87, v152, v153 offset0:128 offset1:196
	ds_write2_b32 v139, v154, v155 offset0:8 offset1:76
	ds_write2_b32 v140, v236, v237 offset0:128 offset1:196
	ds_write2_b32 v141, v238, v239 offset0:8 offset1:76
	s_waitcnt lgkmcnt(4)
	v_mfma_f32_16x16x32_bf16 v[48:51], v[188:191], v[204:207], v[48:51]
	v_mfma_f32_16x16x32_bf16 v[52:55], v[188:191], v[208:211], v[52:55]
	v_mfma_f32_16x16x32_bf16 v[56:59], v[188:191], v[212:215], v[56:59]
	v_mfma_f32_16x16x32_bf16 v[60:63], v[188:191], v[216:219], v[60:63]
	v_mfma_f32_16x16x32_bf16 v[48:51], v[196:199], v[220:223], v[48:51]
	v_mfma_f32_16x16x32_bf16 v[52:55], v[196:199], v[224:227], v[52:55]
	v_mfma_f32_16x16x32_bf16 v[56:59], v[196:199], v[228:231], v[56:59]
	v_mfma_f32_16x16x32_bf16 v[60:63], v[196:199], v[232:235], v[60:63]
	ds_read_b128 v[152:155], v65 offset:60928
	s_waitcnt lgkmcnt(0)
	s_barrier
	v_pk_mul_f32 v[50:51], v[50:51], v[154:155]
	v_pk_mul_f32 v[48:49], v[48:49], v[152:153]
	v_pk_mul_f32 v[54:55], v[54:55], v[154:155]
	v_pk_mul_f32 v[52:53], v[52:53], v[152:153]
	v_pk_mul_f32 v[56:57], v[56:57], v[152:153]
	v_pk_mul_f32 v[60:61], v[60:61], v[152:153]
	v_cvt_pk_bf16_f32 v152, v48, v49
	v_cvt_pk_bf16_f32 v153, v50, v51
	v_pk_mul_f32 v[58:59], v[58:59], v[154:155]
	ds_write_b64 v143, v[152:153]
	v_cvt_pk_bf16_f32 v152, v52, v53
	v_cvt_pk_bf16_f32 v153, v54, v55
	v_pk_mul_f32 v[62:63], v[62:63], v[154:155]
	ds_write_b64 v145, v[152:153]
	v_cvt_pk_bf16_f32 v152, v56, v57
	v_cvt_pk_bf16_f32 v153, v58, v59
	ds_write_b64 v146, v[152:153]
	v_cvt_pk_bf16_f32 v152, v60, v61
	v_cvt_pk_bf16_f32 v153, v62, v63
	ds_write_b64 v145, v[152:153] offset:8704
	v_sub_u32_e32 v152, s51, v85
	v_cndmask_b32_e64 v152, v152, v85, s[6:7]
	v_ashrrev_i32_e32 v153, 31, v152
	v_lshl_add_u64 v[152:153], s[24:25], 0, v[152:153]
	v_lshlrev_b64 v[152:153], 11, v[152:153]
	v_lshl_add_u64 v[164:165], v[76:77], 0, v[152:153]
	ds_read_b128 v[152:155], v130 offset:25088
	ds_read_b128 v[156:159], v130 offset:25104
	s_waitcnt lgkmcnt(1)
	v_cvt_pk_bf16_f32 v152, v152, v153
	v_cvt_pk_bf16_f32 v153, v154, v155
	s_waitcnt lgkmcnt(0)
	v_cvt_pk_bf16_f32 v154, v156, v157
	v_cvt_pk_bf16_f32 v155, v158, v159
	global_store_dwordx4 v[164:165], v[152:155], off
	s_waitcnt vmcnt(7)
	ds_write_b128 v113, v[24:27] offset:61440
	s_waitcnt vmcnt(5)
	ds_write_b128 v113, v[32:35] offset:61456
	ds_write_b128 v114, v[28:31]
	s_waitcnt vmcnt(4)
	ds_write_b128 v114, v[36:39] offset:16
	s_waitcnt vmcnt(3)
	ds_write_b128 v118, v[40:43]
	s_cbranch_vccnz .LBB0_561
	s_andn2_b64 vcc, exec, s[26:27]
	s_cbranch_vccz .LBB0_562

; #define PG8_STAGE(bufoff, gbase, voff) do { _Pragma("unroll") for (int _i = 0; _i < 2; ++_i) \
;         __builtin_amdgcn_global_load_lds((const unsigned*)((const char*)(gbase) + (voff)[_i]), (LAS unsigned*)(lds + (bufoff) + ldsw + _i * 8192), 16, 0, 0); } while (0)
; #define PG8_WAIT_V(n) asm volatile("s_waitcnt vmcnt(" #n ")" ::: "memory")
; #define PG8_BAR __builtin_amdgcn_s_barrier()
; template <class Epi, class Sched, bool ALIGN_EPI = false, bool SP2 = false>
; __device__ __forceinline__ void gemm_phase(LAS unsigned char* lds, const Gemm g, const Sched& S, const Epi& E) {
;     ...
;     const char* cA = cur.a; const char* cB = cur.b;
;     S.a_ready(cur);
;     if constexpr (SP2) {
;         PG8_STAGE(PG8_SB(0, 0), cB, voffB); PG8_STAGE(PG8_SB(0, 1), cB + hstep, voffB); PG8_STAGE(PG8_SA(0, 0), cA, voffA); PG8_STAGE(PG8_SA(0, 1), cA + hstep, voffA);
;         if (wr == 1) PG8_BAR;
;         PG8_WAIT_V(2); PG8_BAR;
;         PG8_STAGE(PG8_SB(1, 0), cB + kstep, voffB); PG8_STAGE(PG8_SA(1, 0), cA + kstep, voffA); PG8_STAGE(PG8_SB(1, 1), cB + hstep + kstep, voffB);
;         PG8_WAIT_V(6); PG8_BAR;
;     } else {
;         PG8_STAGE(PG8_SB(0, 0), cB, voffB); PG8_STAGE(PG8_SA(0, 0), cA, voffA); PG8_STAGE(PG8_SB(0, 1), cB + hstep, voffB); PG8_STAGE(PG8_SA(0, 1), cA + hstep, voffA);
;         if (wr == 1) PG8_BAR;
;         PG8_WAIT_V(4); PG8_BAR;
;         PG8_STAGE(PG8_SB(1, 0), cB + kstep, voffB); PG8_STAGE(PG8_SA(1, 0), cA + kstep, voffA); PG8_STAGE(PG8_SB(1, 1), cB + hstep + kstep, voffB);
;         PG8_WAIT_V(6); PG8_BAR;
;     }
; __device__ __forceinline__ void run_gemm_store(const Params& p, LAS unsigned char* ldsl, const int ph) {
;     ...
;     else { E.O0 = (bf16_t*)(ws + WS_H); E.ldc0 = DFF; E.ACT = 1; S.add(A, (const bf16_t*)(ws + WS_WUP) + (size_t)l1 * D * DFF, Mrows / 256, DFF / 256, 1, D / 64, 0); }
.LBB0_882:
	s_cmp_lt_i32 s80, 8
	s_cselect_b64 s[2:3], -1, 0
	s_and_b64 s[2:3], s[2:3], s[0:1]
	s_andn2_b64 vcc, exec, s[2:3]
	s_cbranch_vccnz .LBB0_899
	s_mov_b32 s100, 0
	s_cmpk_gt_i32 s92, 0x87f
	v_readfirstlane_b32 s1, v162
	s_cbranch_scc1 .LBB0_899
	v_lshrrev_b32_e32 v2, 1, v162
	v_and_b32_e32 v11, 24, v2
	v_lshrrev_b32_e32 v2, 5, v162
	v_and_b32_e32 v2, 4, v2
	v_bfe_u32 v3, v162, 2, 2
	s_add_u32 s33, s90, 0xc600000
	v_lshlrev_b32_e32 v0, 4, v162
	v_and_b32_e32 v1, 32, v162
	v_bfe_u32 v10, v162, 2, 4
	v_or3_b32 v2, v2, v3, v11
	v_lshrrev_b32_e32 v3, 3, v162
	s_movk_i32 s0, 0x70
	s_addc_u32 s44, s91, 0
	v_bitop3_b32 v8, v0, v1, 48 bitop3:0x6c
	v_and_b32_e32 v9, 64, v162
	v_and_or_b32 v4, v3, s0, v10
	s_movk_i32 s0, 0x60
	v_add_u32_e32 v12, 0x2000, v0
	s_add_u32 s45, s90, 0x1e00000
	v_or_b32_e32 v1, v8, v9
	v_and_or_b32 v3, v3, s0, v2
	v_lshrrev_b32_e32 v0, 7, v12
	s_movk_i32 s0, 0xf0
	s_addc_u32 s46, s91, 0
	v_lshl_or_b32 v130, v3, 12, v1
	v_and_or_b32 v3, v0, s0, v10
	s_movk_i32 s0, 0xe0
	s_ashr_i32 s48, s92, 31
	v_and_or_b32 v0, v0, s0, v2
	s_lshr_b32 s0, s48, 29
	s_add_i32 s0, s92, s0
	s_lshr_b32 s8, s1, 6
	s_ashr_i32 s6, s0, 3
	s_and_b32 s0, s0, -8
	s_lshr_b32 s10, s1, 8
	s_lshl_b32 s47, s8, 10
	s_sub_i32 s0, s92, s0
	s_cmp_lt_i32 s0, 0
	s_movk_i32 s49, 0x111
	s_cselect_b32 s7, s49, 0x110
	s_mul_i32 s0, s0, s7
	s_add_i32 s0, s0, s6
	s_ashr_i32 s6, s0, 31
	s_lshr_b32 s6, s6, 25
	s_add_i32 s6, s0, s6
	s_ashr_i32 s7, s6, 7
	s_and_b32 s6, s6, 0xff80
	s_sub_i32 s0, s0, s6
	s_bfe_i32 s6, s0, 0x80000
	s_bfe_u32 s6, s6, 0x2000d
	s_add_i32 s6, s0, s6
	s_and_b32 s9, s6, 0xfc
	s_sub_i32 s0, s0, s9
	s_lshl_b32 s7, s7, 2
	s_sext_i32_i8 s0, s0
	s_add_i32 s30, s7, s0
	s_bfe_i32 s0, s6, 0x80000
	s_sext_i32_i16 s0, s0
	s_ashr_i32 s31, s30, 31
	s_lshr_b32 s0, s0, 2
	s_lshl_b64 s[6:7], s[30:31], 20
	s_add_u32 s38, s33, s6
	s_addc_u32 s39, s44, s7
	s_bfe_i64 s[6:7], s[0:1], 0x100000
	s_lshl_b64 s[6:7], s[6:7], 20
	s_add_u32 s40, s45, s6
	s_addc_u32 s41, s46, s7
	s_add_i32 s31, s47, 0
	s_add_i32 m0, s31, 0x10000
	v_lshl_or_b32 v134, v0, 12, v1
	global_load_lds_dwordx4 v130, s[40:41]
	s_add_i32 m0, s31, 0x12000
	s_add_u32 s6, s40, 0x80000
	global_load_lds_dwordx4 v134, s[40:41]
	s_addc_u32 s7, s41, 0
	s_add_i32 m0, s31, 0x14000
	s_add_i32 s50, s31, 0x2000
	global_load_lds_dwordx4 v130, s[6:7]
	s_add_i32 m0, s31, 0x16000
	v_lshl_or_b32 v128, v4, 12, v1
	global_load_lds_dwordx4 v134, s[6:7]
	s_mov_b32 m0, s31
	s_add_u32 s6, s38, 0x80000
	v_lshl_or_b32 v132, v3, 12, v1
	global_load_lds_dwordx4 v128, s[38:39]
	s_mov_b32 m0, s50
	s_addc_u32 s7, s39, 0
	s_add_i32 s51, s31, 0x4000
	global_load_lds_dwordx4 v132, s[38:39]
	s_mov_b32 m0, s51
	s_add_i32 s52, s31, 0x6000
	global_load_lds_dwordx4 v128, s[6:7]
	s_mov_b32 m0, s52
	v_mov_b32_e32 v131, 0
	global_load_lds_dwordx4 v132, s[6:7]
	v_mov_b32_e32 v135, v131
	v_mov_b32_e32 v129, v131
	v_mov_b32_e32 v133, v131
	s_cmp_eq_u32 s10, 1
	s_mov_b32 s53, 0
	v_lshl_add_u64 v[6:7], s[40:41], 0, v[130:131]
	v_lshl_add_u64 v[4:5], s[40:41], 0, v[134:135]
	v_lshl_add_u64 v[0:1], s[38:39], 0, v[128:129]
	s_cselect_b64 s[6:7], -1, 0
	s_cmp_lg_u32 s10, 1
	v_lshl_add_u64 v[2:3], s[38:39], 0, v[132:133]
	s_cbranch_scc1 .LBB0_886
	s_barrier

; #define PG8_STAGE(bufoff, gbase, voff) do { _Pragma("unroll") for (int _i = 0; _i < 2; ++_i) \
;         __builtin_amdgcn_global_load_lds((const unsigned*)((const char*)(gbase) + (voff)[_i]), (LAS unsigned*)(lds + (bufoff) + ldsw + _i * 8192), 16, 0, 0); } while (0)
; #define PG8_LDA(dst, b, h) do { _Pragma("unroll") for (int m = 0; m < 4; ++m) _Pragma("unroll") for (int k = 0; k < 2; ++k) dst[m][k] = *(const LAS bf16x8*)(lds + PG8_SA(b, h) + aoff + m * 2048 + k * 1024); } while (0)
; #define PG8_LDB(dst, b, h) do { _Pragma("unroll") for (int n = 0; n < 2; ++n) _Pragma("unroll") for (int k = 0; k < 2; ++k) dst[n][k] = *(const LAS bf16x8*)(lds + PG8_SB(b, h) + boff + n * 2048 + k * 1024); } while (0)
; #define PG8_MMA(ai, bj, At, Bt) do { __builtin_amdgcn_s_setprio(1); _Pragma("unroll") for (int m = 0; m < 4; ++m) _Pragma("unroll") for (int n = 0; n < 2; ++n) _Pragma("unroll") for (int k = 0; k < 2; ++k) \
;         acc[ai][bj][m][n] = __builtin_amdgcn_mfma_f32_16x16x32_bf16(Bt[n][k], At[m][k], acc[ai][bj][m][n], 0, 0, 0); __builtin_amdgcn_s_setprio(0); } while (0)
; #define PG8_WAIT_V(n) asm volatile("s_waitcnt vmcnt(" #n ")" ::: "memory")
; #define PG8_WAIT_L(n) asm volatile("s_waitcnt lgkmcnt(" #n ")" ::: "memory")
; #define PG8_BAR __builtin_amdgcn_s_barrier()
; #define PG8_SCHED __builtin_amdgcn_sched_barrier(0)
; template <class Epi, class Sched, bool ALIGN_EPI = false, bool SP2 = false>
; __device__ __forceinline__ void gemm_phase(LAS unsigned char* lds, const Gemm g, const Sched& S, const Epi& E) {
;     ...
;             if constexpr (SP2) {
;             PG8_LDB(B0, 0, 0); PG8_LDB(B1, 0, 1); PG8_SCHED; PG8_LDA(At, 0, 0); PG8_STAGE(PG8_SA(1, 1), a1 + hstep, voffA);
;             PG8_WAIT_V(8); PG8_WAIT_L(0); PG8_BAR; PG8_MMA(0, 0, At, B0); PG8_MMA(0, 1, At, B1); PG8_BAR; PG8_SCHED;
.LBB0_892:
	ds_read_b128 v[152:155], v149
	ds_read_b128 v[156:159], v149 offset:1024
	ds_read_b128 v[164:167], v149 offset:2048
	ds_read_b128 v[170:173], v149 offset:3072
	ds_read_b128 v[174:177], v150
	ds_read_b128 v[178:181], v150 offset:1024
	ds_read_b128 v[182:185], v150 offset:2048
	ds_read_b128 v[186:189], v150 offset:3072
	s_add_u32 s40, s38, 0xfff80080
	s_addc_u32 s41, s39, -1
	s_cmp_eq_u32 s65, 28
	s_cselect_b32 s43, s35, s41
	s_cselect_b32 s42, s34, s40
	s_cselect_b32 s41, s37, s25
	s_cselect_b32 s40, s36, s23
	v_lshl_add_u64 v[144:145], s[38:39], 0, v[136:137]
	s_add_i32 m0, s31, 0xc000
	ds_read_b128 v[190:193], v151
	ds_read_b128 v[194:197], v151 offset:1024
	ds_read_b128 v[198:201], v151 offset:2048
	ds_read_b128 v[202:205], v151 offset:3072
	ds_read_b128 v[206:209], v151 offset:4096
	ds_read_b128 v[210:213], v151 offset:5120
	ds_read_b128 v[214:217], v151 offset:6144
	ds_read_b128 v[218:221], v151 offset:7168
	global_load_lds_dwordx4 v[144:145], off
	v_lshl_add_u64 v[144:145], s[38:39], 0, v[138:139]
	s_add_i32 m0, s31, 0xe000
	s_nop 0
	global_load_lds_dwordx4 v[144:145], off
	s_cmp_eq_u32 s100, 1
	s_cbranch_scc1 .Ltw_tilewait_20709_0a
	s_waitcnt vmcnt(8)
	s_branch .Ltw_tilewait_20709_0b

; #define PG8_STAGE(bufoff, gbase, voff) do { _Pragma("unroll") for (int _i = 0; _i < 2; ++_i) \
;         __builtin_amdgcn_global_load_lds((const unsigned*)((const char*)(gbase) + (voff)[_i]), (LAS unsigned*)(lds + (bufoff) + ldsw + _i * 8192), 16, 0, 0); } while (0)
; #define PG8_LDA(dst, b, h) do { _Pragma("unroll") for (int m = 0; m < 4; ++m) _Pragma("unroll") for (int k = 0; k < 2; ++k) dst[m][k] = *(const LAS bf16x8*)(lds + PG8_SA(b, h) + aoff + m * 2048 + k * 1024); } while (0)
; #define PG8_MMA(ai, bj, At, Bt) do { __builtin_amdgcn_s_setprio(1); _Pragma("unroll") for (int m = 0; m < 4; ++m) _Pragma("unroll") for (int n = 0; n < 2; ++n) _Pragma("unroll") for (int k = 0; k < 2; ++k) \
;         acc[ai][bj][m][n] = __builtin_amdgcn_mfma_f32_16x16x32_bf16(Bt[n][k], At[m][k], acc[ai][bj][m][n], 0, 0, 0); __builtin_amdgcn_s_setprio(0); } while (0)
; #define PG8_WAIT_V(n) asm volatile("s_waitcnt vmcnt(" #n ")" ::: "memory")
; #define PG8_WAIT_L(n) asm volatile("s_waitcnt lgkmcnt(" #n ")" ::: "memory")
; #define PG8_BAR __builtin_amdgcn_s_barrier()
; #define PG8_SCHED __builtin_amdgcn_sched_barrier(0)
; template <class Epi, class Sched, bool ALIGN_EPI = false, bool SP2 = false>
; __device__ __forceinline__ void gemm_phase(LAS unsigned char* lds, const Gemm g, const Sched& S, const Epi& E) {
;     ...
;             PG8_WAIT_V(8); PG8_WAIT_L(0); PG8_BAR; PG8_MMA(0, 0, At, B0); PG8_MMA(0, 1, At, B1); PG8_BAR; PG8_SCHED;
;             PG8_LDA(At, 0, 1); PG8_STAGE(PG8_SB(0, 0), b2, voffB); PG8_STAGE(PG8_SB(0, 1), b2 + hstep, voffB); PG8_STAGE(PG8_SA(0, 0), a2, voffA);
;             PG8_WAIT_V(8); PG8_WAIT_L(0); PG8_BAR; PG8_MMA(1, 0, At, B0); PG8_MMA(1, 1, At, B1); PG8_BAR; PG8_SCHED;
.Ltw_tilewait_20709_0b:
	s_waitcnt lgkmcnt(0)
	s_barrier
	s_setprio 1
	s_waitcnt lgkmcnt(0)
	v_mfma_f32_16x16x32_bf16 v[124:127], v[152:155], v[190:193], v[124:127]
	v_mfma_f32_16x16x32_bf16 v[120:123], v[164:167], v[190:193], v[120:123]
	v_mfma_f32_16x16x32_bf16 v[108:111], v[152:155], v[198:201], v[108:111]
	v_mfma_f32_16x16x32_bf16 v[104:107], v[164:167], v[198:201], v[104:107]
	v_mfma_f32_16x16x32_bf16 v[92:95], v[152:155], v[206:209], v[92:95]
	v_mfma_f32_16x16x32_bf16 v[88:91], v[164:167], v[206:209], v[88:91]
	v_mfma_f32_16x16x32_bf16 v[76:79], v[152:155], v[214:217], v[76:79]
	v_mfma_f32_16x16x32_bf16 v[72:75], v[164:167], v[214:217], v[72:75]
	v_mfma_f32_16x16x32_bf16 v[124:127], v[156:159], v[194:197], v[124:127]
	v_mfma_f32_16x16x32_bf16 v[120:123], v[170:173], v[194:197], v[120:123]
	v_mfma_f32_16x16x32_bf16 v[108:111], v[156:159], v[202:205], v[108:111]
	v_mfma_f32_16x16x32_bf16 v[104:107], v[170:173], v[202:205], v[104:107]
	v_mfma_f32_16x16x32_bf16 v[92:95], v[156:159], v[210:213], v[92:95]
	v_mfma_f32_16x16x32_bf16 v[88:91], v[170:173], v[210:213], v[88:91]
	v_mfma_f32_16x16x32_bf16 v[76:79], v[156:159], v[218:221], v[76:79]
	v_mfma_f32_16x16x32_bf16 v[72:75], v[170:173], v[218:221], v[72:75]
	s_setprio 0
	s_setprio 1
	v_mfma_f32_16x16x32_bf16 v[116:119], v[174:177], v[190:193], v[116:119]
	v_mfma_f32_16x16x32_bf16 v[112:115], v[182:185], v[190:193], v[112:115]
	v_mfma_f32_16x16x32_bf16 v[100:103], v[174:177], v[198:201], v[100:103]
	v_mfma_f32_16x16x32_bf16 v[96:99], v[182:185], v[198:201], v[96:99]
	v_mfma_f32_16x16x32_bf16 v[84:87], v[174:177], v[206:209], v[84:87]
	v_mfma_f32_16x16x32_bf16 v[80:83], v[182:185], v[206:209], v[80:83]
	v_mfma_f32_16x16x32_bf16 v[68:71], v[174:177], v[214:217], v[68:71]
	v_mfma_f32_16x16x32_bf16 v[64:67], v[182:185], v[214:217], v[64:67]
	v_mfma_f32_16x16x32_bf16 v[116:119], v[178:181], v[194:197], v[116:119]
	v_mfma_f32_16x16x32_bf16 v[112:115], v[186:189], v[194:197], v[112:115]
	v_mfma_f32_16x16x32_bf16 v[100:103], v[178:181], v[202:205], v[100:103]
	v_mfma_f32_16x16x32_bf16 v[96:99], v[186:189], v[202:205], v[96:99]
	v_mfma_f32_16x16x32_bf16 v[84:87], v[178:181], v[210:213], v[84:87]
	v_mfma_f32_16x16x32_bf16 v[80:83], v[186:189], v[210:213], v[80:83]
	v_mfma_f32_16x16x32_bf16 v[68:71], v[178:181], v[218:221], v[68:71]
	v_mfma_f32_16x16x32_bf16 v[64:67], v[186:189], v[218:221], v[64:67]
	s_setprio 0
	s_barrier
	s_add_i32 s66, s58, s47
	v_lshl_add_u64 v[144:145], s[40:41], 0, v[130:131]
	s_mov_b32 m0, s66
	ds_read_b128 v[190:193], v151 offset:16384
	ds_read_b128 v[194:197], v151 offset:17408
	ds_read_b128 v[198:201], v151 offset:18432
	ds_read_b128 v[202:205], v151 offset:19456
	ds_read_b128 v[206:209], v151 offset:20480
	ds_read_b128 v[210:213], v151 offset:21504
	ds_read_b128 v[214:217], v151 offset:22528
	ds_read_b128 v[218:221], v151 offset:23552
	global_load_lds_dwordx4 v[144:145], off
	s_add_i32 m0, s66, 0x2000
	s_add_u32 s66, s40, 0x80000
	v_lshl_add_u64 v[222:223], s[40:41], 0, v[134:135]
	s_addc_u32 s67, s41, 0
	s_add_i32 s68, s59, s47
	global_load_lds_dwordx4 v[222:223], off
	v_lshl_add_u64 v[224:225], s[66:67], 0, v[130:131]
	s_mov_b32 m0, s68
	v_lshl_add_u64 v[226:227], s[42:43], 0, v[132:133]
	global_load_lds_dwordx4 v[224:225], off
	v_lshl_add_u64 v[224:225], s[66:67], 0, v[134:135]
	s_add_i32 m0, s68, 0x2000
	s_nop 0
	global_load_lds_dwordx4 v[224:225], off
	v_lshl_add_u64 v[224:225], s[42:43], 0, v[128:129]
	s_mov_b32 m0, s31
	s_nop 0
	global_load_lds_dwordx4 v[224:225], off
	s_mov_b32 m0, s50
	s_nop 0
	global_load_lds_dwordx4 v[226:227], off
	s_cmp_eq_u32 s100, 1
	s_cbranch_scc1 .Ltw_tilewait_20709_1a
	s_waitcnt vmcnt(8)
	s_branch .Ltw_tilewait_20709_1b

; #define PG8_STAGE(bufoff, gbase, voff) do { _Pragma("unroll") for (int _i = 0; _i < 2; ++_i) \
;         __builtin_amdgcn_global_load_lds((const unsigned*)((const char*)(gbase) + (voff)[_i]), (LAS unsigned*)(lds + (bufoff) + ldsw + _i * 8192), 16, 0, 0); } while (0)
; #define PG8_LDA(dst, b, h) do { _Pragma("unroll") for (int m = 0; m < 4; ++m) _Pragma("unroll") for (int k = 0; k < 2; ++k) dst[m][k] = *(const LAS bf16x8*)(lds + PG8_SA(b, h) + aoff + m * 2048 + k * 1024); } while (0)
; #define PG8_LDB(dst, b, h) do { _Pragma("unroll") for (int n = 0; n < 2; ++n) _Pragma("unroll") for (int k = 0; k < 2; ++k) dst[n][k] = *(const LAS bf16x8*)(lds + PG8_SB(b, h) + boff + n * 2048 + k * 1024); } while (0)
; #define PG8_MMA(ai, bj, At, Bt) do { __builtin_amdgcn_s_setprio(1); _Pragma("unroll") for (int m = 0; m < 4; ++m) _Pragma("unroll") for (int n = 0; n < 2; ++n) _Pragma("unroll") for (int k = 0; k < 2; ++k) \
;         acc[ai][bj][m][n] = __builtin_amdgcn_mfma_f32_16x16x32_bf16(Bt[n][k], At[m][k], acc[ai][bj][m][n], 0, 0, 0); __builtin_amdgcn_s_setprio(0); } while (0)
; #define PG8_WAIT_V(n) asm volatile("s_waitcnt vmcnt(" #n ")" ::: "memory")
; #define PG8_WAIT_L(n) asm volatile("s_waitcnt lgkmcnt(" #n ")" ::: "memory")
; #define PG8_BAR __builtin_amdgcn_s_barrier()
; #define PG8_SCHED __builtin_amdgcn_sched_barrier(0)
; template <class Epi, class Sched, bool ALIGN_EPI = false, bool SP2 = false>
; __device__ __forceinline__ void gemm_phase(LAS unsigned char* lds, const Gemm g, const Sched& S, const Epi& E) {
;     ...
;             PG8_WAIT_V(8); PG8_WAIT_L(0); PG8_BAR; PG8_MMA(1, 0, At, B0); PG8_MMA(1, 1, At, B1); PG8_BAR; PG8_SCHED;
;             PG8_LDB(B0, 1, 0); PG8_LDB(B1, 1, 1); PG8_SCHED; PG8_LDA(At, 1, 0); PG8_STAGE(PG8_SA(0, 1), a2 + hstep, voffA);
;             PG8_WAIT_V(8); PG8_WAIT_L(0); PG8_BAR; PG8_MMA(0, 0, At, B0); PG8_MMA(0, 1, At, B1); PG8_BAR; PG8_SCHED;
.Ltw_tilewait_20709_1b:
	s_waitcnt lgkmcnt(0)
	s_barrier
	s_setprio 1
	s_waitcnt lgkmcnt(0)
	v_mfma_f32_16x16x32_bf16 v[60:63], v[152:155], v[190:193], v[60:63]
	v_mfma_f32_16x16x32_bf16 v[56:59], v[164:167], v[190:193], v[56:59]
	v_mfma_f32_16x16x32_bf16 v[44:47], v[152:155], v[198:201], v[44:47]
	v_mfma_f32_16x16x32_bf16 v[40:43], v[164:167], v[198:201], v[40:43]
	v_mfma_f32_16x16x32_bf16 v[28:31], v[152:155], v[206:209], v[28:31]
	v_mfma_f32_16x16x32_bf16 v[24:27], v[164:167], v[206:209], v[24:27]
	v_mfma_f32_16x16x32_bf16 v[12:15], v[152:155], v[214:217], v[12:15]
	v_mfma_f32_16x16x32_bf16 v[8:11], v[164:167], v[214:217], v[8:11]
	v_mfma_f32_16x16x32_bf16 v[60:63], v[156:159], v[194:197], v[60:63]
	v_mfma_f32_16x16x32_bf16 v[56:59], v[170:173], v[194:197], v[56:59]
	v_mfma_f32_16x16x32_bf16 v[44:47], v[156:159], v[202:205], v[44:47]
	v_mfma_f32_16x16x32_bf16 v[40:43], v[170:173], v[202:205], v[40:43]
	v_mfma_f32_16x16x32_bf16 v[28:31], v[156:159], v[210:213], v[28:31]
	v_mfma_f32_16x16x32_bf16 v[24:27], v[170:173], v[210:213], v[24:27]
	v_mfma_f32_16x16x32_bf16 v[12:15], v[156:159], v[218:221], v[12:15]
	v_mfma_f32_16x16x32_bf16 v[8:11], v[170:173], v[218:221], v[8:11]
	s_setprio 0
	s_setprio 1
	v_mfma_f32_16x16x32_bf16 v[52:55], v[174:177], v[190:193], v[52:55]
	v_mfma_f32_16x16x32_bf16 v[48:51], v[182:185], v[190:193], v[48:51]
	v_mfma_f32_16x16x32_bf16 v[36:39], v[174:177], v[198:201], v[36:39]
	v_mfma_f32_16x16x32_bf16 v[32:35], v[182:185], v[198:201], v[32:35]
	v_mfma_f32_16x16x32_bf16 v[20:23], v[174:177], v[206:209], v[20:23]
	v_mfma_f32_16x16x32_bf16 v[16:19], v[182:185], v[206:209], v[16:19]
	v_mfma_f32_16x16x32_bf16 v[4:7], v[174:177], v[214:217], v[4:7]
	v_mfma_f32_16x16x32_bf16 v[0:3], v[182:185], v[214:217], v[0:3]
	v_mfma_f32_16x16x32_bf16 v[52:55], v[178:181], v[194:197], v[52:55]
	v_mfma_f32_16x16x32_bf16 v[48:51], v[186:189], v[194:197], v[48:51]
	v_mfma_f32_16x16x32_bf16 v[36:39], v[178:181], v[202:205], v[36:39]
	v_mfma_f32_16x16x32_bf16 v[32:35], v[186:189], v[202:205], v[32:35]
	v_mfma_f32_16x16x32_bf16 v[20:23], v[178:181], v[210:213], v[20:23]
	v_mfma_f32_16x16x32_bf16 v[16:19], v[186:189], v[210:213], v[16:19]
	v_mfma_f32_16x16x32_bf16 v[4:7], v[178:181], v[218:221], v[4:7]
	v_mfma_f32_16x16x32_bf16 v[0:3], v[186:189], v[218:221], v[0:3]
	s_setprio 0
	s_barrier
	s_add_i32 s66, 0, 0x18000
	v_add_u32_e32 v163, s66, v147
	s_add_i32 s67, 0, 0x1c000
	ds_read_b128 v[152:155], v163
	ds_read_b128 v[156:159], v163 offset:1024
	ds_read_b128 v[164:167], v163 offset:2048
	ds_read_b128 v[170:173], v163 offset:3072
	v_add_u32_e32 v163, s67, v147
	ds_read_b128 v[174:177], v163
	ds_read_b128 v[178:181], v163 offset:1024
	ds_read_b128 v[182:185], v163 offset:2048
	ds_read_b128 v[186:189], v163 offset:3072
	s_add_u32 s42, s42, 0x80000
	s_addc_u32 s43, s43, 0
	s_mov_b32 m0, s51
	v_lshl_add_u64 v[228:229], s[42:43], 0, v[128:129]
	ds_read_b128 v[190:193], v151 offset:32768
	ds_read_b128 v[194:197], v151 offset:33792
	ds_read_b128 v[198:201], v151 offset:34816
	ds_read_b128 v[202:205], v151 offset:35840
	ds_read_b128 v[206:209], v151 offset:36864
	ds_read_b128 v[210:213], v151 offset:37888
	ds_read_b128 v[214:217], v151 offset:38912
	ds_read_b128 v[218:221], v151 offset:39936
	global_load_lds_dwordx4 v[228:229], off
	v_lshl_add_u64 v[228:229], s[42:43], 0, v[132:133]
	s_mov_b32 m0, s52
	s_nop 0
	global_load_lds_dwordx4 v[228:229], off
	s_waitcnt vmcnt(8)
	s_waitcnt lgkmcnt(0)
	s_barrier
	s_setprio 1
	s_waitcnt lgkmcnt(0)
	v_mfma_f32_16x16x32_bf16 v[124:127], v[152:155], v[190:193], v[124:127]
	v_mfma_f32_16x16x32_bf16 v[120:123], v[164:167], v[190:193], v[120:123]
	v_mfma_f32_16x16x32_bf16 v[108:111], v[152:155], v[198:201], v[108:111]
	v_mfma_f32_16x16x32_bf16 v[104:107], v[164:167], v[198:201], v[104:107]
	v_mfma_f32_16x16x32_bf16 v[92:95], v[152:155], v[206:209], v[92:95]
	v_mfma_f32_16x16x32_bf16 v[88:91], v[164:167], v[206:209], v[88:91]
	v_mfma_f32_16x16x32_bf16 v[76:79], v[152:155], v[214:217], v[76:79]
	v_mfma_f32_16x16x32_bf16 v[72:75], v[164:167], v[214:217], v[72:75]
	v_mfma_f32_16x16x32_bf16 v[124:127], v[156:159], v[194:197], v[124:127]
	v_mfma_f32_16x16x32_bf16 v[120:123], v[170:173], v[194:197], v[120:123]
	v_mfma_f32_16x16x32_bf16 v[108:111], v[156:159], v[202:205], v[108:111]
	v_mfma_f32_16x16x32_bf16 v[104:107], v[170:173], v[202:205], v[104:107]
	v_mfma_f32_16x16x32_bf16 v[92:95], v[156:159], v[210:213], v[92:95]
	v_mfma_f32_16x16x32_bf16 v[88:91], v[170:173], v[210:213], v[88:91]
	v_mfma_f32_16x16x32_bf16 v[76:79], v[156:159], v[218:221], v[76:79]
	v_mfma_f32_16x16x32_bf16 v[72:75], v[170:173], v[218:221], v[72:75]
	s_setprio 0
	s_setprio 1
	v_mfma_f32_16x16x32_bf16 v[116:119], v[174:177], v[190:193], v[116:119]
	v_mfma_f32_16x16x32_bf16 v[112:115], v[182:185], v[190:193], v[112:115]
	v_mfma_f32_16x16x32_bf16 v[100:103], v[174:177], v[198:201], v[100:103]
	v_mfma_f32_16x16x32_bf16 v[96:99], v[182:185], v[198:201], v[96:99]
	v_mfma_f32_16x16x32_bf16 v[84:87], v[174:177], v[206:209], v[84:87]
	v_mfma_f32_16x16x32_bf16 v[80:83], v[182:185], v[206:209], v[80:83]
	v_mfma_f32_16x16x32_bf16 v[68:71], v[174:177], v[214:217], v[68:71]
	v_mfma_f32_16x16x32_bf16 v[64:67], v[182:185], v[214:217], v[64:67]
	v_mfma_f32_16x16x32_bf16 v[116:119], v[178:181], v[194:197], v[116:119]
	v_mfma_f32_16x16x32_bf16 v[112:115], v[186:189], v[194:197], v[112:115]
	v_mfma_f32_16x16x32_bf16 v[100:103], v[178:181], v[202:205], v[100:103]
	v_mfma_f32_16x16x32_bf16 v[96:99], v[186:189], v[202:205], v[96:99]
	v_mfma_f32_16x16x32_bf16 v[84:87], v[178:181], v[210:213], v[84:87]
	v_mfma_f32_16x16x32_bf16 v[80:83], v[186:189], v[210:213], v[80:83]
	v_mfma_f32_16x16x32_bf16 v[68:71], v[178:181], v[218:221], v[68:71]
	v_mfma_f32_16x16x32_bf16 v[64:67], v[186:189], v[218:221], v[64:67]
	s_setprio 0
	s_barrier
; __device__ __forceinline__ unsigned cvt_pk_bf16(float lo, float hi) { return pk2(lo, hi); }
; #define PG8_STAGE(bufoff, gbase, voff) do { _Pragma("unroll") for (int _i = 0; _i < 2; ++_i) \
;         __builtin_amdgcn_global_load_lds((const unsigned*)((const char*)(gbase) + (voff)[_i]), (LAS unsigned*)(lds + (bufoff) + ldsw + _i * 8192), 16, 0, 0); } while (0)
; #define PG8_LDA(dst, b, h) do { _Pragma("unroll") for (int m = 0; m < 4; ++m) _Pragma("unroll") for (int k = 0; k < 2; ++k) dst[m][k] = *(const LAS bf16x8*)(lds + PG8_SA(b, h) + aoff + m * 2048 + k * 1024); } while (0)
; #define PG8_MMA(ai, bj, At, Bt) do { __builtin_amdgcn_s_setprio(1); _Pragma("unroll") for (int m = 0; m < 4; ++m) _Pragma("unroll") for (int n = 0; n < 2; ++n) _Pragma("unroll") for (int k = 0; k < 2; ++k) \
;         acc[ai][bj][m][n] = __builtin_amdgcn_mfma_f32_16x16x32_bf16(Bt[n][k], At[m][k], acc[ai][bj][m][n], 0, 0, 0); __builtin_amdgcn_s_setprio(0); } while (0)
; #define PG8_WAIT_V(n) asm volatile("s_waitcnt vmcnt(" #n ")" ::: "memory")
; #define PG8_WAIT_L(n) asm volatile("s_waitcnt lgkmcnt(" #n ")" ::: "memory")
;     __device__ __forceinline__ void operator()(const f32x4 (&acc)[2][2][4][2], const Unit& u, int wr, int wc, int fr, int fq) const {
;     ...
;             for (int m = 0; m < 4; ++m) { bf16_t* rowp = O + (size_t)(row0 + ai * HALF + m * 16) * ldc + col0;
; #pragma unroll
;                 for (int bj = 0; bj < 2; ++bj) { f32x4 v0 = acc[ai][bj][m][0], v1 = acc[ai][bj][m][1];
;                     if (ACT == 1) {
; #pragma unroll
;                         for (int e = 0; e < 4; ++e) { float a = fmaxf(v0[e], 0.f), b = fmaxf(v1[e], 0.f); v0[e] = a * a; v1[e] = b * b; } }
;                     u32x4 w; w.x = cvt_pk_bf16(v0[0], v0[1]); w.y = cvt_pk_bf16(v0[2], v0[3]); w.z = cvt_pk_bf16(v1[0], v1[1]); w.w = cvt_pk_bf16(v1[2], v1[3]);
;                     *(u32x4*)(rowp + bj * HALF) = w; } }
; template <class Epi, class Sched, bool ALIGN_EPI = false, bool SP2 = false>
; __device__ __forceinline__ void gemm_phase(LAS unsigned char* lds, const Gemm g, const Sched& S, const Epi& E) {
;     ...
;             PG8_LDA(At, 1, 1); PG8_STAGE(PG8_SB(1, 0), b3, voffB); PG8_STAGE(PG8_SB(1, 1), b3 + hstep, voffB); PG8_STAGE(PG8_SA(1, 0), a3, voffA);
;             PG8_WAIT_V(8); PG8_WAIT_L(0); PG8_BAR; PG8_MMA(1, 0, At, B0); PG8_MMA(1, 1, At, B1); PG8_BAR; PG8_SCHED;
	s_add_i32 s42, s66, s47
	v_lshl_add_u64 v[144:145], v[144:145], 0, s[8:9]
	s_mov_b32 m0, s42
	ds_read_b128 v[190:193], v151 offset:49152
	ds_read_b128 v[194:197], v151 offset:50176
	ds_read_b128 v[198:201], v151 offset:51200
	ds_read_b128 v[202:205], v151 offset:52224
	ds_read_b128 v[206:209], v151 offset:53248
	ds_read_b128 v[210:213], v151 offset:54272
	ds_read_b128 v[214:217], v151 offset:55296
	ds_read_b128 v[218:221], v151 offset:56320
	global_load_lds_dwordx4 v[144:145], off
	s_add_i32 m0, s42, 0x2000
	s_add_u32 s40, s40, 0x80080
	v_lshl_add_u64 v[144:145], v[222:223], 0, s[8:9]
	s_addc_u32 s41, s41, 0
	s_add_i32 s42, s67, s47
	global_load_lds_dwordx4 v[144:145], off
	v_lshl_add_u64 v[144:145], s[40:41], 0, v[130:131]
	s_mov_b32 m0, s42
	s_nop 0
	global_load_lds_dwordx4 v[144:145], off
	v_lshl_add_u64 v[144:145], s[40:41], 0, v[134:135]
	s_add_i32 m0, s42, 0x2000
	s_nop 0
	global_load_lds_dwordx4 v[144:145], off
	v_lshl_add_u64 v[144:145], v[224:225], 0, s[8:9]
	s_mov_b32 m0, s55
	s_nop 0
	global_load_lds_dwordx4 v[144:145], off
	v_lshl_add_u64 v[144:145], v[226:227], 0, s[8:9]
	s_mov_b32 m0, s56
	s_nop 0
	global_load_lds_dwordx4 v[144:145], off
	s_waitcnt vmcnt(8)
	s_waitcnt lgkmcnt(0)
	s_barrier
	s_setprio 1
	s_waitcnt lgkmcnt(0)
	v_mfma_f32_16x16x32_bf16 v[60:63], v[152:155], v[190:193], v[60:63]
	v_mfma_f32_16x16x32_bf16 v[56:59], v[164:167], v[190:193], v[56:59]
	v_mfma_f32_16x16x32_bf16 v[44:47], v[152:155], v[198:201], v[44:47]
	v_mfma_f32_16x16x32_bf16 v[40:43], v[164:167], v[198:201], v[40:43]
	v_mfma_f32_16x16x32_bf16 v[28:31], v[152:155], v[206:209], v[28:31]
	v_mfma_f32_16x16x32_bf16 v[24:27], v[164:167], v[206:209], v[24:27]
	v_mfma_f32_16x16x32_bf16 v[12:15], v[152:155], v[214:217], v[12:15]
	v_mfma_f32_16x16x32_bf16 v[8:11], v[164:167], v[214:217], v[8:11]
	v_mfma_f32_16x16x32_bf16 v[60:63], v[156:159], v[194:197], v[60:63]
	v_mfma_f32_16x16x32_bf16 v[56:59], v[170:173], v[194:197], v[56:59]
	v_mfma_f32_16x16x32_bf16 v[44:47], v[156:159], v[202:205], v[44:47]
	v_mfma_f32_16x16x32_bf16 v[40:43], v[170:173], v[202:205], v[40:43]
	v_mfma_f32_16x16x32_bf16 v[28:31], v[156:159], v[210:213], v[28:31]
	v_mfma_f32_16x16x32_bf16 v[24:27], v[170:173], v[210:213], v[24:27]
	v_mfma_f32_16x16x32_bf16 v[12:15], v[156:159], v[218:221], v[12:15]
	v_mfma_f32_16x16x32_bf16 v[8:11], v[170:173], v[218:221], v[8:11]
	s_setprio 0
	s_setprio 1
	v_mfma_f32_16x16x32_bf16 v[52:55], v[174:177], v[190:193], v[52:55]
	v_mfma_f32_16x16x32_bf16 v[48:51], v[182:185], v[190:193], v[48:51]
	v_mfma_f32_16x16x32_bf16 v[36:39], v[174:177], v[198:201], v[36:39]
	v_mfma_f32_16x16x32_bf16 v[32:35], v[182:185], v[198:201], v[32:35]
	v_mfma_f32_16x16x32_bf16 v[20:23], v[174:177], v[206:209], v[20:23]
	v_mfma_f32_16x16x32_bf16 v[16:19], v[182:185], v[206:209], v[16:19]
	v_mfma_f32_16x16x32_bf16 v[4:7], v[174:177], v[214:217], v[4:7]
	v_mfma_f32_16x16x32_bf16 v[0:3], v[182:185], v[214:217], v[0:3]
	v_mfma_f32_16x16x32_bf16 v[52:55], v[178:181], v[194:197], v[52:55]
	v_mfma_f32_16x16x32_bf16 v[48:51], v[186:189], v[194:197], v[48:51]
	v_mfma_f32_16x16x32_bf16 v[36:39], v[178:181], v[202:205], v[36:39]
	v_mfma_f32_16x16x32_bf16 v[32:35], v[186:189], v[202:205], v[32:35]
	v_mfma_f32_16x16x32_bf16 v[20:23], v[178:181], v[210:213], v[20:23]
	v_mfma_f32_16x16x32_bf16 v[16:19], v[186:189], v[210:213], v[16:19]
	v_mfma_f32_16x16x32_bf16 v[4:7], v[178:181], v[218:221], v[4:7]
	v_mfma_f32_16x16x32_bf16 v[0:3], v[186:189], v[218:221], v[0:3]
	s_setprio 0
	s_barrier
	s_add_i32 s65, s65, 2
	s_add_u32 s38, s38, 0x100
	s_addc_u32 s39, s39, 0
	s_add_u32 s23, s23, 0x100
	s_addc_u32 s25, s25, 0
	s_cmp_gt_u32 s65, 29
	s_mov_b32 s100, 0
	s_cbranch_scc0 .LBB0_892
	s_and_b64 vcc, exec, s[10:11]
	s_cbranch_vccz .LBB0_895
	s_barrier
.LBB0_895:
	v_max_f32_e32 v120, v120, v120
	v_max_f32_e32 v121, v121, v121
	v_max_f32_e32 v120, 0, v120
	v_max_f32_e32 v121, 0, v121
	v_pk_mul_f32 v[156:157], v[120:121], v[120:121]
	v_max_f32_e32 v121, v122, v122
	v_lshl_or_b32 v144, s64, 8, v148
	v_lshl_add_u32 v152, s30, 8, v146
	v_max_f32_e32 v124, v124, v124
	v_max_f32_e32 v125, v125, v125
	v_max_f32_e32 v120, v126, v126
	v_max_f32_e32 v122, 0, v121
	v_max_f32_e32 v121, v127, v127
	v_max_f32_e32 v123, v123, v123
	v_ashrrev_i32_e32 v145, 31, v144
	v_ashrrev_i32_e32 v153, 31, v152
	v_max_f32_e32 v124, 0, v124
	v_max_f32_e32 v125, 0, v125
	v_max_f32_e32 v120, 0, v120
	v_max_f32_e32 v121, 0, v121
	v_max_f32_e32 v123, 0, v123
	v_lshl_add_u64 v[154:155], v[144:145], 1, s[12:13]
	v_lshlrev_b64 v[144:145], 14, v[152:153]
	v_pk_mul_f32 v[124:125], v[124:125], v[124:125]
	v_pk_mul_f32 v[126:127], v[120:121], v[120:121]
	v_pk_mul_f32 v[158:159], v[122:123], v[122:123]
	v_max_f32_e32 v112, v112, v112
	v_max_f32_e32 v113, v113, v113
	v_lshl_add_u64 v[144:145], v[154:155], 0, v[144:145]
	v_cvt_pk_bf16_f32 v120, v124, v125
	v_cvt_pk_bf16_f32 v121, v126, v127
	v_cvt_pk_bf16_f32 v122, v156, v157
	v_cvt_pk_bf16_f32 v123, v158, v159
	v_max_f32_e32 v112, 0, v112
	v_max_f32_e32 v113, 0, v113
	global_store_dwordx4 v[144:145], v[120:123], off
	v_max_f32_e32 v116, v116, v116
	v_max_f32_e32 v117, v117, v117
	v_pk_mul_f32 v[120:121], v[112:113], v[112:113]
	v_max_f32_e32 v113, v114, v114
	v_max_f32_e32 v112, v118, v118
	v_max_f32_e32 v114, 0, v113
	v_max_f32_e32 v113, v119, v119
	v_max_f32_e32 v115, v115, v115
	v_max_f32_e32 v116, 0, v116
	v_max_f32_e32 v117, 0, v117
	v_max_f32_e32 v112, 0, v112
	v_max_f32_e32 v113, 0, v113
	v_max_f32_e32 v115, 0, v115
	v_pk_mul_f32 v[116:117], v[116:117], v[116:117]
	v_pk_mul_f32 v[118:119], v[112:113], v[112:113]
	v_pk_mul_f32 v[122:123], v[114:115], v[114:115]
	v_max_f32_e32 v104, v104, v104
; __device__ __forceinline__ unsigned cvt_pk_bf16(float lo, float hi) { return pk2(lo, hi); }
;     __device__ __forceinline__ void operator()(const f32x4 (&acc)[2][2][4][2], const Unit& u, int wr, int wc, int fr, int fq) const {
;     ...
;             for (int m = 0; m < 4; ++m) { bf16_t* rowp = O + (size_t)(row0 + ai * HALF + m * 16) * ldc + col0;
; #pragma unroll
;                 for (int bj = 0; bj < 2; ++bj) { f32x4 v0 = acc[ai][bj][m][0], v1 = acc[ai][bj][m][1];
;                     if (ACT == 1) {
; #pragma unroll
;                         for (int e = 0; e < 4; ++e) { float a = fmaxf(v0[e], 0.f), b = fmaxf(v1[e], 0.f); v0[e] = a * a; v1[e] = b * b; } }
;                     u32x4 w; w.x = cvt_pk_bf16(v0[0], v0[1]); w.y = cvt_pk_bf16(v0[2], v0[3]); w.z = cvt_pk_bf16(v1[0], v1[1]); w.w = cvt_pk_bf16(v1[2], v1[3]);
;                     *(u32x4*)(rowp + bj * HALF) = w; } }
	v_max_f32_e32 v105, v105, v105
	v_cvt_pk_bf16_f32 v112, v116, v117
	v_cvt_pk_bf16_f32 v113, v118, v119
	v_cvt_pk_bf16_f32 v114, v120, v121
	v_cvt_pk_bf16_f32 v115, v122, v123
	v_max_f32_e32 v104, 0, v104
	v_max_f32_e32 v105, 0, v105
	global_store_dwordx4 v[144:145], v[112:115], off offset:256
	v_max_f32_e32 v108, v108, v108
	v_max_f32_e32 v109, v109, v109
	v_pk_mul_f32 v[114:115], v[104:105], v[104:105]
	v_max_f32_e32 v105, v106, v106
	v_or_b32_e32 v112, 16, v152
	v_max_f32_e32 v104, v110, v110
	v_max_f32_e32 v106, 0, v105
	v_max_f32_e32 v105, v111, v111
	v_max_f32_e32 v107, v107, v107
	v_ashrrev_i32_e32 v113, 31, v112
	v_max_f32_e32 v108, 0, v108
	v_max_f32_e32 v109, 0, v109
	v_max_f32_e32 v104, 0, v104
	v_max_f32_e32 v105, 0, v105
	v_max_f32_e32 v107, 0, v107
	v_lshlrev_b64 v[112:113], 14, v[112:113]
	v_pk_mul_f32 v[108:109], v[108:109], v[108:109]
	v_pk_mul_f32 v[110:111], v[104:105], v[104:105]
	v_pk_mul_f32 v[116:117], v[106:107], v[106:107]
	v_max_f32_e32 v96, v96, v96
	v_max_f32_e32 v97, v97, v97
	v_lshl_add_u64 v[112:113], v[154:155], 0, v[112:113]
	v_cvt_pk_bf16_f32 v104, v108, v109
	v_cvt_pk_bf16_f32 v105, v110, v111
	v_cvt_pk_bf16_f32 v106, v114, v115
	v_cvt_pk_bf16_f32 v107, v116, v117
	v_max_f32_e32 v96, 0, v96
	v_max_f32_e32 v97, 0, v97
	global_store_dwordx4 v[112:113], v[104:107], off
	v_max_f32_e32 v100, v100, v100
	v_max_f32_e32 v101, v101, v101
	v_pk_mul_f32 v[104:105], v[96:97], v[96:97]
	v_max_f32_e32 v97, v98, v98
	v_max_f32_e32 v96, v102, v102
	v_max_f32_e32 v98, 0, v97
	v_max_f32_e32 v97, v103, v103
	v_max_f32_e32 v99, v99, v99
	v_max_f32_e32 v100, 0, v100
	v_max_f32_e32 v101, 0, v101
	v_max_f32_e32 v96, 0, v96
	v_max_f32_e32 v97, 0, v97
	v_max_f32_e32 v99, 0, v99
	v_pk_mul_f32 v[100:101], v[100:101], v[100:101]
	v_pk_mul_f32 v[102:103], v[96:97], v[96:97]
	v_pk_mul_f32 v[106:107], v[98:99], v[98:99]
	v_max_f32_e32 v88, v88, v88
	v_max_f32_e32 v89, v89, v89
	v_cvt_pk_bf16_f32 v96, v100, v101
	v_cvt_pk_bf16_f32 v97, v102, v103
	v_cvt_pk_bf16_f32 v98, v104, v105
	v_cvt_pk_bf16_f32 v99, v106, v107
	v_max_f32_e32 v88, 0, v88
	v_max_f32_e32 v89, 0, v89
	global_store_dwordx4 v[112:113], v[96:99], off offset:256
	v_max_f32_e32 v92, v92, v92
	v_max_f32_e32 v93, v93, v93
	v_pk_mul_f32 v[98:99], v[88:89], v[88:89]
	v_max_f32_e32 v89, v90, v90
	v_or_b32_e32 v96, 32, v152
	v_max_f32_e32 v88, v94, v94
	v_max_f32_e32 v90, 0, v89
	v_max_f32_e32 v89, v95, v95
	v_max_f32_e32 v91, v91, v91
	v_ashrrev_i32_e32 v97, 31, v96
	v_max_f32_e32 v92, 0, v92
	v_max_f32_e32 v93, 0, v93
	v_max_f32_e32 v88, 0, v88
	v_max_f32_e32 v89, 0, v89
	v_max_f32_e32 v91, 0, v91
	v_lshlrev_b64 v[96:97], 14, v[96:97]
	v_pk_mul_f32 v[92:93], v[92:93], v[92:93]
	v_pk_mul_f32 v[94:95], v[88:89], v[88:89]
	v_pk_mul_f32 v[100:101], v[90:91], v[90:91]
	v_max_f32_e32 v80, v80, v80
	v_max_f32_e32 v81, v81, v81
	v_lshl_add_u64 v[96:97], v[154:155], 0, v[96:97]
	v_cvt_pk_bf16_f32 v88, v92, v93
	v_cvt_pk_bf16_f32 v89, v94, v95
	v_cvt_pk_bf16_f32 v90, v98, v99
	v_cvt_pk_bf16_f32 v91, v100, v101
	v_max_f32_e32 v80, 0, v80
	v_max_f32_e32 v81, 0, v81
	global_store_dwordx4 v[96:97], v[88:91], off
	v_max_f32_e32 v84, v84, v84
	v_max_f32_e32 v85, v85, v85
	v_pk_mul_f32 v[88:89], v[80:81], v[80:81]
	v_max_f32_e32 v81, v82, v82
	v_max_f32_e32 v80, v86, v86
	v_max_f32_e32 v82, 0, v81
	v_max_f32_e32 v81, v87, v87
	v_max_f32_e32 v83, v83, v83
	v_max_f32_e32 v84, 0, v84
	v_max_f32_e32 v85, 0, v85
	v_max_f32_e32 v80, 0, v80
	v_max_f32_e32 v81, 0, v81
	v_max_f32_e32 v83, 0, v83
	v_pk_mul_f32 v[84:85], v[84:85], v[84:85]
	v_pk_mul_f32 v[86:87], v[80:81], v[80:81]
	v_pk_mul_f32 v[90:91], v[82:83], v[82:83]
	v_max_f32_e32 v72, v72, v72
	v_max_f32_e32 v73, v73, v73
	v_cvt_pk_bf16_f32 v80, v84, v85
	v_cvt_pk_bf16_f32 v81, v86, v87
	v_cvt_pk_bf16_f32 v82, v88, v89
	v_cvt_pk_bf16_f32 v83, v90, v91
	v_max_f32_e32 v72, 0, v72
	v_max_f32_e32 v73, 0, v73
	global_store_dwordx4 v[96:97], v[80:83], off offset:256
	v_max_f32_e32 v76, v76, v76
	v_max_f32_e32 v77, v77, v77
	v_pk_mul_f32 v[82:83], v[72:73], v[72:73]
	v_max_f32_e32 v73, v74, v74
	v_or_b32_e32 v80, 48, v152
	v_max_f32_e32 v72, v78, v78
	v_max_f32_e32 v74, 0, v73
	v_max_f32_e32 v73, v79, v79
	v_max_f32_e32 v75, v75, v75
	v_ashrrev_i32_e32 v81, 31, v80
	v_max_f32_e32 v76, 0, v76
	v_max_f32_e32 v77, 0, v77
	v_max_f32_e32 v72, 0, v72
	v_max_f32_e32 v73, 0, v73
	v_max_f32_e32 v75, 0, v75
	v_lshlrev_b64 v[80:81], 14, v[80:81]
	v_pk_mul_f32 v[76:77], v[76:77], v[76:77]
	v_pk_mul_f32 v[78:79], v[72:73], v[72:73]
	v_pk_mul_f32 v[84:85], v[74:75], v[74:75]
	v_max_f32_e32 v64, v64, v64
	v_max_f32_e32 v65, v65, v65
	v_lshl_add_u64 v[80:81], v[154:155], 0, v[80:81]
	v_cvt_pk_bf16_f32 v72, v76, v77
	v_cvt_pk_bf16_f32 v73, v78, v79
	v_cvt_pk_bf16_f32 v74, v82, v83
	v_cvt_pk_bf16_f32 v75, v84, v85
	v_max_f32_e32 v64, 0, v64
	v_max_f32_e32 v65, 0, v65
	global_store_dwordx4 v[80:81], v[72:75], off
	v_max_f32_e32 v68, v68, v68
	v_max_f32_e32 v69, v69, v69
	v_pk_mul_f32 v[72:73], v[64:65], v[64:65]
	v_max_f32_e32 v65, v66, v66
	v_max_f32_e32 v64, v70, v70
	v_max_f32_e32 v66, 0, v65
	v_max_f32_e32 v65, v71, v71
	v_max_f32_e32 v67, v67, v67
	v_max_f32_e32 v68, 0, v68
	v_max_f32_e32 v69, 0, v69
	v_max_f32_e32 v64, 0, v64
	v_max_f32_e32 v65, 0, v65
	v_max_f32_e32 v67, 0, v67
	v_pk_mul_f32 v[68:69], v[68:69], v[68:69]
	v_pk_mul_f32 v[70:71], v[64:65], v[64:65]
	v_pk_mul_f32 v[74:75], v[66:67], v[66:67]
	v_max_f32_e32 v56, v56, v56
	v_max_f32_e32 v57, v57, v57
	v_cvt_pk_bf16_f32 v64, v68, v69
	v_cvt_pk_bf16_f32 v65, v70, v71
	v_cvt_pk_bf16_f32 v66, v72, v73
	v_cvt_pk_bf16_f32 v67, v74, v75
	v_max_f32_e32 v56, 0, v56
	v_max_f32_e32 v57, 0, v57
; __device__ __forceinline__ unsigned cvt_pk_bf16(float lo, float hi) { return pk2(lo, hi); }
;     __device__ __forceinline__ void operator()(const f32x4 (&acc)[2][2][4][2], const Unit& u, int wr, int wc, int fr, int fq) const {
;     ...
;             for (int m = 0; m < 4; ++m) { bf16_t* rowp = O + (size_t)(row0 + ai * HALF + m * 16) * ldc + col0;
; #pragma unroll
;                 for (int bj = 0; bj < 2; ++bj) { f32x4 v0 = acc[ai][bj][m][0], v1 = acc[ai][bj][m][1];
;                     if (ACT == 1) {
; #pragma unroll
;                         for (int e = 0; e < 4; ++e) { float a = fmaxf(v0[e], 0.f), b = fmaxf(v1[e], 0.f); v0[e] = a * a; v1[e] = b * b; } }
;                     u32x4 w; w.x = cvt_pk_bf16(v0[0], v0[1]); w.y = cvt_pk_bf16(v0[2], v0[3]); w.z = cvt_pk_bf16(v1[0], v1[1]); w.w = cvt_pk_bf16(v1[2], v1[3]);
;                     *(u32x4*)(rowp + bj * HALF) = w; } }
	global_store_dwordx4 v[80:81], v[64:67], off offset:256
	v_max_f32_e32 v60, v60, v60
	v_max_f32_e32 v61, v61, v61
	v_pk_mul_f32 v[66:67], v[56:57], v[56:57]
	v_max_f32_e32 v57, v58, v58
	v_max_f32_e32 v60, 0, v60
	v_max_f32_e32 v61, 0, v61
	v_max_f32_e32 v56, v62, v62
	v_max_f32_e32 v58, 0, v57
	v_max_f32_e32 v57, v63, v63
	v_max_f32_e32 v59, v59, v59
	v_pk_mul_f32 v[60:61], v[60:61], v[60:61]
	v_max_f32_e32 v56, 0, v56
	v_max_f32_e32 v57, 0, v57
	v_max_f32_e32 v59, 0, v59
	v_pk_mul_f32 v[62:63], v[56:57], v[56:57]
	v_pk_mul_f32 v[68:69], v[58:59], v[58:59]
	v_cvt_pk_bf16_f32 v56, v60, v61
	v_add_co_u32_e32 v60, vcc, s60, v144
	v_max_f32_e32 v48, v48, v48
	v_max_f32_e32 v49, v49, v49
	v_cvt_pk_bf16_f32 v57, v62, v63
	v_cvt_pk_bf16_f32 v58, v66, v67
	v_cvt_pk_bf16_f32 v59, v68, v69
	v_addc_co_u32_e32 v61, vcc, 0, v145, vcc
	v_max_f32_e32 v48, 0, v48
	v_max_f32_e32 v49, 0, v49
	global_store_dwordx4 v[60:61], v[56:59], off
	v_max_f32_e32 v52, v52, v52
	v_max_f32_e32 v53, v53, v53
	v_pk_mul_f32 v[56:57], v[48:49], v[48:49]
	v_max_f32_e32 v49, v50, v50
	v_max_f32_e32 v48, v54, v54
	v_max_f32_e32 v50, 0, v49
	v_max_f32_e32 v49, v55, v55
	v_max_f32_e32 v51, v51, v51
	v_max_f32_e32 v52, 0, v52
	v_max_f32_e32 v53, 0, v53
	v_max_f32_e32 v48, 0, v48
	v_max_f32_e32 v49, 0, v49
	v_max_f32_e32 v51, 0, v51
	v_pk_mul_f32 v[52:53], v[52:53], v[52:53]
	v_pk_mul_f32 v[54:55], v[48:49], v[48:49]
	v_pk_mul_f32 v[58:59], v[50:51], v[50:51]
	v_max_f32_e32 v40, v40, v40
	v_max_f32_e32 v41, v41, v41
	v_lshl_add_u64 v[64:65], v[144:145], 0, s[14:15]
	v_cvt_pk_bf16_f32 v48, v52, v53
	v_cvt_pk_bf16_f32 v49, v54, v55
	v_cvt_pk_bf16_f32 v50, v56, v57
	v_cvt_pk_bf16_f32 v51, v58, v59
	v_max_f32_e32 v40, 0, v40
	v_max_f32_e32 v41, 0, v41
	global_store_dwordx4 v[64:65], v[48:51], off offset:256
	v_max_f32_e32 v44, v44, v44
	v_max_f32_e32 v45, v45, v45
	v_pk_mul_f32 v[50:51], v[40:41], v[40:41]
	v_max_f32_e32 v41, v42, v42
	v_max_f32_e32 v44, 0, v44
	v_max_f32_e32 v45, 0, v45
	v_max_f32_e32 v40, v46, v46
	v_max_f32_e32 v42, 0, v41
	v_max_f32_e32 v41, v47, v47
	v_max_f32_e32 v43, v43, v43
	v_pk_mul_f32 v[44:45], v[44:45], v[44:45]
	v_max_f32_e32 v40, 0, v40
	v_max_f32_e32 v41, 0, v41
	v_max_f32_e32 v43, 0, v43
	v_pk_mul_f32 v[46:47], v[40:41], v[40:41]
	v_pk_mul_f32 v[52:53], v[42:43], v[42:43]
	v_cvt_pk_bf16_f32 v40, v44, v45
	v_add_co_u32_e32 v44, vcc, s61, v144
	v_max_f32_e32 v32, v32, v32
	v_max_f32_e32 v33, v33, v33
	v_cvt_pk_bf16_f32 v41, v46, v47
	v_cvt_pk_bf16_f32 v42, v50, v51
	v_cvt_pk_bf16_f32 v43, v52, v53
	v_addc_co_u32_e32 v45, vcc, 0, v145, vcc
	v_max_f32_e32 v32, 0, v32
	v_max_f32_e32 v33, 0, v33
	global_store_dwordx4 v[44:45], v[40:43], off
	v_max_f32_e32 v36, v36, v36
	v_max_f32_e32 v37, v37, v37
	v_pk_mul_f32 v[40:41], v[32:33], v[32:33]
	v_max_f32_e32 v33, v34, v34
	v_max_f32_e32 v32, v38, v38
	v_max_f32_e32 v34, 0, v33
	v_max_f32_e32 v33, v39, v39
	v_max_f32_e32 v35, v35, v35
	v_max_f32_e32 v36, 0, v36
	v_max_f32_e32 v37, 0, v37
	v_max_f32_e32 v32, 0, v32
	v_max_f32_e32 v33, 0, v33
	v_max_f32_e32 v35, 0, v35
	v_pk_mul_f32 v[36:37], v[36:37], v[36:37]
	v_pk_mul_f32 v[38:39], v[32:33], v[32:33]
	v_pk_mul_f32 v[42:43], v[34:35], v[34:35]
	v_max_f32_e32 v24, v24, v24
	v_max_f32_e32 v25, v25, v25
	v_lshl_add_u64 v[48:49], v[144:145], 0, s[16:17]
	v_cvt_pk_bf16_f32 v32, v36, v37
	v_cvt_pk_bf16_f32 v33, v38, v39
	v_cvt_pk_bf16_f32 v34, v40, v41
	v_cvt_pk_bf16_f32 v35, v42, v43
	v_max_f32_e32 v24, 0, v24
	v_max_f32_e32 v25, 0, v25
	global_store_dwordx4 v[48:49], v[32:35], off offset:256
	v_max_f32_e32 v28, v28, v28
	v_max_f32_e32 v29, v29, v29
	v_pk_mul_f32 v[34:35], v[24:25], v[24:25]
	v_max_f32_e32 v25, v26, v26
	v_max_f32_e32 v28, 0, v28
	v_max_f32_e32 v29, 0, v29
	v_max_f32_e32 v24, v30, v30
	v_max_f32_e32 v26, 0, v25
	v_max_f32_e32 v25, v31, v31
	v_max_f32_e32 v27, v27, v27
	v_pk_mul_f32 v[28:29], v[28:29], v[28:29]
	v_max_f32_e32 v24, 0, v24
	v_max_f32_e32 v25, 0, v25
	v_max_f32_e32 v27, 0, v27
	v_pk_mul_f32 v[30:31], v[24:25], v[24:25]
	v_pk_mul_f32 v[36:37], v[26:27], v[26:27]
	v_cvt_pk_bf16_f32 v24, v28, v29
	v_add_co_u32_e32 v28, vcc, s62, v144
	v_max_f32_e32 v16, v16, v16
	v_max_f32_e32 v17, v17, v17
	v_cvt_pk_bf16_f32 v25, v30, v31
	v_cvt_pk_bf16_f32 v26, v34, v35
	v_cvt_pk_bf16_f32 v27, v36, v37
	v_addc_co_u32_e32 v29, vcc, 0, v145, vcc
	v_max_f32_e32 v16, 0, v16
	v_max_f32_e32 v17, 0, v17
	global_store_dwordx4 v[28:29], v[24:27], off
	v_max_f32_e32 v20, v20, v20
	v_max_f32_e32 v21, v21, v21
	v_pk_mul_f32 v[24:25], v[16:17], v[16:17]
	v_max_f32_e32 v17, v18, v18
	v_max_f32_e32 v16, v22, v22
	v_max_f32_e32 v18, 0, v17
	v_max_f32_e32 v17, v23, v23
	v_max_f32_e32 v19, v19, v19
	v_max_f32_e32 v20, 0, v20
	v_max_f32_e32 v21, 0, v21
	v_max_f32_e32 v16, 0, v16
	v_max_f32_e32 v17, 0, v17
	v_max_f32_e32 v19, 0, v19
	v_pk_mul_f32 v[20:21], v[20:21], v[20:21]
	v_pk_mul_f32 v[22:23], v[16:17], v[16:17]
	v_pk_mul_f32 v[26:27], v[18:19], v[18:19]
	v_max_f32_e32 v8, v8, v8
	v_max_f32_e32 v9, v9, v9
	v_lshl_add_u64 v[32:33], v[144:145], 0, s[18:19]
	v_cvt_pk_bf16_f32 v16, v20, v21
	v_cvt_pk_bf16_f32 v17, v22, v23
	v_cvt_pk_bf16_f32 v18, v24, v25
	v_cvt_pk_bf16_f32 v19, v26, v27
	v_max_f32_e32 v8, 0, v8
	v_max_f32_e32 v9, 0, v9
	global_store_dwordx4 v[32:33], v[16:19], off offset:256
	v_max_f32_e32 v12, v12, v12
	v_max_f32_e32 v13, v13, v13
	v_pk_mul_f32 v[18:19], v[8:9], v[8:9]
	v_max_f32_e32 v9, v10, v10
	v_max_f32_e32 v12, 0, v12
	v_max_f32_e32 v13, 0, v13
	v_max_f32_e32 v8, v14, v14
	v_max_f32_e32 v10, 0, v9
	v_max_f32_e32 v9, v15, v15
	v_max_f32_e32 v11, v11, v11
	v_pk_mul_f32 v[12:13], v[12:13], v[12:13]
	v_max_f32_e32 v8, 0, v8
	v_max_f32_e32 v9, 0, v9
	v_max_f32_e32 v11, 0, v11
	v_pk_mul_f32 v[14:15], v[8:9], v[8:9]
	v_pk_mul_f32 v[20:21], v[10:11], v[10:11]
	v_cvt_pk_bf16_f32 v8, v12, v13
	v_add_co_u32_e32 v12, vcc, s63, v144
	v_max_f32_e32 v0, v0, v0
	v_max_f32_e32 v1, v1, v1
	v_cvt_pk_bf16_f32 v9, v14, v15
	v_cvt_pk_bf16_f32 v10, v18, v19
	v_cvt_pk_bf16_f32 v11, v20, v21
	v_addc_co_u32_e32 v13, vcc, 0, v145, vcc
	v_max_f32_e32 v0, 0, v0
	v_max_f32_e32 v1, 0, v1
	global_store_dwordx4 v[12:13], v[8:11], off
	v_max_f32_e32 v4, v4, v4
	v_max_f32_e32 v5, v5, v5
	v_pk_mul_f32 v[8:9], v[0:1], v[0:1]
	v_max_f32_e32 v1, v2, v2
	v_max_f32_e32 v0, v6, v6
	v_max_f32_e32 v2, 0, v1
	v_max_f32_e32 v1, v7, v7
	v_max_f32_e32 v3, v3, v3
	v_max_f32_e32 v4, 0, v4
	v_max_f32_e32 v5, 0, v5
	v_max_f32_e32 v0, 0, v0
	v_max_f32_e32 v1, 0, v1
	v_max_f32_e32 v3, 0, v3
	v_pk_mul_f32 v[4:5], v[4:5], v[4:5]
	v_pk_mul_f32 v[6:7], v[0:1], v[0:1]
	v_pk_mul_f32 v[10:11], v[2:3], v[2:3]
	v_lshl_add_u64 v[16:17], v[144:145], 0, s[20:21]
	v_cvt_pk_bf16_f32 v0, v4, v5
	v_cvt_pk_bf16_f32 v1, v6, v7
	v_cvt_pk_bf16_f32 v2, v8, v9
	v_cvt_pk_bf16_f32 v3, v10, v11
	s_andn2_b64 vcc, exec, s[0:1]
	s_mov_b64 s[0:1], -1
	global_store_dwordx4 v[16:17], v[0:3], off offset:256
	s_mov_b32 s100, 1
	s_cbranch_vccnz .LBB0_888
	s_andn2_b64 vcc, exec, s[6:7]
	s_cbranch_vccnz .LBB0_887
	s_barrier
	s_branch .LBB0_887

; __device__ __forceinline__ void run_gemm_store(const Params& p, LAS unsigned char* ldsl, const int ph) {
;     ...
;     pg8::Gemm g{D}; pg8::SegOrder S; S.init(D, gridDim.x, blockIdx.x);
;     pg8::EpiBf16 E{(bf16_t*)(ws + WS_P), NIN, (bf16_t*)(ws + WS_VT), MALL, 0};
;     if (ph == 2) { S.add(A, ws + WS_WIN, MALL / 256, NIN / 256, 1, D / 64, 0); S.add(ws + WS_WV0, A, 1024 / 256, MALL / 256, 1, D / 64, 1); }
;     else if (ph == 10) { E.ldc0 = NQK; S.add(A, ws + WS_WQKV, MALL / 256, NQK / 256, 1, D / 64, 0); S.add((const bf16_t*)(ws + WS_WQKV) + (size_t)NQK * D, A, D / 256, MALL / 256, 1, D / 64, 1); }
;     else { E.O0 = (bf16_t*)(ws + WS_H); E.ldc0 = DFF; E.ACT = 1; S.add(A, (const bf16_t*)(ws + WS_WUP) + (size_t)l1 * D * DFF, Mrows / 256, DFF / 256, 1, D / 64, 0); }
;     pg8::gemm_phase<pg8::EpiBf16, pg8::SegOrder, true, true>(ldsl, g, S, E);
.LBB0_1121:
	s_cmp_lt_i32 s80, 11
	s_cselect_b64 s[2:3], -1, 0
	s_and_b64 s[0:1], s[2:3], s[0:1]
	s_andn2_b64 vcc, exec, s[0:1]
	s_cbranch_vccnz .LBB0_1142
	s_mov_b32 s100, 0
	s_ashr_i32 s30, s92, 31
	s_cmpk_lt_i32 s92, 0x440
	s_cselect_b64 s[8:9], -1, 0
	v_readfirstlane_b32 s10, v162
	s_and_b64 vcc, exec, s[8:9]
	s_cbranch_vccnz .LBB0_1124
	s_add_u32 s2, s92, 0xfffffbc0
	s_addc_u32 s3, s30, -1
	v_mov_b64_e32 v[0:1], 0x220
	v_cmp_lt_u64_e64 s[8:9], s[2:3], v[0:1]
	s_mov_b32 s38, 1
	s_movk_i32 s14, 0x44
	s_mov_b32 s13, 8
	s_mov_b64 s[6:7], 0xc600000
	s_mov_b64 s[4:5], 0xae00000
	s_andn2_b64 vcc, exec, s[8:9]
	s_cbranch_vccz .LBB0_1125
	s_branch .LBB0_1142

; #define PG8_STAGE(bufoff, gbase, voff) do { _Pragma("unroll") for (int _i = 0; _i < 2; ++_i) \
;         __builtin_amdgcn_global_load_lds((const unsigned*)((const char*)(gbase) + (voff)[_i]), (LAS unsigned*)(lds + (bufoff) + ldsw + _i * 8192), 16, 0, 0); } while (0)
; #define PG8_LDA(dst, b, h) do { _Pragma("unroll") for (int m = 0; m < 4; ++m) _Pragma("unroll") for (int k = 0; k < 2; ++k) dst[m][k] = *(const LAS bf16x8*)(lds + PG8_SA(b, h) + aoff + m * 2048 + k * 1024); } while (0)
; #define PG8_LDB(dst, b, h) do { _Pragma("unroll") for (int n = 0; n < 2; ++n) _Pragma("unroll") for (int k = 0; k < 2; ++k) dst[n][k] = *(const LAS bf16x8*)(lds + PG8_SB(b, h) + boff + n * 2048 + k * 1024); } while (0)
; #define PG8_MMA(ai, bj, At, Bt) do { __builtin_amdgcn_s_setprio(1); _Pragma("unroll") for (int m = 0; m < 4; ++m) _Pragma("unroll") for (int n = 0; n < 2; ++n) _Pragma("unroll") for (int k = 0; k < 2; ++k) \
;         acc[ai][bj][m][n] = __builtin_amdgcn_mfma_f32_16x16x32_bf16(Bt[n][k], At[m][k], acc[ai][bj][m][n], 0, 0, 0); __builtin_amdgcn_s_setprio(0); } while (0)
; #define PG8_WAIT_V(n) asm volatile("s_waitcnt vmcnt(" #n ")" ::: "memory")
; #define PG8_WAIT_L(n) asm volatile("s_waitcnt lgkmcnt(" #n ")" ::: "memory")
; #define PG8_BAR __builtin_amdgcn_s_barrier()
; #define PG8_SCHED __builtin_amdgcn_sched_barrier(0)
; template <class Epi, class Sched, bool ALIGN_EPI = false, bool SP2 = false>
; __device__ __forceinline__ void gemm_phase(LAS unsigned char* lds, const Gemm g, const Sched& S, const Epi& E) {
;     ...
;             if constexpr (SP2) {
;             PG8_LDB(B0, 0, 0); PG8_LDB(B1, 0, 1); PG8_SCHED; PG8_LDA(At, 0, 0); PG8_STAGE(PG8_SA(1, 1), a1 + hstep, voffA);
;             PG8_WAIT_V(8); PG8_WAIT_L(0); PG8_BAR; PG8_MMA(0, 0, At, B0); PG8_MMA(0, 1, At, B1); PG8_BAR; PG8_SCHED;
.LBB0_1135:
	ds_read_b128 v[150:153], v147
	ds_read_b128 v[154:157], v147 offset:1024
	ds_read_b128 v[164:167], v147 offset:2048
	ds_read_b128 v[170:173], v147 offset:3072
	ds_read_b128 v[174:177], v148
	ds_read_b128 v[178:181], v148 offset:1024
	ds_read_b128 v[182:185], v148 offset:2048
	ds_read_b128 v[186:189], v148 offset:3072
	s_add_u32 s22, s20, 0xfff80080
	s_addc_u32 s23, s21, -1
	s_cmp_eq_u32 s48, 28
	s_cselect_b32 s25, s13, s23
	s_cselect_b32 s24, s26, s22
	s_cselect_b32 s23, s27, s47
	s_cselect_b32 s22, s28, s29
	v_lshl_add_u64 v[158:159], s[20:21], 0, v[136:137]
	s_add_i32 m0, s33, 0xc000
	ds_read_b128 v[190:193], v149
	ds_read_b128 v[194:197], v149 offset:1024
	ds_read_b128 v[198:201], v149 offset:2048
	ds_read_b128 v[202:205], v149 offset:3072
	ds_read_b128 v[206:209], v149 offset:4096
	ds_read_b128 v[210:213], v149 offset:5120
	ds_read_b128 v[214:217], v149 offset:6144
	ds_read_b128 v[218:221], v149 offset:7168
	global_load_lds_dwordx4 v[158:159], off
	v_lshl_add_u64 v[158:159], s[20:21], 0, v[138:139]
	s_add_i32 m0, s33, 0xe000
	s_nop 0
	global_load_lds_dwordx4 v[158:159], off
	s_cmp_eq_u32 s100, 1
	s_cbranch_scc1 .Ltw_tilewait_26611_0a
	s_waitcnt vmcnt(8)
	s_branch .Ltw_tilewait_26611_0b

; #define PG8_STAGE(bufoff, gbase, voff) do { _Pragma("unroll") for (int _i = 0; _i < 2; ++_i) \
;         __builtin_amdgcn_global_load_lds((const unsigned*)((const char*)(gbase) + (voff)[_i]), (LAS unsigned*)(lds + (bufoff) + ldsw + _i * 8192), 16, 0, 0); } while (0)
; #define PG8_LDA(dst, b, h) do { _Pragma("unroll") for (int m = 0; m < 4; ++m) _Pragma("unroll") for (int k = 0; k < 2; ++k) dst[m][k] = *(const LAS bf16x8*)(lds + PG8_SA(b, h) + aoff + m * 2048 + k * 1024); } while (0)
; #define PG8_MMA(ai, bj, At, Bt) do { __builtin_amdgcn_s_setprio(1); _Pragma("unroll") for (int m = 0; m < 4; ++m) _Pragma("unroll") for (int n = 0; n < 2; ++n) _Pragma("unroll") for (int k = 0; k < 2; ++k) \
;         acc[ai][bj][m][n] = __builtin_amdgcn_mfma_f32_16x16x32_bf16(Bt[n][k], At[m][k], acc[ai][bj][m][n], 0, 0, 0); __builtin_amdgcn_s_setprio(0); } while (0)
; #define PG8_WAIT_V(n) asm volatile("s_waitcnt vmcnt(" #n ")" ::: "memory")
; #define PG8_WAIT_L(n) asm volatile("s_waitcnt lgkmcnt(" #n ")" ::: "memory")
; #define PG8_BAR __builtin_amdgcn_s_barrier()
; #define PG8_SCHED __builtin_amdgcn_sched_barrier(0)
; template <class Epi, class Sched, bool ALIGN_EPI = false, bool SP2 = false>
; __device__ __forceinline__ void gemm_phase(LAS unsigned char* lds, const Gemm g, const Sched& S, const Epi& E) {
;     ...
;             PG8_WAIT_V(8); PG8_WAIT_L(0); PG8_BAR; PG8_MMA(0, 0, At, B0); PG8_MMA(0, 1, At, B1); PG8_BAR; PG8_SCHED;
;             PG8_LDA(At, 0, 1); PG8_STAGE(PG8_SB(0, 0), b2, voffB); PG8_STAGE(PG8_SB(0, 1), b2 + hstep, voffB); PG8_STAGE(PG8_SA(0, 0), a2, voffA);
;             PG8_WAIT_V(8); PG8_WAIT_L(0); PG8_BAR; PG8_MMA(1, 0, At, B0); PG8_MMA(1, 1, At, B1); PG8_BAR; PG8_SCHED;
.Ltw_tilewait_26611_0b:
	s_waitcnt lgkmcnt(0)
	s_barrier
	s_setprio 1
	s_waitcnt lgkmcnt(0)
	v_mfma_f32_16x16x32_bf16 v[124:127], v[150:153], v[190:193], v[124:127]
	v_mfma_f32_16x16x32_bf16 v[120:123], v[164:167], v[190:193], v[120:123]
	v_mfma_f32_16x16x32_bf16 v[116:119], v[150:153], v[198:201], v[116:119]
	v_mfma_f32_16x16x32_bf16 v[112:115], v[164:167], v[198:201], v[112:115]
	v_mfma_f32_16x16x32_bf16 v[100:103], v[150:153], v[206:209], v[100:103]
	v_mfma_f32_16x16x32_bf16 v[96:99], v[164:167], v[206:209], v[96:99]
	v_mfma_f32_16x16x32_bf16 v[84:87], v[150:153], v[214:217], v[84:87]
	v_mfma_f32_16x16x32_bf16 v[80:83], v[164:167], v[214:217], v[80:83]
	v_mfma_f32_16x16x32_bf16 v[124:127], v[154:157], v[194:197], v[124:127]
	v_mfma_f32_16x16x32_bf16 v[120:123], v[170:173], v[194:197], v[120:123]
	v_mfma_f32_16x16x32_bf16 v[116:119], v[154:157], v[202:205], v[116:119]
	v_mfma_f32_16x16x32_bf16 v[112:115], v[170:173], v[202:205], v[112:115]
	v_mfma_f32_16x16x32_bf16 v[100:103], v[154:157], v[210:213], v[100:103]
	v_mfma_f32_16x16x32_bf16 v[96:99], v[170:173], v[210:213], v[96:99]
	v_mfma_f32_16x16x32_bf16 v[84:87], v[154:157], v[218:221], v[84:87]
	v_mfma_f32_16x16x32_bf16 v[80:83], v[170:173], v[218:221], v[80:83]
	s_setprio 0
	s_setprio 1
	v_mfma_f32_16x16x32_bf16 v[108:111], v[174:177], v[190:193], v[108:111]
	v_mfma_f32_16x16x32_bf16 v[104:107], v[182:185], v[190:193], v[104:107]
	v_mfma_f32_16x16x32_bf16 v[92:95], v[174:177], v[198:201], v[92:95]
	v_mfma_f32_16x16x32_bf16 v[88:91], v[182:185], v[198:201], v[88:91]
	v_mfma_f32_16x16x32_bf16 v[76:79], v[174:177], v[206:209], v[76:79]
	v_mfma_f32_16x16x32_bf16 v[72:75], v[182:185], v[206:209], v[72:75]
	v_mfma_f32_16x16x32_bf16 v[68:71], v[174:177], v[214:217], v[68:71]
	v_mfma_f32_16x16x32_bf16 v[64:67], v[182:185], v[214:217], v[64:67]
	v_mfma_f32_16x16x32_bf16 v[108:111], v[178:181], v[194:197], v[108:111]
	v_mfma_f32_16x16x32_bf16 v[104:107], v[186:189], v[194:197], v[104:107]
	v_mfma_f32_16x16x32_bf16 v[92:95], v[178:181], v[202:205], v[92:95]
	v_mfma_f32_16x16x32_bf16 v[88:91], v[186:189], v[202:205], v[88:91]
	v_mfma_f32_16x16x32_bf16 v[76:79], v[178:181], v[210:213], v[76:79]
	v_mfma_f32_16x16x32_bf16 v[72:75], v[186:189], v[210:213], v[72:75]
	v_mfma_f32_16x16x32_bf16 v[68:71], v[178:181], v[218:221], v[68:71]
	v_mfma_f32_16x16x32_bf16 v[64:67], v[186:189], v[218:221], v[64:67]
	s_setprio 0
	s_barrier
	s_add_i32 s49, s43, s31
	v_lshl_add_u64 v[158:159], s[22:23], 0, v[130:131]
	s_mov_b32 m0, s49
	ds_read_b128 v[190:193], v149 offset:16384
	ds_read_b128 v[194:197], v149 offset:17408
	ds_read_b128 v[198:201], v149 offset:18432
	ds_read_b128 v[202:205], v149 offset:19456
	ds_read_b128 v[206:209], v149 offset:20480
	ds_read_b128 v[210:213], v149 offset:21504
	ds_read_b128 v[214:217], v149 offset:22528
	ds_read_b128 v[218:221], v149 offset:23552
	global_load_lds_dwordx4 v[158:159], off
	s_add_i32 m0, s49, 0x2000
	s_add_u32 s50, s22, 0x80000
	v_lshl_add_u64 v[222:223], s[22:23], 0, v[134:135]
	s_addc_u32 s51, s23, 0
	s_add_i32 s49, s44, s31
	global_load_lds_dwordx4 v[222:223], off
	v_lshl_add_u64 v[224:225], s[50:51], 0, v[130:131]
	s_mov_b32 m0, s49
	v_lshl_add_u64 v[226:227], s[24:25], 0, v[132:133]
	global_load_lds_dwordx4 v[224:225], off
	v_lshl_add_u64 v[224:225], s[50:51], 0, v[134:135]
	s_add_i32 m0, s49, 0x2000
	s_nop 0
	global_load_lds_dwordx4 v[224:225], off
	v_lshl_add_u64 v[224:225], s[24:25], 0, v[128:129]
	s_mov_b32 m0, s33
	s_nop 0
	global_load_lds_dwordx4 v[224:225], off
	s_mov_b32 m0, s34
	s_nop 0
	global_load_lds_dwordx4 v[226:227], off
	s_cmp_eq_u32 s100, 1
	s_cbranch_scc1 .Ltw_tilewait_26611_1a
	s_waitcnt vmcnt(8)
	s_branch .Ltw_tilewait_26611_1b

; #define PG8_STAGE(bufoff, gbase, voff) do { _Pragma("unroll") for (int _i = 0; _i < 2; ++_i) \
;         __builtin_amdgcn_global_load_lds((const unsigned*)((const char*)(gbase) + (voff)[_i]), (LAS unsigned*)(lds + (bufoff) + ldsw + _i * 8192), 16, 0, 0); } while (0)
; #define PG8_LDA(dst, b, h) do { _Pragma("unroll") for (int m = 0; m < 4; ++m) _Pragma("unroll") for (int k = 0; k < 2; ++k) dst[m][k] = *(const LAS bf16x8*)(lds + PG8_SA(b, h) + aoff + m * 2048 + k * 1024); } while (0)
; #define PG8_LDB(dst, b, h) do { _Pragma("unroll") for (int n = 0; n < 2; ++n) _Pragma("unroll") for (int k = 0; k < 2; ++k) dst[n][k] = *(const LAS bf16x8*)(lds + PG8_SB(b, h) + boff + n * 2048 + k * 1024); } while (0)
; #define PG8_MMA(ai, bj, At, Bt) do { __builtin_amdgcn_s_setprio(1); _Pragma("unroll") for (int m = 0; m < 4; ++m) _Pragma("unroll") for (int n = 0; n < 2; ++n) _Pragma("unroll") for (int k = 0; k < 2; ++k) \
;         acc[ai][bj][m][n] = __builtin_amdgcn_mfma_f32_16x16x32_bf16(Bt[n][k], At[m][k], acc[ai][bj][m][n], 0, 0, 0); __builtin_amdgcn_s_setprio(0); } while (0)
; #define PG8_WAIT_V(n) asm volatile("s_waitcnt vmcnt(" #n ")" ::: "memory")
; #define PG8_WAIT_L(n) asm volatile("s_waitcnt lgkmcnt(" #n ")" ::: "memory")
; #define PG8_BAR __builtin_amdgcn_s_barrier()
; #define PG8_SCHED __builtin_amdgcn_sched_barrier(0)
; template <class Epi, class Sched, bool ALIGN_EPI = false, bool SP2 = false>
; __device__ __forceinline__ void gemm_phase(LAS unsigned char* lds, const Gemm g, const Sched& S, const Epi& E) {
;     ...
;             PG8_WAIT_V(8); PG8_WAIT_L(0); PG8_BAR; PG8_MMA(1, 0, At, B0); PG8_MMA(1, 1, At, B1); PG8_BAR; PG8_SCHED;
;             PG8_LDB(B0, 1, 0); PG8_LDB(B1, 1, 1); PG8_SCHED; PG8_LDA(At, 1, 0); PG8_STAGE(PG8_SA(0, 1), a2 + hstep, voffA);
;             PG8_WAIT_V(8); PG8_WAIT_L(0); PG8_BAR; PG8_MMA(0, 0, At, B0); PG8_MMA(0, 1, At, B1); PG8_BAR; PG8_SCHED;
.Ltw_tilewait_26611_1b:
	s_waitcnt lgkmcnt(0)
	s_barrier
	s_setprio 1
	s_waitcnt lgkmcnt(0)
	v_mfma_f32_16x16x32_bf16 v[60:63], v[150:153], v[190:193], v[60:63]
	v_mfma_f32_16x16x32_bf16 v[56:59], v[164:167], v[190:193], v[56:59]
	v_mfma_f32_16x16x32_bf16 v[52:55], v[150:153], v[198:201], v[52:55]
	v_mfma_f32_16x16x32_bf16 v[48:51], v[164:167], v[198:201], v[48:51]
	v_mfma_f32_16x16x32_bf16 v[36:39], v[150:153], v[206:209], v[36:39]
	v_mfma_f32_16x16x32_bf16 v[32:35], v[164:167], v[206:209], v[32:35]
	v_mfma_f32_16x16x32_bf16 v[20:23], v[150:153], v[214:217], v[20:23]
	v_mfma_f32_16x16x32_bf16 v[16:19], v[164:167], v[214:217], v[16:19]
	v_mfma_f32_16x16x32_bf16 v[60:63], v[154:157], v[194:197], v[60:63]
	v_mfma_f32_16x16x32_bf16 v[56:59], v[170:173], v[194:197], v[56:59]
	v_mfma_f32_16x16x32_bf16 v[52:55], v[154:157], v[202:205], v[52:55]
	v_mfma_f32_16x16x32_bf16 v[48:51], v[170:173], v[202:205], v[48:51]
	v_mfma_f32_16x16x32_bf16 v[36:39], v[154:157], v[210:213], v[36:39]
	v_mfma_f32_16x16x32_bf16 v[32:35], v[170:173], v[210:213], v[32:35]
	v_mfma_f32_16x16x32_bf16 v[20:23], v[154:157], v[218:221], v[20:23]
	v_mfma_f32_16x16x32_bf16 v[16:19], v[170:173], v[218:221], v[16:19]
	s_setprio 0
	s_setprio 1
	v_mfma_f32_16x16x32_bf16 v[44:47], v[174:177], v[190:193], v[44:47]
	v_mfma_f32_16x16x32_bf16 v[40:43], v[182:185], v[190:193], v[40:43]
	v_mfma_f32_16x16x32_bf16 v[28:31], v[174:177], v[198:201], v[28:31]
	v_mfma_f32_16x16x32_bf16 v[24:27], v[182:185], v[198:201], v[24:27]
	v_mfma_f32_16x16x32_bf16 v[12:15], v[174:177], v[206:209], v[12:15]
	v_mfma_f32_16x16x32_bf16 v[8:11], v[182:185], v[206:209], v[8:11]
	v_mfma_f32_16x16x32_bf16 v[4:7], v[174:177], v[214:217], v[4:7]
	v_mfma_f32_16x16x32_bf16 v[0:3], v[182:185], v[214:217], v[0:3]
	v_mfma_f32_16x16x32_bf16 v[44:47], v[178:181], v[194:197], v[44:47]
	v_mfma_f32_16x16x32_bf16 v[40:43], v[186:189], v[194:197], v[40:43]
	v_mfma_f32_16x16x32_bf16 v[28:31], v[178:181], v[202:205], v[28:31]
	v_mfma_f32_16x16x32_bf16 v[24:27], v[186:189], v[202:205], v[24:27]
	v_mfma_f32_16x16x32_bf16 v[12:15], v[178:181], v[210:213], v[12:15]
	v_mfma_f32_16x16x32_bf16 v[8:11], v[186:189], v[210:213], v[8:11]
	v_mfma_f32_16x16x32_bf16 v[4:7], v[178:181], v[218:221], v[4:7]
	v_mfma_f32_16x16x32_bf16 v[0:3], v[186:189], v[218:221], v[0:3]
	s_setprio 0
	s_barrier
	s_add_i32 s49, 0, 0x18000
	v_add_u32_e32 v163, s49, v145
	s_add_i32 s50, 0, 0x1c000
	ds_read_b128 v[150:153], v163
	ds_read_b128 v[154:157], v163 offset:1024
	ds_read_b128 v[164:167], v163 offset:2048
	ds_read_b128 v[170:173], v163 offset:3072
	v_add_u32_e32 v163, s50, v145
	ds_read_b128 v[174:177], v163
	ds_read_b128 v[178:181], v163 offset:1024
	ds_read_b128 v[182:185], v163 offset:2048
	ds_read_b128 v[186:189], v163 offset:3072
	s_add_u32 s24, s24, 0x80000
	s_addc_u32 s25, s25, 0
	s_mov_b32 m0, s35
	v_lshl_add_u64 v[228:229], s[24:25], 0, v[128:129]
	ds_read_b128 v[190:193], v149 offset:32768
	ds_read_b128 v[194:197], v149 offset:33792
	ds_read_b128 v[198:201], v149 offset:34816
	ds_read_b128 v[202:205], v149 offset:35840
	ds_read_b128 v[206:209], v149 offset:36864
	ds_read_b128 v[210:213], v149 offset:37888
	ds_read_b128 v[214:217], v149 offset:38912
	ds_read_b128 v[218:221], v149 offset:39936
	global_load_lds_dwordx4 v[228:229], off
	v_lshl_add_u64 v[228:229], s[24:25], 0, v[132:133]
	s_mov_b32 m0, s36
	s_nop 0
	global_load_lds_dwordx4 v[228:229], off
	s_waitcnt vmcnt(8)
	s_waitcnt lgkmcnt(0)
	s_barrier
	s_setprio 1
	s_waitcnt lgkmcnt(0)
	v_mfma_f32_16x16x32_bf16 v[124:127], v[150:153], v[190:193], v[124:127]
	v_mfma_f32_16x16x32_bf16 v[120:123], v[164:167], v[190:193], v[120:123]
	v_mfma_f32_16x16x32_bf16 v[116:119], v[150:153], v[198:201], v[116:119]
	v_mfma_f32_16x16x32_bf16 v[112:115], v[164:167], v[198:201], v[112:115]
	v_mfma_f32_16x16x32_bf16 v[100:103], v[150:153], v[206:209], v[100:103]
	v_mfma_f32_16x16x32_bf16 v[96:99], v[164:167], v[206:209], v[96:99]
	v_mfma_f32_16x16x32_bf16 v[84:87], v[150:153], v[214:217], v[84:87]
	v_mfma_f32_16x16x32_bf16 v[80:83], v[164:167], v[214:217], v[80:83]
	v_mfma_f32_16x16x32_bf16 v[124:127], v[154:157], v[194:197], v[124:127]
	v_mfma_f32_16x16x32_bf16 v[120:123], v[170:173], v[194:197], v[120:123]
	v_mfma_f32_16x16x32_bf16 v[116:119], v[154:157], v[202:205], v[116:119]
	v_mfma_f32_16x16x32_bf16 v[112:115], v[170:173], v[202:205], v[112:115]
	v_mfma_f32_16x16x32_bf16 v[100:103], v[154:157], v[210:213], v[100:103]
	v_mfma_f32_16x16x32_bf16 v[96:99], v[170:173], v[210:213], v[96:99]
	v_mfma_f32_16x16x32_bf16 v[84:87], v[154:157], v[218:221], v[84:87]
	v_mfma_f32_16x16x32_bf16 v[80:83], v[170:173], v[218:221], v[80:83]
	s_setprio 0
	s_setprio 1
	v_mfma_f32_16x16x32_bf16 v[108:111], v[174:177], v[190:193], v[108:111]
	v_mfma_f32_16x16x32_bf16 v[104:107], v[182:185], v[190:193], v[104:107]
	v_mfma_f32_16x16x32_bf16 v[92:95], v[174:177], v[198:201], v[92:95]
	v_mfma_f32_16x16x32_bf16 v[88:91], v[182:185], v[198:201], v[88:91]
	v_mfma_f32_16x16x32_bf16 v[76:79], v[174:177], v[206:209], v[76:79]
	v_mfma_f32_16x16x32_bf16 v[72:75], v[182:185], v[206:209], v[72:75]
	v_mfma_f32_16x16x32_bf16 v[68:71], v[174:177], v[214:217], v[68:71]
	v_mfma_f32_16x16x32_bf16 v[64:67], v[182:185], v[214:217], v[64:67]
	v_mfma_f32_16x16x32_bf16 v[108:111], v[178:181], v[194:197], v[108:111]
	v_mfma_f32_16x16x32_bf16 v[104:107], v[186:189], v[194:197], v[104:107]
	v_mfma_f32_16x16x32_bf16 v[92:95], v[178:181], v[202:205], v[92:95]
	v_mfma_f32_16x16x32_bf16 v[88:91], v[186:189], v[202:205], v[88:91]
	v_mfma_f32_16x16x32_bf16 v[76:79], v[178:181], v[210:213], v[76:79]
	v_mfma_f32_16x16x32_bf16 v[72:75], v[186:189], v[210:213], v[72:75]
	v_mfma_f32_16x16x32_bf16 v[68:71], v[178:181], v[218:221], v[68:71]
	v_mfma_f32_16x16x32_bf16 v[64:67], v[186:189], v[218:221], v[64:67]
	s_setprio 0
	s_barrier
; #define PG8_STAGE(bufoff, gbase, voff) do { _Pragma("unroll") for (int _i = 0; _i < 2; ++_i) \
;         __builtin_amdgcn_global_load_lds((const unsigned*)((const char*)(gbase) + (voff)[_i]), (LAS unsigned*)(lds + (bufoff) + ldsw + _i * 8192), 16, 0, 0); } while (0)
; #define PG8_LDA(dst, b, h) do { _Pragma("unroll") for (int m = 0; m < 4; ++m) _Pragma("unroll") for (int k = 0; k < 2; ++k) dst[m][k] = *(const LAS bf16x8*)(lds + PG8_SA(b, h) + aoff + m * 2048 + k * 1024); } while (0)
; #define PG8_MMA(ai, bj, At, Bt) do { __builtin_amdgcn_s_setprio(1); _Pragma("unroll") for (int m = 0; m < 4; ++m) _Pragma("unroll") for (int n = 0; n < 2; ++n) _Pragma("unroll") for (int k = 0; k < 2; ++k) \
;         acc[ai][bj][m][n] = __builtin_amdgcn_mfma_f32_16x16x32_bf16(Bt[n][k], At[m][k], acc[ai][bj][m][n], 0, 0, 0); __builtin_amdgcn_s_setprio(0); } while (0)
; #define PG8_WAIT_V(n) asm volatile("s_waitcnt vmcnt(" #n ")" ::: "memory")
; #define PG8_WAIT_L(n) asm volatile("s_waitcnt lgkmcnt(" #n ")" ::: "memory")
; #define PG8_BAR __builtin_amdgcn_s_barrier()
; #define PG8_SCHED __builtin_amdgcn_sched_barrier(0)
; template <class Epi, class Sched, bool ALIGN_EPI = false, bool SP2 = false>
; __device__ __forceinline__ void gemm_phase(LAS unsigned char* lds, const Gemm g, const Sched& S, const Epi& E) {
;     ...
;         for (int t = 0; t < nt; t += 2) {
;     ...
;             PG8_LDA(At, 1, 1); PG8_STAGE(PG8_SB(1, 0), b3, voffB); PG8_STAGE(PG8_SB(1, 1), b3 + hstep, voffB); PG8_STAGE(PG8_SA(1, 0), a3, voffA);
;             PG8_WAIT_V(8); PG8_WAIT_L(0); PG8_BAR; PG8_MMA(1, 0, At, B0); PG8_MMA(1, 1, At, B1); PG8_BAR; PG8_SCHED;
	s_add_i32 s24, s49, s31
	v_lshl_add_u64 v[158:159], v[158:159], 0, s[4:5]
	s_mov_b32 m0, s24
	ds_read_b128 v[190:193], v149 offset:49152
	ds_read_b128 v[194:197], v149 offset:50176
	ds_read_b128 v[198:201], v149 offset:51200
	ds_read_b128 v[202:205], v149 offset:52224
	ds_read_b128 v[206:209], v149 offset:53248
	ds_read_b128 v[210:213], v149 offset:54272
	ds_read_b128 v[214:217], v149 offset:55296
	ds_read_b128 v[218:221], v149 offset:56320
	global_load_lds_dwordx4 v[158:159], off
	s_add_i32 m0, s24, 0x2000
	s_add_u32 s22, s22, 0x80080
	v_lshl_add_u64 v[158:159], v[222:223], 0, s[4:5]
	s_addc_u32 s23, s23, 0
	s_add_i32 s24, s50, s31
	global_load_lds_dwordx4 v[158:159], off
	v_lshl_add_u64 v[158:159], s[22:23], 0, v[130:131]
	s_mov_b32 m0, s24
	s_nop 0
	global_load_lds_dwordx4 v[158:159], off
	v_lshl_add_u64 v[158:159], s[22:23], 0, v[134:135]
	s_add_i32 m0, s24, 0x2000
	s_nop 0
	global_load_lds_dwordx4 v[158:159], off
	v_lshl_add_u64 v[158:159], v[224:225], 0, s[4:5]
	s_mov_b32 m0, s40
	s_nop 0
	global_load_lds_dwordx4 v[158:159], off
	v_lshl_add_u64 v[158:159], v[226:227], 0, s[4:5]
	s_mov_b32 m0, s41
	s_nop 0
	global_load_lds_dwordx4 v[158:159], off
	s_waitcnt vmcnt(8)
	s_waitcnt lgkmcnt(0)
	s_barrier
	s_setprio 1
	s_waitcnt lgkmcnt(0)
	v_mfma_f32_16x16x32_bf16 v[60:63], v[150:153], v[190:193], v[60:63]
	v_mfma_f32_16x16x32_bf16 v[56:59], v[164:167], v[190:193], v[56:59]
	v_mfma_f32_16x16x32_bf16 v[52:55], v[150:153], v[198:201], v[52:55]
	v_mfma_f32_16x16x32_bf16 v[48:51], v[164:167], v[198:201], v[48:51]
	v_mfma_f32_16x16x32_bf16 v[36:39], v[150:153], v[206:209], v[36:39]
	v_mfma_f32_16x16x32_bf16 v[32:35], v[164:167], v[206:209], v[32:35]
	v_mfma_f32_16x16x32_bf16 v[20:23], v[150:153], v[214:217], v[20:23]
	v_mfma_f32_16x16x32_bf16 v[16:19], v[164:167], v[214:217], v[16:19]
	v_mfma_f32_16x16x32_bf16 v[60:63], v[154:157], v[194:197], v[60:63]
	v_mfma_f32_16x16x32_bf16 v[56:59], v[170:173], v[194:197], v[56:59]
	v_mfma_f32_16x16x32_bf16 v[52:55], v[154:157], v[202:205], v[52:55]
	v_mfma_f32_16x16x32_bf16 v[48:51], v[170:173], v[202:205], v[48:51]
	v_mfma_f32_16x16x32_bf16 v[36:39], v[154:157], v[210:213], v[36:39]
	v_mfma_f32_16x16x32_bf16 v[32:35], v[170:173], v[210:213], v[32:35]
	v_mfma_f32_16x16x32_bf16 v[20:23], v[154:157], v[218:221], v[20:23]
	v_mfma_f32_16x16x32_bf16 v[16:19], v[170:173], v[218:221], v[16:19]
	s_setprio 0
	s_setprio 1
	v_mfma_f32_16x16x32_bf16 v[44:47], v[174:177], v[190:193], v[44:47]
	v_mfma_f32_16x16x32_bf16 v[40:43], v[182:185], v[190:193], v[40:43]
	v_mfma_f32_16x16x32_bf16 v[28:31], v[174:177], v[198:201], v[28:31]
	v_mfma_f32_16x16x32_bf16 v[24:27], v[182:185], v[198:201], v[24:27]
	v_mfma_f32_16x16x32_bf16 v[12:15], v[174:177], v[206:209], v[12:15]
	v_mfma_f32_16x16x32_bf16 v[8:11], v[182:185], v[206:209], v[8:11]
	v_mfma_f32_16x16x32_bf16 v[4:7], v[174:177], v[214:217], v[4:7]
	v_mfma_f32_16x16x32_bf16 v[0:3], v[182:185], v[214:217], v[0:3]
	v_mfma_f32_16x16x32_bf16 v[44:47], v[178:181], v[194:197], v[44:47]
	v_mfma_f32_16x16x32_bf16 v[40:43], v[186:189], v[194:197], v[40:43]
	v_mfma_f32_16x16x32_bf16 v[28:31], v[178:181], v[202:205], v[28:31]
	v_mfma_f32_16x16x32_bf16 v[24:27], v[186:189], v[202:205], v[24:27]
	v_mfma_f32_16x16x32_bf16 v[12:15], v[178:181], v[210:213], v[12:15]
	v_mfma_f32_16x16x32_bf16 v[8:11], v[186:189], v[210:213], v[8:11]
	v_mfma_f32_16x16x32_bf16 v[4:7], v[178:181], v[218:221], v[4:7]
	v_mfma_f32_16x16x32_bf16 v[0:3], v[186:189], v[218:221], v[0:3]
	s_setprio 0
	s_barrier
	s_add_i32 s48, s48, 2
	s_add_u32 s20, s20, 0x100
	s_addc_u32 s21, s21, 0
	s_add_u32 s29, s29, 0x100
	s_addc_u32 s47, s47, 0
	s_cmp_gt_u32 s48, 29
	s_mov_b32 s100, 0
	s_cbranch_scc0 .LBB0_1135
	s_and_b64 vcc, exec, s[6:7]
	s_cbranch_vccz .LBB0_1138
	s_barrier
; __device__ __forceinline__ unsigned cvt_pk_bf16(float lo, float hi) { return pk2(lo, hi); }
;     __device__ __forceinline__ void operator()(const f32x4 (&acc)[2][2][4][2], const Unit& u, int wr, int wc, int fr, int fq) const {
;         const int row0 = u.pm * BM + wr * 64 + fr; const int col0 = u.pn * BM + wc * 32 + 8 * fq;
;         bf16_t* O = u.mode ? O1 : O0; const int ldc = u.mode ? ldc1 : ldc0;
; #pragma unroll
;         for (int ai = 0; ai < 2; ++ai)
; #pragma unroll
;             for (int m = 0; m < 4; ++m) { bf16_t* rowp = O + (size_t)(row0 + ai * HALF + m * 16) * ldc + col0;
; #pragma unroll
;                 for (int bj = 0; bj < 2; ++bj) { f32x4 v0 = acc[ai][bj][m][0], v1 = acc[ai][bj][m][1];
;                     if (ACT == 1) {
; #pragma unroll
;                         for (int e = 0; e < 4; ++e) { float a = fmaxf(v0[e], 0.f), b = fmaxf(v1[e], 0.f); v0[e] = a * a; v1[e] = b * b; } }
;                     u32x4 w; w.x = cvt_pk_bf16(v0[0], v0[1]); w.y = cvt_pk_bf16(v0[2], v0[3]); w.z = cvt_pk_bf16(v1[0], v1[1]); w.w = cvt_pk_bf16(v1[2], v1[3]);
;                     *(u32x4*)(rowp + bj * HALF) = w; } }
.LBB0_1138:
	s_cmp_eq_u32 s38, 0
	v_lshl_or_b32 v150, s9, 8, v146
	s_cselect_b32 s9, s45, 0x19c00000
	s_cselect_b32 s13, s46, 0x4400
	s_add_u32 s20, s90, s9
	s_addc_u32 s21, s91, 0
	v_lshl_add_u32 v154, s8, 8, v144
	v_ashrrev_i32_e32 v151, 31, v150
	v_lshl_add_u64 v[150:151], v[150:151], 1, s[20:21]
	v_mad_i64_i32 v[152:153], s[8:9], s13, v154, 0
	v_cvt_pk_bf16_f32 v108, v108, v109
	v_cvt_pk_bf16_f32 v109, v110, v111
	v_cvt_pk_bf16_f32 v110, v104, v105
	v_or_b32_e32 v104, 16, v154
	v_lshl_add_u64 v[152:153], v[152:153], 1, v[150:151]
	v_cvt_pk_bf16_f32 v111, v106, v107
	v_mad_i64_i32 v[104:105], s[8:9], s13, v104, 0
	v_cvt_pk_bf16_f32 v92, v92, v93
	v_cvt_pk_bf16_f32 v93, v94, v95
	v_cvt_pk_bf16_f32 v94, v88, v89
	v_or_b32_e32 v88, 32, v154
	v_cvt_pk_bf16_f32 v124, v124, v125
	v_cvt_pk_bf16_f32 v125, v126, v127
	v_cvt_pk_bf16_f32 v126, v120, v121
	v_cvt_pk_bf16_f32 v127, v122, v123
	global_store_dwordx4 v[152:153], v[108:111], off offset:256
	v_cvt_pk_bf16_f32 v95, v90, v91
	v_mad_i64_i32 v[88:89], s[8:9], s13, v88, 0
	v_lshl_add_u64 v[108:109], v[104:105], 1, v[150:151]
	v_cvt_pk_bf16_f32 v76, v76, v77
	v_cvt_pk_bf16_f32 v77, v78, v79
	v_cvt_pk_bf16_f32 v78, v72, v73
	v_or_b32_e32 v72, 48, v154
	v_cvt_pk_bf16_f32 v68, v68, v69
	v_cvt_pk_bf16_f32 v69, v70, v71
	v_cvt_pk_bf16_f32 v70, v64, v65
	v_add_u32_e32 v64, 0x80, v154
	global_store_dwordx4 v[152:153], v[124:127], off
	v_cvt_pk_bf16_f32 v104, v116, v117
	v_cvt_pk_bf16_f32 v105, v118, v119
	v_cvt_pk_bf16_f32 v106, v112, v113
	v_cvt_pk_bf16_f32 v107, v114, v115
	global_store_dwordx4 v[108:109], v[92:95], off offset:256
	v_cvt_pk_bf16_f32 v79, v74, v75
	v_mad_i64_i32 v[72:73], s[8:9], s13, v72, 0
	v_lshl_add_u64 v[92:93], v[88:89], 1, v[150:151]
	v_mad_i64_i32 v[64:65], s[8:9], s13, v64, 0
	v_cvt_pk_bf16_f32 v44, v44, v45
	v_cvt_pk_bf16_f32 v45, v46, v47
	v_cvt_pk_bf16_f32 v46, v40, v41
	v_add_u32_e32 v40, 0x90, v154
	global_store_dwordx4 v[108:109], v[104:107], off
	v_cvt_pk_bf16_f32 v88, v100, v101
	v_cvt_pk_bf16_f32 v89, v102, v103
	v_cvt_pk_bf16_f32 v90, v96, v97
	v_cvt_pk_bf16_f32 v91, v98, v99
	global_store_dwordx4 v[92:93], v[76:79], off offset:256
	v_cvt_pk_bf16_f32 v74, v80, v81
	v_cvt_pk_bf16_f32 v75, v82, v83
	v_lshl_add_u64 v[76:77], v[72:73], 1, v[150:151]
	v_cvt_pk_bf16_f32 v72, v84, v85
	v_cvt_pk_bf16_f32 v73, v86, v87
	v_cvt_pk_bf16_f32 v71, v66, v67
	v_lshl_add_u64 v[64:65], v[64:65], 1, v[150:151]
	v_cvt_pk_bf16_f32 v47, v42, v43
	v_mad_i64_i32 v[40:41], s[8:9], s13, v40, 0
	v_cvt_pk_bf16_f32 v28, v28, v29
	v_cvt_pk_bf16_f32 v29, v30, v31
	v_cvt_pk_bf16_f32 v30, v24, v25
	v_add_u32_e32 v24, 0xa0, v154
	global_store_dwordx4 v[92:93], v[88:91], off
	global_store_dwordx4 v[76:77], v[72:75], off
	global_store_dwordx4 v[76:77], v[68:71], off offset:256
	v_cvt_pk_bf16_f32 v60, v60, v61
	v_cvt_pk_bf16_f32 v61, v62, v63
	v_cvt_pk_bf16_f32 v62, v56, v57
	v_cvt_pk_bf16_f32 v63, v58, v59
	global_store_dwordx4 v[64:65], v[44:47], off offset:256
	v_cvt_pk_bf16_f32 v31, v26, v27
	v_mad_i64_i32 v[24:25], s[8:9], s13, v24, 0
	v_lshl_add_u64 v[44:45], v[40:41], 1, v[150:151]
	v_cvt_pk_bf16_f32 v12, v12, v13
	v_cvt_pk_bf16_f32 v13, v14, v15
	v_cvt_pk_bf16_f32 v14, v8, v9
	v_add_u32_e32 v8, 0xb0, v154
	global_store_dwordx4 v[64:65], v[60:63], off
	v_cvt_pk_bf16_f32 v40, v52, v53
	v_cvt_pk_bf16_f32 v41, v54, v55
	v_cvt_pk_bf16_f32 v42, v48, v49
	v_cvt_pk_bf16_f32 v43, v50, v51
	global_store_dwordx4 v[44:45], v[28:31], off offset:256
	v_cvt_pk_bf16_f32 v15, v10, v11
	v_mad_i64_i32 v[8:9], s[8:9], s13, v8, 0
	v_lshl_add_u64 v[28:29], v[24:25], 1, v[150:151]
	global_store_dwordx4 v[44:45], v[40:43], off
	v_cvt_pk_bf16_f32 v24, v36, v37
	v_cvt_pk_bf16_f32 v25, v38, v39
	v_cvt_pk_bf16_f32 v26, v32, v33
	v_cvt_pk_bf16_f32 v27, v34, v35
	global_store_dwordx4 v[28:29], v[12:15], off offset:256
	v_cvt_pk_bf16_f32 v10, v16, v17
	v_cvt_pk_bf16_f32 v11, v18, v19
	v_lshl_add_u64 v[12:13], v[8:9], 1, v[150:151]
	v_cvt_pk_bf16_f32 v8, v20, v21
	v_cvt_pk_bf16_f32 v9, v22, v23
	v_cvt_pk_bf16_f32 v4, v4, v5
	v_cvt_pk_bf16_f32 v5, v6, v7
	v_cvt_pk_bf16_f32 v6, v0, v1
	v_cvt_pk_bf16_f32 v7, v2, v3
	s_andn2_b64 vcc, exec, s[18:19]
	s_mov_b64 s[8:9], -1
	global_store_dwordx4 v[28:29], v[24:27], off
	global_store_dwordx4 v[12:13], v[8:11], off
	global_store_dwordx4 v[12:13], v[4:7], off offset:256
	s_mov_b32 s100, 1
	s_cbranch_vccnz .LBB0_1129
	s_andn2_b64 vcc, exec, s[2:3]
	s_cbranch_vccnz .LBB0_1128
	s_barrier
	s_branch .LBB0_1128

; #define PG8_STAGE(bufoff, gbase, voff) do { _Pragma("unroll") for (int _i = 0; _i < 2; ++_i) \
;         __builtin_amdgcn_global_load_lds((const unsigned*)((const char*)(gbase) + (voff)[_i]), (LAS unsigned*)(lds + (bufoff) + ldsw + _i * 8192), 16, 0, 0); } while (0)
; #define PG8_WAIT_V(n) asm volatile("s_waitcnt vmcnt(" #n ")" ::: "memory")
; #define PG8_BAR __builtin_amdgcn_s_barrier()
; template <class Epi, class Sched, bool ALIGN_EPI = false, bool SP2 = false>
; __device__ __forceinline__ void gemm_phase(LAS unsigned char* lds, const Gemm g, const Sched& S, const Epi& E) {
;     ...
;     const char* cA = cur.a; const char* cB = cur.b;
;     S.a_ready(cur);
;     if constexpr (SP2) {
;         PG8_STAGE(PG8_SB(0, 0), cB, voffB); PG8_STAGE(PG8_SB(0, 1), cB + hstep, voffB); PG8_STAGE(PG8_SA(0, 0), cA, voffA); PG8_STAGE(PG8_SA(0, 1), cA + hstep, voffA);
;         if (wr == 1) PG8_BAR;
;         PG8_WAIT_V(2); PG8_BAR;
;         PG8_STAGE(PG8_SB(1, 0), cB + kstep, voffB); PG8_STAGE(PG8_SA(1, 0), cA + kstep, voffA); PG8_STAGE(PG8_SB(1, 1), cB + hstep + kstep, voffB);
;         PG8_WAIT_V(6); PG8_BAR;
;     } else {
;         PG8_STAGE(PG8_SB(0, 0), cB, voffB); PG8_STAGE(PG8_SA(0, 0), cA, voffA); PG8_STAGE(PG8_SB(0, 1), cB + hstep, voffB); PG8_STAGE(PG8_SA(0, 1), cA + hstep, voffA);
;         if (wr == 1) PG8_BAR;
;         PG8_WAIT_V(4); PG8_BAR;
;         PG8_STAGE(PG8_SB(1, 0), cB + kstep, voffB); PG8_STAGE(PG8_SA(1, 0), cA + kstep, voffA); PG8_STAGE(PG8_SB(1, 1), cB + hstep + kstep, voffB);
;         PG8_WAIT_V(6); PG8_BAR;
;     }
; __device__ __forceinline__ void run_gemm_store(const Params& p, LAS unsigned char* ldsl, const int ph) {
;     ...
;     else { E.O0 = (bf16_t*)(ws + WS_H); E.ldc0 = DFF; E.ACT = 1; S.add(A, (const bf16_t*)(ws + WS_WUP) + (size_t)l1 * D * DFF, Mrows / 256, DFF / 256, 1, D / 64, 0); }
.LBB0_1538:
	s_cmp_lt_i32 s80, 15
	s_cselect_b64 s[2:3], -1, 0
	s_and_b64 s[2:3], s[2:3], s[0:1]
	s_andn2_b64 vcc, exec, s[2:3]
	s_cbranch_vccnz .LBB0_1559
	s_mov_b32 s100, 0
	s_cmpk_gt_i32 s92, 0x7ff
	v_readfirstlane_b32 s1, v162
	s_cbranch_scc1 .LBB0_1559
	v_lshrrev_b32_e32 v2, 1, v162
	v_and_b32_e32 v11, 24, v2
	v_lshrrev_b32_e32 v2, 5, v162
	v_and_b32_e32 v2, 4, v2
	v_bfe_u32 v3, v162, 2, 2
	s_add_u32 s33, s90, 0xc600000
	v_lshlrev_b32_e32 v0, 4, v162
	v_and_b32_e32 v1, 32, v162
	v_bfe_u32 v10, v162, 2, 4
	v_or3_b32 v2, v2, v3, v11
	v_lshrrev_b32_e32 v3, 3, v162
	s_movk_i32 s0, 0x70
	s_addc_u32 s42, s91, 0
	v_bitop3_b32 v8, v0, v1, 48 bitop3:0x6c
	v_and_b32_e32 v9, 64, v162
	v_and_or_b32 v4, v3, s0, v10
	s_movk_i32 s0, 0x60
	v_add_u32_e32 v12, 0x2000, v0
	s_add_u32 s43, s90, 0x3e00000
	v_or_b32_e32 v1, v8, v9
	v_and_or_b32 v3, v3, s0, v2
	v_lshrrev_b32_e32 v0, 7, v12
	s_movk_i32 s0, 0xf0
	s_addc_u32 s44, s91, 0
	v_lshl_or_b32 v130, v3, 12, v1
	v_and_or_b32 v3, v0, s0, v10
	s_movk_i32 s0, 0xe0
	s_ashr_i32 s46, s92, 31
	v_and_or_b32 v0, v0, s0, v2
	s_lshr_b32 s0, s46, 29
	s_add_i32 s0, s92, s0
	s_and_b32 s4, s0, -8
	s_lshr_b32 s6, s1, 6
	s_sub_i32 s4, s92, s4
	s_lshr_b32 s8, s1, 8
	s_lshl_b32 s45, s6, 10
	s_lshl_b32 s7, s4, 8
	s_ashr_i32 s0, s0, 3
	s_mul_i32 s5, s4, 0x101
	s_cmp_lt_i32 s4, 0
	s_cselect_b32 s4, s5, s7
	s_add_i32 s0, s4, s0
	s_ashr_i32 s4, s0, 31
	s_lshr_b32 s4, s4, 25
	s_add_i32 s4, s0, s4
	s_ashr_i32 s5, s4, 7
	s_lshl_b32 s7, s5, 2
	s_sub_i32 s5, 64, s7
	s_min_u32 s9, s5, 4
	s_and_b32 s4, s4, 0xffffff80
	v_lshl_or_b32 v132, v3, 12, v1
	s_sub_i32 s10, s0, s4
	v_cvt_f32_ubyte0_e32 v3, s9
	v_lshl_or_b32 v128, v4, 12, v1
	v_cvt_f32_i32_e32 v2, s10
	v_rcp_iflag_f32_e32 v4, v3
	v_lshl_or_b32 v134, v0, 12, v1
	s_ashr_i32 s0, s10, 30
	s_or_b32 s0, s0, 1
	v_mul_f32_e32 v0, v2, v4
	v_trunc_f32_e32 v0, v0
	v_fma_f32 v1, -v0, v3, v2
	v_cvt_i32_f32_e32 v0, v0
	v_cmp_ge_f32_e64 s[4:5], |v1|, v3
	s_and_b64 s[4:5], s[4:5], exec
	s_cselect_b32 s0, s0, 0
	v_readfirstlane_b32 s4, v0
	s_add_i32 s0, s4, s0
	s_mul_i32 s4, s0, s9
	s_sub_i32 s4, s10, s4
	s_sext_i32_i8 s4, s4
	s_add_i32 s28, s7, s4
	s_ashr_i32 s29, s28, 31
	s_lshl_b64 s[4:5], s[28:29], 20
	s_add_u32 s36, s33, s4
	s_addc_u32 s37, s42, s5
	s_bfe_i64 s[4:5], s[0:1], 0x80000
	s_lshl_b64 s[4:5], s[4:5], 20
	s_add_u32 s38, s43, s4
	s_addc_u32 s39, s44, s5
	s_add_i32 s29, s45, 0
	s_add_i32 m0, s29, 0x10000
	v_mov_b32_e32 v131, 0
	global_load_lds_dwordx4 v130, s[38:39]
	s_add_i32 m0, s29, 0x12000
	s_add_u32 s4, s38, 0x80000
	global_load_lds_dwordx4 v134, s[38:39]
	s_addc_u32 s5, s39, 0
	s_add_i32 m0, s29, 0x14000
	s_add_i32 s47, s29, 0x2000
	global_load_lds_dwordx4 v130, s[4:5]
	s_add_i32 m0, s29, 0x16000
	v_mov_b32_e32 v135, v131
	global_load_lds_dwordx4 v134, s[4:5]
	s_mov_b32 m0, s29
	s_add_u32 s4, s36, 0x80000
	global_load_lds_dwordx4 v128, s[36:37]
	s_mov_b32 m0, s47
	s_addc_u32 s5, s37, 0
	s_add_i32 s48, s29, 0x4000
	global_load_lds_dwordx4 v132, s[36:37]
	s_mov_b32 m0, s48
	s_add_i32 s49, s29, 0x6000
	global_load_lds_dwordx4 v128, s[4:5]
	s_mov_b32 m0, s49
	v_mov_b32_e32 v129, v131
	global_load_lds_dwordx4 v132, s[4:5]
	v_mov_b32_e32 v133, v131
	s_cmp_eq_u32 s8, 1
	s_mov_b32 s50, 0
	v_lshl_add_u64 v[6:7], s[38:39], 0, v[130:131]
	v_lshl_add_u64 v[4:5], s[38:39], 0, v[134:135]
	v_lshl_add_u64 v[0:1], s[36:37], 0, v[128:129]
	s_cselect_b64 s[4:5], -1, 0
	s_cmp_lg_u32 s8, 1
	v_lshl_add_u64 v[2:3], s[36:37], 0, v[132:133]
	s_cbranch_scc1 .LBB0_1542
	s_barrier

; #define PG8_STAGE(bufoff, gbase, voff) do { _Pragma("unroll") for (int _i = 0; _i < 2; ++_i) \
;         __builtin_amdgcn_global_load_lds((const unsigned*)((const char*)(gbase) + (voff)[_i]), (LAS unsigned*)(lds + (bufoff) + ldsw + _i * 8192), 16, 0, 0); } while (0)
; #define PG8_LDA(dst, b, h) do { _Pragma("unroll") for (int m = 0; m < 4; ++m) _Pragma("unroll") for (int k = 0; k < 2; ++k) dst[m][k] = *(const LAS bf16x8*)(lds + PG8_SA(b, h) + aoff + m * 2048 + k * 1024); } while (0)
; #define PG8_LDB(dst, b, h) do { _Pragma("unroll") for (int n = 0; n < 2; ++n) _Pragma("unroll") for (int k = 0; k < 2; ++k) dst[n][k] = *(const LAS bf16x8*)(lds + PG8_SB(b, h) + boff + n * 2048 + k * 1024); } while (0)
; #define PG8_MMA(ai, bj, At, Bt) do { __builtin_amdgcn_s_setprio(1); _Pragma("unroll") for (int m = 0; m < 4; ++m) _Pragma("unroll") for (int n = 0; n < 2; ++n) _Pragma("unroll") for (int k = 0; k < 2; ++k) \
;         acc[ai][bj][m][n] = __builtin_amdgcn_mfma_f32_16x16x32_bf16(Bt[n][k], At[m][k], acc[ai][bj][m][n], 0, 0, 0); __builtin_amdgcn_s_setprio(0); } while (0)
; #define PG8_WAIT_V(n) asm volatile("s_waitcnt vmcnt(" #n ")" ::: "memory")
; #define PG8_WAIT_L(n) asm volatile("s_waitcnt lgkmcnt(" #n ")" ::: "memory")
; #define PG8_BAR __builtin_amdgcn_s_barrier()
; #define PG8_SCHED __builtin_amdgcn_sched_barrier(0)
; template <class Epi, class Sched, bool ALIGN_EPI = false, bool SP2 = false>
; __device__ __forceinline__ void gemm_phase(LAS unsigned char* lds, const Gemm g, const Sched& S, const Epi& E) {
;     ...
;             if constexpr (SP2) {
;             PG8_LDB(B0, 0, 0); PG8_LDB(B1, 0, 1); PG8_SCHED; PG8_LDA(At, 0, 0); PG8_STAGE(PG8_SA(1, 1), a1 + hstep, voffA);
;             PG8_WAIT_V(8); PG8_WAIT_L(0); PG8_BAR; PG8_MMA(0, 0, At, B0); PG8_MMA(0, 1, At, B1); PG8_BAR; PG8_SCHED;
.LBB0_1552:
	ds_read_b128 v[152:155], v149
	ds_read_b128 v[156:159], v149 offset:1024
	ds_read_b128 v[164:167], v149 offset:2048
	ds_read_b128 v[170:173], v149 offset:3072
	ds_read_b128 v[174:177], v150
	ds_read_b128 v[178:181], v150 offset:1024
	ds_read_b128 v[182:185], v150 offset:2048
	ds_read_b128 v[186:189], v150 offset:3072
	s_add_u32 s38, s36, 0xfff80080
	s_addc_u32 s39, s37, -1
	s_cmp_eq_u32 s62, 28
	s_cselect_b32 s41, s31, s39
	s_cselect_b32 s40, s30, s38
	s_cselect_b32 s39, s35, s23
	s_cselect_b32 s38, s34, s21
	v_lshl_add_u64 v[144:145], s[36:37], 0, v[136:137]
	s_add_i32 m0, s29, 0xc000
	ds_read_b128 v[190:193], v151
	ds_read_b128 v[194:197], v151 offset:1024
	ds_read_b128 v[198:201], v151 offset:2048
	ds_read_b128 v[202:205], v151 offset:3072
	ds_read_b128 v[206:209], v151 offset:4096
	ds_read_b128 v[210:213], v151 offset:5120
	ds_read_b128 v[214:217], v151 offset:6144
	ds_read_b128 v[218:221], v151 offset:7168
	global_load_lds_dwordx4 v[144:145], off
	v_lshl_add_u64 v[144:145], s[36:37], 0, v[138:139]
	s_add_i32 m0, s29, 0xe000
	s_nop 0
	global_load_lds_dwordx4 v[144:145], off
	s_cmp_eq_u32 s100, 1
	s_cbranch_scc1 .Ltw_tilewait_33600_0a
	s_waitcnt vmcnt(8)
	s_branch .Ltw_tilewait_33600_0b

; #define PG8_STAGE(bufoff, gbase, voff) do { _Pragma("unroll") for (int _i = 0; _i < 2; ++_i) \
;         __builtin_amdgcn_global_load_lds((const unsigned*)((const char*)(gbase) + (voff)[_i]), (LAS unsigned*)(lds + (bufoff) + ldsw + _i * 8192), 16, 0, 0); } while (0)
; #define PG8_LDA(dst, b, h) do { _Pragma("unroll") for (int m = 0; m < 4; ++m) _Pragma("unroll") for (int k = 0; k < 2; ++k) dst[m][k] = *(const LAS bf16x8*)(lds + PG8_SA(b, h) + aoff + m * 2048 + k * 1024); } while (0)
; #define PG8_LDB(dst, b, h) do { _Pragma("unroll") for (int n = 0; n < 2; ++n) _Pragma("unroll") for (int k = 0; k < 2; ++k) dst[n][k] = *(const LAS bf16x8*)(lds + PG8_SB(b, h) + boff + n * 2048 + k * 1024); } while (0)
; #define PG8_MMA(ai, bj, At, Bt) do { __builtin_amdgcn_s_setprio(1); _Pragma("unroll") for (int m = 0; m < 4; ++m) _Pragma("unroll") for (int n = 0; n < 2; ++n) _Pragma("unroll") for (int k = 0; k < 2; ++k) \
;         acc[ai][bj][m][n] = __builtin_amdgcn_mfma_f32_16x16x32_bf16(Bt[n][k], At[m][k], acc[ai][bj][m][n], 0, 0, 0); __builtin_amdgcn_s_setprio(0); } while (0)
; #define PG8_WAIT_V(n) asm volatile("s_waitcnt vmcnt(" #n ")" ::: "memory")
; #define PG8_WAIT_L(n) asm volatile("s_waitcnt lgkmcnt(" #n ")" ::: "memory")
; #define PG8_BAR __builtin_amdgcn_s_barrier()
; #define PG8_SCHED __builtin_amdgcn_sched_barrier(0)
; template <class Epi, class Sched, bool ALIGN_EPI = false, bool SP2 = false>
; __device__ __forceinline__ void gemm_phase(LAS unsigned char* lds, const Gemm g, const Sched& S, const Epi& E) {
;     ...
;             PG8_LDB(B0, 0, 0); PG8_LDB(B1, 0, 1); PG8_SCHED; PG8_LDA(At, 0, 0); PG8_STAGE(PG8_SA(1, 1), a1 + hstep, voffA);
;             PG8_WAIT_V(8); PG8_WAIT_L(0); PG8_BAR; PG8_MMA(0, 0, At, B0); PG8_MMA(0, 1, At, B1); PG8_BAR; PG8_SCHED;
;             PG8_LDA(At, 0, 1); PG8_STAGE(PG8_SB(0, 0), b2, voffB); PG8_STAGE(PG8_SB(0, 1), b2 + hstep, voffB); PG8_STAGE(PG8_SA(0, 0), a2, voffA);
;             PG8_WAIT_V(8); PG8_WAIT_L(0); PG8_BAR; PG8_MMA(1, 0, At, B0); PG8_MMA(1, 1, At, B1); PG8_BAR; PG8_SCHED;
.Ltw_tilewait_33600_0b:
	s_waitcnt lgkmcnt(0)
	s_barrier
	s_setprio 1
	s_waitcnt lgkmcnt(0)
	v_mfma_f32_16x16x32_bf16 v[124:127], v[152:155], v[190:193], v[124:127]
	v_mfma_f32_16x16x32_bf16 v[120:123], v[164:167], v[190:193], v[120:123]
	v_mfma_f32_16x16x32_bf16 v[108:111], v[152:155], v[198:201], v[108:111]
	v_mfma_f32_16x16x32_bf16 v[104:107], v[164:167], v[198:201], v[104:107]
	v_mfma_f32_16x16x32_bf16 v[92:95], v[152:155], v[206:209], v[92:95]
	v_mfma_f32_16x16x32_bf16 v[88:91], v[164:167], v[206:209], v[88:91]
	v_mfma_f32_16x16x32_bf16 v[76:79], v[152:155], v[214:217], v[76:79]
	v_mfma_f32_16x16x32_bf16 v[72:75], v[164:167], v[214:217], v[72:75]
	v_mfma_f32_16x16x32_bf16 v[124:127], v[156:159], v[194:197], v[124:127]
	v_mfma_f32_16x16x32_bf16 v[120:123], v[170:173], v[194:197], v[120:123]
	v_mfma_f32_16x16x32_bf16 v[108:111], v[156:159], v[202:205], v[108:111]
	v_mfma_f32_16x16x32_bf16 v[104:107], v[170:173], v[202:205], v[104:107]
	v_mfma_f32_16x16x32_bf16 v[92:95], v[156:159], v[210:213], v[92:95]
	v_mfma_f32_16x16x32_bf16 v[88:91], v[170:173], v[210:213], v[88:91]
	v_mfma_f32_16x16x32_bf16 v[76:79], v[156:159], v[218:221], v[76:79]
	v_mfma_f32_16x16x32_bf16 v[72:75], v[170:173], v[218:221], v[72:75]
	s_setprio 0
	s_setprio 1
	v_mfma_f32_16x16x32_bf16 v[116:119], v[174:177], v[190:193], v[116:119]
	v_mfma_f32_16x16x32_bf16 v[112:115], v[182:185], v[190:193], v[112:115]
	v_mfma_f32_16x16x32_bf16 v[100:103], v[174:177], v[198:201], v[100:103]
	v_mfma_f32_16x16x32_bf16 v[96:99], v[182:185], v[198:201], v[96:99]
	v_mfma_f32_16x16x32_bf16 v[84:87], v[174:177], v[206:209], v[84:87]
	v_mfma_f32_16x16x32_bf16 v[80:83], v[182:185], v[206:209], v[80:83]
	v_mfma_f32_16x16x32_bf16 v[68:71], v[174:177], v[214:217], v[68:71]
	v_mfma_f32_16x16x32_bf16 v[64:67], v[182:185], v[214:217], v[64:67]
	v_mfma_f32_16x16x32_bf16 v[116:119], v[178:181], v[194:197], v[116:119]
	v_mfma_f32_16x16x32_bf16 v[112:115], v[186:189], v[194:197], v[112:115]
	v_mfma_f32_16x16x32_bf16 v[100:103], v[178:181], v[202:205], v[100:103]
	v_mfma_f32_16x16x32_bf16 v[96:99], v[186:189], v[202:205], v[96:99]
	v_mfma_f32_16x16x32_bf16 v[84:87], v[178:181], v[210:213], v[84:87]
	v_mfma_f32_16x16x32_bf16 v[80:83], v[186:189], v[210:213], v[80:83]
	v_mfma_f32_16x16x32_bf16 v[68:71], v[178:181], v[218:221], v[68:71]
	v_mfma_f32_16x16x32_bf16 v[64:67], v[186:189], v[218:221], v[64:67]
	s_setprio 0
	s_barrier
	s_add_i32 s63, s55, s45
	v_lshl_add_u64 v[144:145], s[38:39], 0, v[130:131]
	s_mov_b32 m0, s63
	ds_read_b128 v[190:193], v151 offset:16384
	ds_read_b128 v[194:197], v151 offset:17408
	ds_read_b128 v[198:201], v151 offset:18432
	ds_read_b128 v[202:205], v151 offset:19456
	ds_read_b128 v[206:209], v151 offset:20480
	ds_read_b128 v[210:213], v151 offset:21504
	ds_read_b128 v[214:217], v151 offset:22528
	ds_read_b128 v[218:221], v151 offset:23552
	global_load_lds_dwordx4 v[144:145], off
	s_add_i32 m0, s63, 0x2000
	s_add_u32 s64, s38, 0x80000
	v_lshl_add_u64 v[222:223], s[38:39], 0, v[134:135]
	s_addc_u32 s65, s39, 0
	s_add_i32 s63, s56, s45
	global_load_lds_dwordx4 v[222:223], off
	v_lshl_add_u64 v[224:225], s[64:65], 0, v[130:131]
	s_mov_b32 m0, s63
	v_lshl_add_u64 v[226:227], s[40:41], 0, v[132:133]
	global_load_lds_dwordx4 v[224:225], off
	v_lshl_add_u64 v[224:225], s[64:65], 0, v[134:135]
	s_add_i32 m0, s63, 0x2000
	s_nop 0
	global_load_lds_dwordx4 v[224:225], off
	v_lshl_add_u64 v[224:225], s[40:41], 0, v[128:129]
	s_mov_b32 m0, s29
	s_nop 0
	global_load_lds_dwordx4 v[224:225], off
	s_mov_b32 m0, s47
	s_nop 0
	global_load_lds_dwordx4 v[226:227], off
	s_cmp_eq_u32 s100, 1
	s_cbranch_scc1 .Ltw_tilewait_33600_1a
	s_waitcnt vmcnt(8)
	s_branch .Ltw_tilewait_33600_1b

; #define PG8_STAGE(bufoff, gbase, voff) do { _Pragma("unroll") for (int _i = 0; _i < 2; ++_i) \
;         __builtin_amdgcn_global_load_lds((const unsigned*)((const char*)(gbase) + (voff)[_i]), (LAS unsigned*)(lds + (bufoff) + ldsw + _i * 8192), 16, 0, 0); } while (0)
; #define PG8_LDA(dst, b, h) do { _Pragma("unroll") for (int m = 0; m < 4; ++m) _Pragma("unroll") for (int k = 0; k < 2; ++k) dst[m][k] = *(const LAS bf16x8*)(lds + PG8_SA(b, h) + aoff + m * 2048 + k * 1024); } while (0)
; #define PG8_LDB(dst, b, h) do { _Pragma("unroll") for (int n = 0; n < 2; ++n) _Pragma("unroll") for (int k = 0; k < 2; ++k) dst[n][k] = *(const LAS bf16x8*)(lds + PG8_SB(b, h) + boff + n * 2048 + k * 1024); } while (0)
; #define PG8_MMA(ai, bj, At, Bt) do { __builtin_amdgcn_s_setprio(1); _Pragma("unroll") for (int m = 0; m < 4; ++m) _Pragma("unroll") for (int n = 0; n < 2; ++n) _Pragma("unroll") for (int k = 0; k < 2; ++k) \
;         acc[ai][bj][m][n] = __builtin_amdgcn_mfma_f32_16x16x32_bf16(Bt[n][k], At[m][k], acc[ai][bj][m][n], 0, 0, 0); __builtin_amdgcn_s_setprio(0); } while (0)
; #define PG8_WAIT_V(n) asm volatile("s_waitcnt vmcnt(" #n ")" ::: "memory")
; #define PG8_WAIT_L(n) asm volatile("s_waitcnt lgkmcnt(" #n ")" ::: "memory")
; #define PG8_BAR __builtin_amdgcn_s_barrier()
; #define PG8_SCHED __builtin_amdgcn_sched_barrier(0)
; template <class Epi, class Sched, bool ALIGN_EPI = false, bool SP2 = false>
; __device__ __forceinline__ void gemm_phase(LAS unsigned char* lds, const Gemm g, const Sched& S, const Epi& E) {
;     ...
;             PG8_WAIT_V(8); PG8_WAIT_L(0); PG8_BAR; PG8_MMA(1, 0, At, B0); PG8_MMA(1, 1, At, B1); PG8_BAR; PG8_SCHED;
;             PG8_LDB(B0, 1, 0); PG8_LDB(B1, 1, 1); PG8_SCHED; PG8_LDA(At, 1, 0); PG8_STAGE(PG8_SA(0, 1), a2 + hstep, voffA);
;             PG8_WAIT_V(8); PG8_WAIT_L(0); PG8_BAR; PG8_MMA(0, 0, At, B0); PG8_MMA(0, 1, At, B1); PG8_BAR; PG8_SCHED;
.Ltw_tilewait_33600_1b:
	s_waitcnt lgkmcnt(0)
	s_barrier
	s_setprio 1
	s_waitcnt lgkmcnt(0)
	v_mfma_f32_16x16x32_bf16 v[60:63], v[152:155], v[190:193], v[60:63]
	v_mfma_f32_16x16x32_bf16 v[56:59], v[164:167], v[190:193], v[56:59]
	v_mfma_f32_16x16x32_bf16 v[44:47], v[152:155], v[198:201], v[44:47]
	v_mfma_f32_16x16x32_bf16 v[40:43], v[164:167], v[198:201], v[40:43]
	v_mfma_f32_16x16x32_bf16 v[28:31], v[152:155], v[206:209], v[28:31]
	v_mfma_f32_16x16x32_bf16 v[24:27], v[164:167], v[206:209], v[24:27]
	v_mfma_f32_16x16x32_bf16 v[12:15], v[152:155], v[214:217], v[12:15]
	v_mfma_f32_16x16x32_bf16 v[8:11], v[164:167], v[214:217], v[8:11]
	v_mfma_f32_16x16x32_bf16 v[60:63], v[156:159], v[194:197], v[60:63]
	v_mfma_f32_16x16x32_bf16 v[56:59], v[170:173], v[194:197], v[56:59]
	v_mfma_f32_16x16x32_bf16 v[44:47], v[156:159], v[202:205], v[44:47]
	v_mfma_f32_16x16x32_bf16 v[40:43], v[170:173], v[202:205], v[40:43]
	v_mfma_f32_16x16x32_bf16 v[28:31], v[156:159], v[210:213], v[28:31]
	v_mfma_f32_16x16x32_bf16 v[24:27], v[170:173], v[210:213], v[24:27]
	v_mfma_f32_16x16x32_bf16 v[12:15], v[156:159], v[218:221], v[12:15]
	v_mfma_f32_16x16x32_bf16 v[8:11], v[170:173], v[218:221], v[8:11]
	s_setprio 0
	s_setprio 1
	v_mfma_f32_16x16x32_bf16 v[52:55], v[174:177], v[190:193], v[52:55]
	v_mfma_f32_16x16x32_bf16 v[48:51], v[182:185], v[190:193], v[48:51]
	v_mfma_f32_16x16x32_bf16 v[36:39], v[174:177], v[198:201], v[36:39]
	v_mfma_f32_16x16x32_bf16 v[32:35], v[182:185], v[198:201], v[32:35]
	v_mfma_f32_16x16x32_bf16 v[20:23], v[174:177], v[206:209], v[20:23]
	v_mfma_f32_16x16x32_bf16 v[16:19], v[182:185], v[206:209], v[16:19]
	v_mfma_f32_16x16x32_bf16 v[4:7], v[174:177], v[214:217], v[4:7]
	v_mfma_f32_16x16x32_bf16 v[0:3], v[182:185], v[214:217], v[0:3]
	v_mfma_f32_16x16x32_bf16 v[52:55], v[178:181], v[194:197], v[52:55]
	v_mfma_f32_16x16x32_bf16 v[48:51], v[186:189], v[194:197], v[48:51]
	v_mfma_f32_16x16x32_bf16 v[36:39], v[178:181], v[202:205], v[36:39]
	v_mfma_f32_16x16x32_bf16 v[32:35], v[186:189], v[202:205], v[32:35]
	v_mfma_f32_16x16x32_bf16 v[20:23], v[178:181], v[210:213], v[20:23]
	v_mfma_f32_16x16x32_bf16 v[16:19], v[186:189], v[210:213], v[16:19]
	v_mfma_f32_16x16x32_bf16 v[4:7], v[178:181], v[218:221], v[4:7]
	v_mfma_f32_16x16x32_bf16 v[0:3], v[186:189], v[218:221], v[0:3]
	s_setprio 0
	s_barrier
	s_add_i32 s63, 0, 0x18000
	v_add_u32_e32 v163, s63, v147
	s_add_i32 s64, 0, 0x1c000
	ds_read_b128 v[152:155], v163
	ds_read_b128 v[156:159], v163 offset:1024
	ds_read_b128 v[164:167], v163 offset:2048
	ds_read_b128 v[170:173], v163 offset:3072
	v_add_u32_e32 v163, s64, v147
	ds_read_b128 v[174:177], v163
	ds_read_b128 v[178:181], v163 offset:1024
	ds_read_b128 v[182:185], v163 offset:2048
	ds_read_b128 v[186:189], v163 offset:3072
	s_add_u32 s40, s40, 0x80000
	s_addc_u32 s41, s41, 0
	s_mov_b32 m0, s48
	v_lshl_add_u64 v[228:229], s[40:41], 0, v[128:129]
	ds_read_b128 v[190:193], v151 offset:32768
	ds_read_b128 v[194:197], v151 offset:33792
	ds_read_b128 v[198:201], v151 offset:34816
	ds_read_b128 v[202:205], v151 offset:35840
	ds_read_b128 v[206:209], v151 offset:36864
	ds_read_b128 v[210:213], v151 offset:37888
	ds_read_b128 v[214:217], v151 offset:38912
	ds_read_b128 v[218:221], v151 offset:39936
	global_load_lds_dwordx4 v[228:229], off
	v_lshl_add_u64 v[228:229], s[40:41], 0, v[132:133]
	s_mov_b32 m0, s49
	s_nop 0
	global_load_lds_dwordx4 v[228:229], off
	s_waitcnt vmcnt(8)
	s_waitcnt lgkmcnt(0)
	s_barrier
	s_setprio 1
	s_waitcnt lgkmcnt(0)
	v_mfma_f32_16x16x32_bf16 v[124:127], v[152:155], v[190:193], v[124:127]
	v_mfma_f32_16x16x32_bf16 v[120:123], v[164:167], v[190:193], v[120:123]
	v_mfma_f32_16x16x32_bf16 v[108:111], v[152:155], v[198:201], v[108:111]
	v_mfma_f32_16x16x32_bf16 v[104:107], v[164:167], v[198:201], v[104:107]
	v_mfma_f32_16x16x32_bf16 v[92:95], v[152:155], v[206:209], v[92:95]
	v_mfma_f32_16x16x32_bf16 v[88:91], v[164:167], v[206:209], v[88:91]
	v_mfma_f32_16x16x32_bf16 v[76:79], v[152:155], v[214:217], v[76:79]
	v_mfma_f32_16x16x32_bf16 v[72:75], v[164:167], v[214:217], v[72:75]
	v_mfma_f32_16x16x32_bf16 v[124:127], v[156:159], v[194:197], v[124:127]
	v_mfma_f32_16x16x32_bf16 v[120:123], v[170:173], v[194:197], v[120:123]
	v_mfma_f32_16x16x32_bf16 v[108:111], v[156:159], v[202:205], v[108:111]
	v_mfma_f32_16x16x32_bf16 v[104:107], v[170:173], v[202:205], v[104:107]
	v_mfma_f32_16x16x32_bf16 v[92:95], v[156:159], v[210:213], v[92:95]
	v_mfma_f32_16x16x32_bf16 v[88:91], v[170:173], v[210:213], v[88:91]
	v_mfma_f32_16x16x32_bf16 v[76:79], v[156:159], v[218:221], v[76:79]
	v_mfma_f32_16x16x32_bf16 v[72:75], v[170:173], v[218:221], v[72:75]
	s_setprio 0
	s_setprio 1
	v_mfma_f32_16x16x32_bf16 v[116:119], v[174:177], v[190:193], v[116:119]
	v_mfma_f32_16x16x32_bf16 v[112:115], v[182:185], v[190:193], v[112:115]
	v_mfma_f32_16x16x32_bf16 v[100:103], v[174:177], v[198:201], v[100:103]
	v_mfma_f32_16x16x32_bf16 v[96:99], v[182:185], v[198:201], v[96:99]
	v_mfma_f32_16x16x32_bf16 v[84:87], v[174:177], v[206:209], v[84:87]
	v_mfma_f32_16x16x32_bf16 v[80:83], v[182:185], v[206:209], v[80:83]
	v_mfma_f32_16x16x32_bf16 v[68:71], v[174:177], v[214:217], v[68:71]
	v_mfma_f32_16x16x32_bf16 v[64:67], v[182:185], v[214:217], v[64:67]
	v_mfma_f32_16x16x32_bf16 v[116:119], v[178:181], v[194:197], v[116:119]
	v_mfma_f32_16x16x32_bf16 v[112:115], v[186:189], v[194:197], v[112:115]
	v_mfma_f32_16x16x32_bf16 v[100:103], v[178:181], v[202:205], v[100:103]
	v_mfma_f32_16x16x32_bf16 v[96:99], v[186:189], v[202:205], v[96:99]
	v_mfma_f32_16x16x32_bf16 v[84:87], v[178:181], v[210:213], v[84:87]
	v_mfma_f32_16x16x32_bf16 v[80:83], v[186:189], v[210:213], v[80:83]
	v_mfma_f32_16x16x32_bf16 v[68:71], v[178:181], v[218:221], v[68:71]
	v_mfma_f32_16x16x32_bf16 v[64:67], v[186:189], v[218:221], v[64:67]
	s_setprio 0
	s_barrier
;     __device__ __forceinline__ void operator()(const f32x4 (&acc)[2][2][4][2], const Unit& u, int wr, int wc, int fr, int fq) const {
;     ...
;             for (int m = 0; m < 4; ++m) { bf16_t* rowp = O + (size_t)(row0 + ai * HALF + m * 16) * ldc + col0;
; #pragma unroll
;                 for (int bj = 0; bj < 2; ++bj) { f32x4 v0 = acc[ai][bj][m][0], v1 = acc[ai][bj][m][1];
;                     if (ACT == 1) {
; #pragma unroll
;                         for (int e = 0; e < 4; ++e) { float a = fmaxf(v0[e], 0.f), b = fmaxf(v1[e], 0.f); v0[e] = a * a; v1[e] = b * b; } }
; template <class Epi, class Sched, bool ALIGN_EPI = false, bool SP2 = false>
; __device__ __forceinline__ void gemm_phase(LAS unsigned char* lds, const Gemm g, const Sched& S, const Epi& E) {
;     ...
;             PG8_LDA(At, 1, 1); PG8_STAGE(PG8_SB(1, 0), b3, voffB); PG8_STAGE(PG8_SB(1, 1), b3 + hstep, voffB); PG8_STAGE(PG8_SA(1, 0), a3, voffA);
;             PG8_WAIT_V(8); PG8_WAIT_L(0); PG8_BAR; PG8_MMA(1, 0, At, B0); PG8_MMA(1, 1, At, B1); PG8_BAR; PG8_SCHED;
;             } else {
;             PG8_LDB(B0, 0, 0); PG8_SCHED; PG8_LDA(At, 0, 0); PG8_STAGE(PG8_SA(1, 1), a1 + hstep, voffA);
;             PG8_WAIT_L(8); PG8_BAR; PG8_WAIT_L(0); PG8_MMA(0, 0, At, B0); PG8_BAR; PG8_SCHED;
;             PG8_LDB(B1, 0, 1); PG8_STAGE(PG8_SB(0, 0), b2, voffB);
;             PG8_BAR; PG8_WAIT_L(0); PG8_MMA(0, 1, At, B1); PG8_BAR;
;             PG8_LDA(At, 0, 1); PG8_STAGE(PG8_SA(0, 0), a2, voffA);
;             PG8_BAR; PG8_WAIT_L(0); PG8_MMA(1, 0, At, B0); PG8_BAR; PG8_SCHED;
;             PG8_STAGE(PG8_SB(0, 1), b2 + hstep, voffB);
;             PG8_WAIT_V(6); PG8_BAR; PG8_MMA(1, 1, At, B1); PG8_BAR;
;             PG8_LDB(B0, 1, 0); PG8_SCHED; PG8_LDA(At, 1, 0); PG8_STAGE(PG8_SA(0, 1), a2 + hstep, voffA);
;             PG8_WAIT_L(8); PG8_BAR; PG8_WAIT_L(0); PG8_MMA(0, 0, At, B0); PG8_BAR; PG8_SCHED;
;             PG8_LDB(B1, 1, 1); PG8_STAGE(PG8_SB(1, 0), b3, voffB);
;             PG8_BAR; PG8_WAIT_L(0); PG8_MMA(0, 1, At, B1); PG8_BAR;
;             PG8_LDA(At, 1, 1); PG8_STAGE(PG8_SA(1, 0), a3, voffA);
;             PG8_BAR; PG8_WAIT_L(0); PG8_MMA(1, 0, At, B0); PG8_BAR; PG8_SCHED;
;             PG8_STAGE(PG8_SB(1, 1), b3 + hstep, voffB);
;             PG8_WAIT_V(6); PG8_BAR; PG8_MMA(1, 1, At, B1); PG8_BAR;
;             }
;         }
;         if constexpr (ALIGN_EPI) { if (wr == 0) PG8_BAR; }
	s_add_i32 s40, s63, s45
	v_lshl_add_u64 v[144:145], v[144:145], 0, s[6:7]
	s_mov_b32 m0, s40
	ds_read_b128 v[190:193], v151 offset:49152
	ds_read_b128 v[194:197], v151 offset:50176
	ds_read_b128 v[198:201], v151 offset:51200
	ds_read_b128 v[202:205], v151 offset:52224
	ds_read_b128 v[206:209], v151 offset:53248
	ds_read_b128 v[210:213], v151 offset:54272
	ds_read_b128 v[214:217], v151 offset:55296
	ds_read_b128 v[218:221], v151 offset:56320
	global_load_lds_dwordx4 v[144:145], off
	s_add_i32 m0, s40, 0x2000
	s_add_u32 s38, s38, 0x80080
	v_lshl_add_u64 v[144:145], v[222:223], 0, s[6:7]
	s_addc_u32 s39, s39, 0
	s_add_i32 s40, s64, s45
	global_load_lds_dwordx4 v[144:145], off
	v_lshl_add_u64 v[144:145], s[38:39], 0, v[130:131]
	s_mov_b32 m0, s40
	s_nop 0
	global_load_lds_dwordx4 v[144:145], off
	v_lshl_add_u64 v[144:145], s[38:39], 0, v[134:135]
	s_add_i32 m0, s40, 0x2000
	s_nop 0
	global_load_lds_dwordx4 v[144:145], off
	v_lshl_add_u64 v[144:145], v[224:225], 0, s[6:7]
	s_mov_b32 m0, s52
	s_nop 0
	global_load_lds_dwordx4 v[144:145], off
	v_lshl_add_u64 v[144:145], v[226:227], 0, s[6:7]
	s_mov_b32 m0, s53
	s_nop 0
	global_load_lds_dwordx4 v[144:145], off
	s_waitcnt vmcnt(8)
	s_waitcnt lgkmcnt(0)
	s_barrier
	s_setprio 1
	s_waitcnt lgkmcnt(0)
	v_mfma_f32_16x16x32_bf16 v[60:63], v[152:155], v[190:193], v[60:63]
	v_mfma_f32_16x16x32_bf16 v[56:59], v[164:167], v[190:193], v[56:59]
	v_mfma_f32_16x16x32_bf16 v[44:47], v[152:155], v[198:201], v[44:47]
	v_mfma_f32_16x16x32_bf16 v[40:43], v[164:167], v[198:201], v[40:43]
	v_mfma_f32_16x16x32_bf16 v[28:31], v[152:155], v[206:209], v[28:31]
	v_mfma_f32_16x16x32_bf16 v[24:27], v[164:167], v[206:209], v[24:27]
	v_mfma_f32_16x16x32_bf16 v[12:15], v[152:155], v[214:217], v[12:15]
	v_mfma_f32_16x16x32_bf16 v[8:11], v[164:167], v[214:217], v[8:11]
	v_mfma_f32_16x16x32_bf16 v[60:63], v[156:159], v[194:197], v[60:63]
	v_mfma_f32_16x16x32_bf16 v[56:59], v[170:173], v[194:197], v[56:59]
	v_mfma_f32_16x16x32_bf16 v[44:47], v[156:159], v[202:205], v[44:47]
	v_mfma_f32_16x16x32_bf16 v[40:43], v[170:173], v[202:205], v[40:43]
	v_mfma_f32_16x16x32_bf16 v[28:31], v[156:159], v[210:213], v[28:31]
	v_mfma_f32_16x16x32_bf16 v[24:27], v[170:173], v[210:213], v[24:27]
	v_mfma_f32_16x16x32_bf16 v[12:15], v[156:159], v[218:221], v[12:15]
	v_mfma_f32_16x16x32_bf16 v[8:11], v[170:173], v[218:221], v[8:11]
	s_setprio 0
	s_setprio 1
	v_mfma_f32_16x16x32_bf16 v[52:55], v[174:177], v[190:193], v[52:55]
	v_mfma_f32_16x16x32_bf16 v[48:51], v[182:185], v[190:193], v[48:51]
	v_mfma_f32_16x16x32_bf16 v[36:39], v[174:177], v[198:201], v[36:39]
	v_mfma_f32_16x16x32_bf16 v[32:35], v[182:185], v[198:201], v[32:35]
	v_mfma_f32_16x16x32_bf16 v[20:23], v[174:177], v[206:209], v[20:23]
	v_mfma_f32_16x16x32_bf16 v[16:19], v[182:185], v[206:209], v[16:19]
	v_mfma_f32_16x16x32_bf16 v[4:7], v[174:177], v[214:217], v[4:7]
	v_mfma_f32_16x16x32_bf16 v[0:3], v[182:185], v[214:217], v[0:3]
	v_mfma_f32_16x16x32_bf16 v[52:55], v[178:181], v[194:197], v[52:55]
	v_mfma_f32_16x16x32_bf16 v[48:51], v[186:189], v[194:197], v[48:51]
	v_mfma_f32_16x16x32_bf16 v[36:39], v[178:181], v[202:205], v[36:39]
	v_mfma_f32_16x16x32_bf16 v[32:35], v[186:189], v[202:205], v[32:35]
	v_mfma_f32_16x16x32_bf16 v[20:23], v[178:181], v[210:213], v[20:23]
	v_mfma_f32_16x16x32_bf16 v[16:19], v[186:189], v[210:213], v[16:19]
	v_mfma_f32_16x16x32_bf16 v[4:7], v[178:181], v[218:221], v[4:7]
	v_mfma_f32_16x16x32_bf16 v[0:3], v[186:189], v[218:221], v[0:3]
	s_setprio 0
	s_barrier
	s_add_i32 s62, s62, 2
	s_add_u32 s36, s36, 0x100
	s_addc_u32 s37, s37, 0
	s_add_u32 s21, s21, 0x100
	s_addc_u32 s23, s23, 0
	s_cmp_gt_u32 s62, 29
	s_mov_b32 s100, 0
	s_cbranch_scc0 .LBB0_1552
	s_and_b64 vcc, exec, s[8:9]
	s_cbranch_vccz .LBB0_1555
	s_barrier
.LBB0_1555:
	v_max_f32_e32 v120, v120, v120
	v_max_f32_e32 v121, v121, v121
	v_max_f32_e32 v120, 0, v120
	v_max_f32_e32 v121, 0, v121
	v_pk_mul_f32 v[156:157], v[120:121], v[120:121]
	v_max_f32_e32 v121, v122, v122
	v_lshl_or_b32 v144, s61, 8, v148
	v_lshl_add_u32 v152, s28, 8, v146
	v_max_f32_e32 v124, v124, v124
	v_max_f32_e32 v125, v125, v125
	v_max_f32_e32 v120, v126, v126
	v_max_f32_e32 v122, 0, v121
	v_max_f32_e32 v121, v127, v127
	v_max_f32_e32 v123, v123, v123
	v_ashrrev_i32_e32 v145, 31, v144
	v_ashrrev_i32_e32 v153, 31, v152
	v_max_f32_e32 v124, 0, v124
	v_max_f32_e32 v125, 0, v125
	v_max_f32_e32 v120, 0, v120
	v_max_f32_e32 v121, 0, v121
	v_max_f32_e32 v123, 0, v123
	v_lshl_add_u64 v[154:155], v[144:145], 1, s[10:11]
	v_lshlrev_b64 v[144:145], 14, v[152:153]
	v_pk_mul_f32 v[124:125], v[124:125], v[124:125]
	v_pk_mul_f32 v[126:127], v[120:121], v[120:121]
	v_pk_mul_f32 v[158:159], v[122:123], v[122:123]
	v_max_f32_e32 v112, v112, v112
	v_max_f32_e32 v113, v113, v113
	v_lshl_add_u64 v[144:145], v[154:155], 0, v[144:145]
	v_cvt_pk_bf16_f32 v120, v124, v125
	v_cvt_pk_bf16_f32 v121, v126, v127
	v_cvt_pk_bf16_f32 v122, v156, v157
	v_cvt_pk_bf16_f32 v123, v158, v159
	v_max_f32_e32 v112, 0, v112
	v_max_f32_e32 v113, 0, v113
	global_store_dwordx4 v[144:145], v[120:123], off
	v_max_f32_e32 v116, v116, v116
	v_max_f32_e32 v117, v117, v117
	v_pk_mul_f32 v[120:121], v[112:113], v[112:113]
	v_max_f32_e32 v113, v114, v114
	v_max_f32_e32 v112, v118, v118
	v_max_f32_e32 v114, 0, v113
	v_max_f32_e32 v113, v119, v119
	v_max_f32_e32 v115, v115, v115
	v_max_f32_e32 v116, 0, v116
	v_max_f32_e32 v117, 0, v117
	v_max_f32_e32 v112, 0, v112
	v_max_f32_e32 v113, 0, v113
	v_max_f32_e32 v115, 0, v115
	v_pk_mul_f32 v[116:117], v[116:117], v[116:117]
	v_pk_mul_f32 v[118:119], v[112:113], v[112:113]
	v_pk_mul_f32 v[122:123], v[114:115], v[114:115]
	v_max_f32_e32 v104, v104, v104
; __device__ __forceinline__ unsigned cvt_pk_bf16(float lo, float hi) { return pk2(lo, hi); }
;     __device__ __forceinline__ void operator()(const f32x4 (&acc)[2][2][4][2], const Unit& u, int wr, int wc, int fr, int fq) const {
;     ...
;             for (int m = 0; m < 4; ++m) { bf16_t* rowp = O + (size_t)(row0 + ai * HALF + m * 16) * ldc + col0;
; #pragma unroll
;                 for (int bj = 0; bj < 2; ++bj) { f32x4 v0 = acc[ai][bj][m][0], v1 = acc[ai][bj][m][1];
;                     if (ACT == 1) {
; #pragma unroll
;                         for (int e = 0; e < 4; ++e) { float a = fmaxf(v0[e], 0.f), b = fmaxf(v1[e], 0.f); v0[e] = a * a; v1[e] = b * b; } }
;                     u32x4 w; w.x = cvt_pk_bf16(v0[0], v0[1]); w.y = cvt_pk_bf16(v0[2], v0[3]); w.z = cvt_pk_bf16(v1[0], v1[1]); w.w = cvt_pk_bf16(v1[2], v1[3]);
;                     *(u32x4*)(rowp + bj * HALF) = w; } }
	v_max_f32_e32 v105, v105, v105
	v_cvt_pk_bf16_f32 v112, v116, v117
	v_cvt_pk_bf16_f32 v113, v118, v119
	v_cvt_pk_bf16_f32 v114, v120, v121
	v_cvt_pk_bf16_f32 v115, v122, v123
	v_max_f32_e32 v104, 0, v104
	v_max_f32_e32 v105, 0, v105
	global_store_dwordx4 v[144:145], v[112:115], off offset:256
	v_max_f32_e32 v108, v108, v108
	v_max_f32_e32 v109, v109, v109
	v_pk_mul_f32 v[114:115], v[104:105], v[104:105]
	v_max_f32_e32 v105, v106, v106
	v_or_b32_e32 v112, 16, v152
	v_max_f32_e32 v104, v110, v110
	v_max_f32_e32 v106, 0, v105
	v_max_f32_e32 v105, v111, v111
	v_max_f32_e32 v107, v107, v107
	v_ashrrev_i32_e32 v113, 31, v112
	v_max_f32_e32 v108, 0, v108
	v_max_f32_e32 v109, 0, v109
	v_max_f32_e32 v104, 0, v104
	v_max_f32_e32 v105, 0, v105
	v_max_f32_e32 v107, 0, v107
	v_lshlrev_b64 v[112:113], 14, v[112:113]
	v_pk_mul_f32 v[108:109], v[108:109], v[108:109]
	v_pk_mul_f32 v[110:111], v[104:105], v[104:105]
	v_pk_mul_f32 v[116:117], v[106:107], v[106:107]
	v_max_f32_e32 v96, v96, v96
	v_max_f32_e32 v97, v97, v97
	v_lshl_add_u64 v[112:113], v[154:155], 0, v[112:113]
	v_cvt_pk_bf16_f32 v104, v108, v109
	v_cvt_pk_bf16_f32 v105, v110, v111
	v_cvt_pk_bf16_f32 v106, v114, v115
	v_cvt_pk_bf16_f32 v107, v116, v117
	v_max_f32_e32 v96, 0, v96
	v_max_f32_e32 v97, 0, v97
	global_store_dwordx4 v[112:113], v[104:107], off
	v_max_f32_e32 v100, v100, v100
	v_max_f32_e32 v101, v101, v101
	v_pk_mul_f32 v[104:105], v[96:97], v[96:97]
	v_max_f32_e32 v97, v98, v98
	v_max_f32_e32 v96, v102, v102
	v_max_f32_e32 v98, 0, v97
	v_max_f32_e32 v97, v103, v103
	v_max_f32_e32 v99, v99, v99
	v_max_f32_e32 v100, 0, v100
	v_max_f32_e32 v101, 0, v101
	v_max_f32_e32 v96, 0, v96
	v_max_f32_e32 v97, 0, v97
	v_max_f32_e32 v99, 0, v99
	v_pk_mul_f32 v[100:101], v[100:101], v[100:101]
	v_pk_mul_f32 v[102:103], v[96:97], v[96:97]
	v_pk_mul_f32 v[106:107], v[98:99], v[98:99]
	v_max_f32_e32 v88, v88, v88
	v_max_f32_e32 v89, v89, v89
	v_cvt_pk_bf16_f32 v96, v100, v101
	v_cvt_pk_bf16_f32 v97, v102, v103
	v_cvt_pk_bf16_f32 v98, v104, v105
	v_cvt_pk_bf16_f32 v99, v106, v107
	v_max_f32_e32 v88, 0, v88
	v_max_f32_e32 v89, 0, v89
	global_store_dwordx4 v[112:113], v[96:99], off offset:256
	v_max_f32_e32 v92, v92, v92
	v_max_f32_e32 v93, v93, v93
	v_pk_mul_f32 v[98:99], v[88:89], v[88:89]
	v_max_f32_e32 v89, v90, v90
	v_or_b32_e32 v96, 32, v152
	v_max_f32_e32 v88, v94, v94
	v_max_f32_e32 v90, 0, v89
	v_max_f32_e32 v89, v95, v95
	v_max_f32_e32 v91, v91, v91
	v_ashrrev_i32_e32 v97, 31, v96
	v_max_f32_e32 v92, 0, v92
	v_max_f32_e32 v93, 0, v93
	v_max_f32_e32 v88, 0, v88
	v_max_f32_e32 v89, 0, v89
	v_max_f32_e32 v91, 0, v91
	v_lshlrev_b64 v[96:97], 14, v[96:97]
	v_pk_mul_f32 v[92:93], v[92:93], v[92:93]
	v_pk_mul_f32 v[94:95], v[88:89], v[88:89]
	v_pk_mul_f32 v[100:101], v[90:91], v[90:91]
	v_max_f32_e32 v80, v80, v80
	v_max_f32_e32 v81, v81, v81
	v_lshl_add_u64 v[96:97], v[154:155], 0, v[96:97]
	v_cvt_pk_bf16_f32 v88, v92, v93
	v_cvt_pk_bf16_f32 v89, v94, v95
	v_cvt_pk_bf16_f32 v90, v98, v99
	v_cvt_pk_bf16_f32 v91, v100, v101
	v_max_f32_e32 v80, 0, v80
	v_max_f32_e32 v81, 0, v81
	global_store_dwordx4 v[96:97], v[88:91], off
	v_max_f32_e32 v84, v84, v84
	v_max_f32_e32 v85, v85, v85
	v_pk_mul_f32 v[88:89], v[80:81], v[80:81]
	v_max_f32_e32 v81, v82, v82
	v_max_f32_e32 v80, v86, v86
	v_max_f32_e32 v82, 0, v81
	v_max_f32_e32 v81, v87, v87
	v_max_f32_e32 v83, v83, v83
	v_max_f32_e32 v84, 0, v84
	v_max_f32_e32 v85, 0, v85
	v_max_f32_e32 v80, 0, v80
	v_max_f32_e32 v81, 0, v81
	v_max_f32_e32 v83, 0, v83
	v_pk_mul_f32 v[84:85], v[84:85], v[84:85]
	v_pk_mul_f32 v[86:87], v[80:81], v[80:81]
	v_pk_mul_f32 v[90:91], v[82:83], v[82:83]
	v_max_f32_e32 v72, v72, v72
	v_max_f32_e32 v73, v73, v73
	v_cvt_pk_bf16_f32 v80, v84, v85
	v_cvt_pk_bf16_f32 v81, v86, v87
	v_cvt_pk_bf16_f32 v82, v88, v89
	v_cvt_pk_bf16_f32 v83, v90, v91
	v_max_f32_e32 v72, 0, v72
	v_max_f32_e32 v73, 0, v73
	global_store_dwordx4 v[96:97], v[80:83], off offset:256
	v_max_f32_e32 v76, v76, v76
	v_max_f32_e32 v77, v77, v77
	v_pk_mul_f32 v[82:83], v[72:73], v[72:73]
	v_max_f32_e32 v73, v74, v74
	v_or_b32_e32 v80, 48, v152
	v_max_f32_e32 v72, v78, v78
	v_max_f32_e32 v74, 0, v73
	v_max_f32_e32 v73, v79, v79
	v_max_f32_e32 v75, v75, v75
	v_ashrrev_i32_e32 v81, 31, v80
	v_max_f32_e32 v76, 0, v76
	v_max_f32_e32 v77, 0, v77
	v_max_f32_e32 v72, 0, v72
	v_max_f32_e32 v73, 0, v73
	v_max_f32_e32 v75, 0, v75
	v_lshlrev_b64 v[80:81], 14, v[80:81]
	v_pk_mul_f32 v[76:77], v[76:77], v[76:77]
	v_pk_mul_f32 v[78:79], v[72:73], v[72:73]
	v_pk_mul_f32 v[84:85], v[74:75], v[74:75]
	v_max_f32_e32 v64, v64, v64
	v_max_f32_e32 v65, v65, v65
	v_lshl_add_u64 v[80:81], v[154:155], 0, v[80:81]
	v_cvt_pk_bf16_f32 v72, v76, v77
	v_cvt_pk_bf16_f32 v73, v78, v79
	v_cvt_pk_bf16_f32 v74, v82, v83
	v_cvt_pk_bf16_f32 v75, v84, v85
	v_max_f32_e32 v64, 0, v64
	v_max_f32_e32 v65, 0, v65
	global_store_dwordx4 v[80:81], v[72:75], off
	v_max_f32_e32 v68, v68, v68
	v_max_f32_e32 v69, v69, v69
	v_pk_mul_f32 v[72:73], v[64:65], v[64:65]
	v_max_f32_e32 v65, v66, v66
	v_max_f32_e32 v64, v70, v70
	v_max_f32_e32 v66, 0, v65
	v_max_f32_e32 v65, v71, v71
	v_max_f32_e32 v67, v67, v67
	v_max_f32_e32 v68, 0, v68
	v_max_f32_e32 v69, 0, v69
	v_max_f32_e32 v64, 0, v64
	v_max_f32_e32 v65, 0, v65
	v_max_f32_e32 v67, 0, v67
	v_pk_mul_f32 v[68:69], v[68:69], v[68:69]
	v_pk_mul_f32 v[70:71], v[64:65], v[64:65]
	v_pk_mul_f32 v[74:75], v[66:67], v[66:67]
	v_max_f32_e32 v56, v56, v56
	v_max_f32_e32 v57, v57, v57
	v_cvt_pk_bf16_f32 v64, v68, v69
	v_cvt_pk_bf16_f32 v65, v70, v71
	v_cvt_pk_bf16_f32 v66, v72, v73
	v_cvt_pk_bf16_f32 v67, v74, v75
	v_max_f32_e32 v56, 0, v56
	v_max_f32_e32 v57, 0, v57
; __device__ __forceinline__ unsigned cvt_pk_bf16(float lo, float hi) { return pk2(lo, hi); }
; #define PG8_BAR __builtin_amdgcn_s_barrier()
;     __device__ __forceinline__ void operator()(const f32x4 (&acc)[2][2][4][2], const Unit& u, int wr, int wc, int fr, int fq) const {
;     ...
;             for (int m = 0; m < 4; ++m) { bf16_t* rowp = O + (size_t)(row0 + ai * HALF + m * 16) * ldc + col0;
; #pragma unroll
;                 for (int bj = 0; bj < 2; ++bj) { f32x4 v0 = acc[ai][bj][m][0], v1 = acc[ai][bj][m][1];
;                     if (ACT == 1) {
; #pragma unroll
;                         for (int e = 0; e < 4; ++e) { float a = fmaxf(v0[e], 0.f), b = fmaxf(v1[e], 0.f); v0[e] = a * a; v1[e] = b * b; } }
;                     u32x4 w; w.x = cvt_pk_bf16(v0[0], v0[1]); w.y = cvt_pk_bf16(v0[2], v0[3]); w.z = cvt_pk_bf16(v1[0], v1[1]); w.w = cvt_pk_bf16(v1[2], v1[3]);
;                     *(u32x4*)(rowp + bj * HALF) = w; } }
; template <class Epi, class Sched, bool ALIGN_EPI = false, bool SP2 = false>
; __device__ __forceinline__ void gemm_phase(LAS unsigned char* lds, const Gemm g, const Sched& S, const Epi& E) {
;     ...
;         if constexpr (!Epi::AFTER_DRAIN) { E(acc, cur, wr, wc, fr, fq); S.done(cur); }
;         if (!has_next) break;
; #pragma unroll
;         for (int a = 0; a < 2; ++a)
; #pragma unroll
;             for (int b = 0; b < 2; ++b)
; #pragma unroll
;                 for (int m = 0; m < 4; ++m)
; #pragma unroll
;                     for (int n = 0; n < 2; ++n) acc[a][b][m][n] = (f32x4){0.f, 0.f, 0.f, 0.f};
;         cur = nxt; cA = nA; cB = nB; ++ui;
;         if constexpr (ALIGN_EPI) { if (wr == 1) PG8_BAR; }
;     }
	global_store_dwordx4 v[80:81], v[64:67], off offset:256
	v_max_f32_e32 v60, v60, v60
	v_max_f32_e32 v61, v61, v61
	v_pk_mul_f32 v[66:67], v[56:57], v[56:57]
	v_max_f32_e32 v57, v58, v58
	v_max_f32_e32 v60, 0, v60
	v_max_f32_e32 v61, 0, v61
	v_max_f32_e32 v56, v62, v62
	v_max_f32_e32 v58, 0, v57
	v_max_f32_e32 v57, v63, v63
	v_max_f32_e32 v59, v59, v59
	v_pk_mul_f32 v[60:61], v[60:61], v[60:61]
	v_max_f32_e32 v56, 0, v56
	v_max_f32_e32 v57, 0, v57
	v_max_f32_e32 v59, 0, v59
	v_pk_mul_f32 v[62:63], v[56:57], v[56:57]
	v_pk_mul_f32 v[68:69], v[58:59], v[58:59]
	v_cvt_pk_bf16_f32 v56, v60, v61
	v_add_co_u32_e32 v60, vcc, s57, v144
	v_max_f32_e32 v48, v48, v48
	v_max_f32_e32 v49, v49, v49
	v_cvt_pk_bf16_f32 v57, v62, v63
	v_cvt_pk_bf16_f32 v58, v66, v67
	v_cvt_pk_bf16_f32 v59, v68, v69
	v_addc_co_u32_e32 v61, vcc, 0, v145, vcc
	v_max_f32_e32 v48, 0, v48
	v_max_f32_e32 v49, 0, v49
	global_store_dwordx4 v[60:61], v[56:59], off
	v_max_f32_e32 v52, v52, v52
	v_max_f32_e32 v53, v53, v53
	v_pk_mul_f32 v[56:57], v[48:49], v[48:49]
	v_max_f32_e32 v49, v50, v50
	v_max_f32_e32 v48, v54, v54
	v_max_f32_e32 v50, 0, v49
	v_max_f32_e32 v49, v55, v55
	v_max_f32_e32 v51, v51, v51
	v_max_f32_e32 v52, 0, v52
	v_max_f32_e32 v53, 0, v53
	v_max_f32_e32 v48, 0, v48
	v_max_f32_e32 v49, 0, v49
	v_max_f32_e32 v51, 0, v51
	v_pk_mul_f32 v[52:53], v[52:53], v[52:53]
	v_pk_mul_f32 v[54:55], v[48:49], v[48:49]
	v_pk_mul_f32 v[58:59], v[50:51], v[50:51]
	v_max_f32_e32 v40, v40, v40
	v_max_f32_e32 v41, v41, v41
	v_lshl_add_u64 v[64:65], v[144:145], 0, s[12:13]
	v_cvt_pk_bf16_f32 v48, v52, v53
	v_cvt_pk_bf16_f32 v49, v54, v55
	v_cvt_pk_bf16_f32 v50, v56, v57
	v_cvt_pk_bf16_f32 v51, v58, v59
	v_max_f32_e32 v40, 0, v40
	v_max_f32_e32 v41, 0, v41
	global_store_dwordx4 v[64:65], v[48:51], off offset:256
	v_max_f32_e32 v44, v44, v44
	v_max_f32_e32 v45, v45, v45
	v_pk_mul_f32 v[50:51], v[40:41], v[40:41]
	v_max_f32_e32 v41, v42, v42
	v_max_f32_e32 v44, 0, v44
	v_max_f32_e32 v45, 0, v45
	v_max_f32_e32 v40, v46, v46
	v_max_f32_e32 v42, 0, v41
	v_max_f32_e32 v41, v47, v47
	v_max_f32_e32 v43, v43, v43
	v_pk_mul_f32 v[44:45], v[44:45], v[44:45]
	v_max_f32_e32 v40, 0, v40
	v_max_f32_e32 v41, 0, v41
	v_max_f32_e32 v43, 0, v43
	v_pk_mul_f32 v[46:47], v[40:41], v[40:41]
	v_pk_mul_f32 v[52:53], v[42:43], v[42:43]
	v_cvt_pk_bf16_f32 v40, v44, v45
	v_add_co_u32_e32 v44, vcc, s58, v144
	v_max_f32_e32 v32, v32, v32
	v_max_f32_e32 v33, v33, v33
	v_cvt_pk_bf16_f32 v41, v46, v47
	v_cvt_pk_bf16_f32 v42, v50, v51
	v_cvt_pk_bf16_f32 v43, v52, v53
	v_addc_co_u32_e32 v45, vcc, 0, v145, vcc
	v_max_f32_e32 v32, 0, v32
	v_max_f32_e32 v33, 0, v33
	global_store_dwordx4 v[44:45], v[40:43], off
	v_max_f32_e32 v36, v36, v36
	v_max_f32_e32 v37, v37, v37
	v_pk_mul_f32 v[40:41], v[32:33], v[32:33]
	v_max_f32_e32 v33, v34, v34
	v_max_f32_e32 v32, v38, v38
	v_max_f32_e32 v34, 0, v33
	v_max_f32_e32 v33, v39, v39
	v_max_f32_e32 v35, v35, v35
	v_max_f32_e32 v36, 0, v36
	v_max_f32_e32 v37, 0, v37
	v_max_f32_e32 v32, 0, v32
	v_max_f32_e32 v33, 0, v33
	v_max_f32_e32 v35, 0, v35
	v_pk_mul_f32 v[36:37], v[36:37], v[36:37]
	v_pk_mul_f32 v[38:39], v[32:33], v[32:33]
	v_pk_mul_f32 v[42:43], v[34:35], v[34:35]
	v_max_f32_e32 v24, v24, v24
	v_max_f32_e32 v25, v25, v25
	v_lshl_add_u64 v[48:49], v[144:145], 0, s[14:15]
	v_cvt_pk_bf16_f32 v32, v36, v37
	v_cvt_pk_bf16_f32 v33, v38, v39
	v_cvt_pk_bf16_f32 v34, v40, v41
	v_cvt_pk_bf16_f32 v35, v42, v43
	v_max_f32_e32 v24, 0, v24
	v_max_f32_e32 v25, 0, v25
	global_store_dwordx4 v[48:49], v[32:35], off offset:256
	v_max_f32_e32 v28, v28, v28
	v_max_f32_e32 v29, v29, v29
	v_pk_mul_f32 v[34:35], v[24:25], v[24:25]
	v_max_f32_e32 v25, v26, v26
	v_max_f32_e32 v28, 0, v28
	v_max_f32_e32 v29, 0, v29
	v_max_f32_e32 v24, v30, v30
	v_max_f32_e32 v26, 0, v25
	v_max_f32_e32 v25, v31, v31
	v_max_f32_e32 v27, v27, v27
	v_pk_mul_f32 v[28:29], v[28:29], v[28:29]
	v_max_f32_e32 v24, 0, v24
	v_max_f32_e32 v25, 0, v25
	v_max_f32_e32 v27, 0, v27
	v_pk_mul_f32 v[30:31], v[24:25], v[24:25]
	v_pk_mul_f32 v[36:37], v[26:27], v[26:27]
	v_cvt_pk_bf16_f32 v24, v28, v29
	v_add_co_u32_e32 v28, vcc, s59, v144
	v_max_f32_e32 v16, v16, v16
	v_max_f32_e32 v17, v17, v17
	v_cvt_pk_bf16_f32 v25, v30, v31
	v_cvt_pk_bf16_f32 v26, v34, v35
	v_cvt_pk_bf16_f32 v27, v36, v37
	v_addc_co_u32_e32 v29, vcc, 0, v145, vcc
	v_max_f32_e32 v16, 0, v16
	v_max_f32_e32 v17, 0, v17
	global_store_dwordx4 v[28:29], v[24:27], off
	v_max_f32_e32 v20, v20, v20
	v_max_f32_e32 v21, v21, v21
	v_pk_mul_f32 v[24:25], v[16:17], v[16:17]
	v_max_f32_e32 v17, v18, v18
	v_max_f32_e32 v16, v22, v22
	v_max_f32_e32 v18, 0, v17
	v_max_f32_e32 v17, v23, v23
	v_max_f32_e32 v19, v19, v19
	v_max_f32_e32 v20, 0, v20
	v_max_f32_e32 v21, 0, v21
	v_max_f32_e32 v16, 0, v16
	v_max_f32_e32 v17, 0, v17
	v_max_f32_e32 v19, 0, v19
	v_pk_mul_f32 v[20:21], v[20:21], v[20:21]
	v_pk_mul_f32 v[22:23], v[16:17], v[16:17]
	v_pk_mul_f32 v[26:27], v[18:19], v[18:19]
	v_max_f32_e32 v8, v8, v8
	v_max_f32_e32 v9, v9, v9
	v_lshl_add_u64 v[32:33], v[144:145], 0, s[16:17]
	v_cvt_pk_bf16_f32 v16, v20, v21
	v_cvt_pk_bf16_f32 v17, v22, v23
	v_cvt_pk_bf16_f32 v18, v24, v25
	v_cvt_pk_bf16_f32 v19, v26, v27
	v_max_f32_e32 v8, 0, v8
	v_max_f32_e32 v9, 0, v9
	global_store_dwordx4 v[32:33], v[16:19], off offset:256
	v_max_f32_e32 v12, v12, v12
	v_max_f32_e32 v13, v13, v13
	v_pk_mul_f32 v[18:19], v[8:9], v[8:9]
	v_max_f32_e32 v9, v10, v10
	v_max_f32_e32 v12, 0, v12
	v_max_f32_e32 v13, 0, v13
	v_max_f32_e32 v8, v14, v14
	v_max_f32_e32 v10, 0, v9
	v_max_f32_e32 v9, v15, v15
	v_max_f32_e32 v11, v11, v11
	v_pk_mul_f32 v[12:13], v[12:13], v[12:13]
	v_max_f32_e32 v8, 0, v8
	v_max_f32_e32 v9, 0, v9
	v_max_f32_e32 v11, 0, v11
	v_pk_mul_f32 v[14:15], v[8:9], v[8:9]
	v_pk_mul_f32 v[20:21], v[10:11], v[10:11]
	v_cvt_pk_bf16_f32 v8, v12, v13
	v_add_co_u32_e32 v12, vcc, s60, v144
	v_max_f32_e32 v0, v0, v0
	v_max_f32_e32 v1, v1, v1
	v_cvt_pk_bf16_f32 v9, v14, v15
	v_cvt_pk_bf16_f32 v10, v18, v19
	v_cvt_pk_bf16_f32 v11, v20, v21
	v_addc_co_u32_e32 v13, vcc, 0, v145, vcc
	v_max_f32_e32 v0, 0, v0
	v_max_f32_e32 v1, 0, v1
	global_store_dwordx4 v[12:13], v[8:11], off
	v_max_f32_e32 v4, v4, v4
	v_max_f32_e32 v5, v5, v5
	v_pk_mul_f32 v[8:9], v[0:1], v[0:1]
	v_max_f32_e32 v1, v2, v2
	v_max_f32_e32 v0, v6, v6
	v_max_f32_e32 v2, 0, v1
	v_max_f32_e32 v1, v7, v7
	v_max_f32_e32 v3, v3, v3
	v_max_f32_e32 v4, 0, v4
	v_max_f32_e32 v5, 0, v5
	v_max_f32_e32 v0, 0, v0
	v_max_f32_e32 v1, 0, v1
	v_max_f32_e32 v3, 0, v3
	v_pk_mul_f32 v[4:5], v[4:5], v[4:5]
	v_pk_mul_f32 v[6:7], v[0:1], v[0:1]
	v_pk_mul_f32 v[10:11], v[2:3], v[2:3]
	v_lshl_add_u64 v[16:17], v[144:145], 0, s[18:19]
	v_cvt_pk_bf16_f32 v0, v4, v5
	v_cvt_pk_bf16_f32 v1, v6, v7
	v_cvt_pk_bf16_f32 v2, v8, v9
	v_cvt_pk_bf16_f32 v3, v10, v11
	s_andn2_b64 vcc, exec, s[0:1]
	s_mov_b64 s[0:1], -1
	global_store_dwordx4 v[16:17], v[0:3], off offset:256
	s_mov_b32 s100, 1
	s_cbranch_vccnz .LBB0_1544
	s_andn2_b64 vcc, exec, s[4:5]
	s_cbranch_vccnz .LBB0_1543
	s_barrier
	s_branch .LBB0_1543
